# EpiStoreN epilogue: bias vector loads join the rss batch at the epilogue head (12 loads, one exposed round trip), copies at the old load site
# speedup vs baseline: 1.0110x; 1.0052x over previous
;     DI void operator()(const f32x4 (&acc)[2][2][4][2], const pg8::Unit& u, int wr, int wc, int fr, int fq) const {
;         const int lrow0 = u.pm * 256 + wr * 64 + fr, grow0 = row_base + u.pm * 256, col0 = u.pn * 256 + wc * 32 + 8 * fq;
;         bf16* Ou = O + (size_t)(u.pm * 256) * ldc + u.pn * 256;
;         const int mrow = grow0 < NCTX ? 8 : (grow0 - NCTX) >> 12;
;         float rstd[2][4];
; #pragma unroll
;         for (int ai = 0; ai < 2; ++ai)
; #pragma unroll
;             for (int m = 0; m < 4; ++m) rstd[ai][m] = rsqrtf(rss[row_base + lrow0 + ai * 128 + m * 16] * (1.f / DM) + EPS);
;         const float* bp = bias + mrow * 4096 + col0;
;         f32x4 bb[2][2];
; #pragma unroll
;         for (int bj = 0; bj < 2; ++bj) { bb[bj][0] = *(const f32x4*)(bp + bj * 128); bb[bj][1] = *(const f32x4*)(bp + bj * 128 + 4); }
;         asm volatile("" ::: "memory");
; #pragma unroll
;         for (int bj = 0; bj < 2; ++bj) { const f32x4 b0 = bb[bj][0], b1 = bb[bj][1];
; #pragma unroll
;             for (int ai = 0; ai < 2; ++ai)
; #pragma unroll
;                 for (int m = 0; m < 4; ++m) {
;                     f32x4 v0 = acc[ai][bj][m][0] * rstd[ai][m] + b0, v1 = acc[ai][bj][m][1] * rstd[ai][m] + b1;
.LBB0_1030:
	s_lshl_b32 s6, s56, 8
	v_add_u32_e32 v128, s6, v183
	v_ashrrev_i32_e32 v129, 31, v128
	v_lshl_add_u64 v[128:129], v[128:129], 2, s[86:87]
	global_load_dword v200, v[128:129], off
	global_load_dword v201, v[128:129], off offset:64
	global_load_dword v202, v[128:129], off offset:128
	global_load_dword v203, v[128:129], off offset:192
	global_load_dword v204, v[128:129], off offset:512
	global_load_dword v205, v[128:129], off offset:576
	global_load_dword v206, v[128:129], off offset:640
	global_load_dword v207, v[128:129], off offset:704
	s_lshl_b32 s4, s31, 8
	s_ashr_i32 s7, s6, 31
	s_ashr_i32 s5, s4, 31
	s_lshl_b64 s[8:9], s[6:7], 13
	s_add_u32 s8, s33, s8
	s_addc_u32 s9, s59, s9
	s_and_b32 s7, s6, 0xfffff000
	s_cmp_lt_u32 s6, 0x7ffff800
	s_cselect_b32 s6, s7, 0x8000
	s_ashr_i32 s7, s6, 31
	s_lshl_b64 s[6:7], s[6:7], 2
	v_readlane_b32 s22, v253, 61
	v_readlane_b32 s23, v253, 62
	s_add_u32 s6, s22, s6
	s_addc_u32 s7, s23, s7
	v_or_b32_e32 v208, s4, v181
	v_ashrrev_i32_e32 v209, 31, v208
	v_lshl_add_u64 v[208:209], v[208:209], 2, s[6:7]
	global_load_dwordx4 v[220:223], v[208:209], off offset:16
	global_load_dwordx4 v[224:227], v[208:209], off
	global_load_dwordx4 v[228:231], v[208:209], off offset:528
	global_load_dwordx4 v[232:235], v[208:209], off offset:512
	s_waitcnt vmcnt(11)
	v_fmamk_f32 v200, v200, 0x3a800000, v187
	v_cmp_gt_f32_e32 vcc, s52, v200
	v_mul_f32_e32 v131, 0x4b800000, v200
	s_nop 0
	v_cndmask_b32_e32 v200, v200, v131, vcc
	v_rsq_f32_e32 v200, v200
	s_nop 0
	v_mul_f32_e32 v131, 0x45800000, v200
	v_cndmask_b32_e32 v192, v200, v131, vcc
	s_waitcnt vmcnt(10)
	v_fmamk_f32 v201, v201, 0x3a800000, v187
	v_cmp_gt_f32_e32 vcc, s52, v201
	v_mul_f32_e32 v131, 0x4b800000, v201
	s_nop 0
	v_cndmask_b32_e32 v201, v201, v131, vcc
	v_rsq_f32_e32 v201, v201
	s_nop 0
	v_mul_f32_e32 v131, 0x45800000, v201
	v_cndmask_b32_e32 v190, v201, v131, vcc
	s_waitcnt vmcnt(9)
	v_fmamk_f32 v202, v202, 0x3a800000, v187
	v_cmp_gt_f32_e32 vcc, s52, v202
	v_mul_f32_e32 v131, 0x4b800000, v202
	s_nop 0
	v_cndmask_b32_e32 v202, v202, v131, vcc
	v_rsq_f32_e32 v202, v202
	s_nop 0
	v_mul_f32_e32 v131, 0x45800000, v202
	v_cndmask_b32_e32 v188, v202, v131, vcc
	s_waitcnt vmcnt(8)
	v_fmamk_f32 v203, v203, 0x3a800000, v187
	v_cmp_gt_f32_e32 vcc, s52, v203
	v_mul_f32_e32 v131, 0x4b800000, v203
	s_nop 0
	v_cndmask_b32_e32 v203, v203, v131, vcc
	v_rsq_f32_e32 v203, v203
	s_nop 0
	v_mul_f32_e32 v131, 0x45800000, v203
	v_cndmask_b32_e32 v186, v203, v131, vcc
	s_waitcnt vmcnt(7)
	v_fmamk_f32 v204, v204, 0x3a800000, v187
	v_cmp_gt_f32_e32 vcc, s52, v204
	v_mul_f32_e32 v131, 0x4b800000, v204
	s_nop 0
	v_cndmask_b32_e32 v204, v204, v131, vcc
	v_rsq_f32_e32 v204, v204
	s_nop 0
	v_mul_f32_e32 v131, 0x45800000, v204
	v_cndmask_b32_e32 v184, v204, v131, vcc
	s_waitcnt vmcnt(6)
	v_fmamk_f32 v205, v205, 0x3a800000, v187
	v_cmp_gt_f32_e32 vcc, s52, v205
	v_mul_f32_e32 v131, 0x4b800000, v205
	s_nop 0
	v_cndmask_b32_e32 v205, v205, v131, vcc
	v_rsq_f32_e32 v205, v205
	s_nop 0
	v_mul_f32_e32 v131, 0x45800000, v205
	v_cndmask_b32_e32 v182, v205, v131, vcc
	s_waitcnt vmcnt(5)
	v_fmamk_f32 v206, v206, 0x3a800000, v187
	v_cmp_gt_f32_e32 vcc, s52, v206
	v_mul_f32_e32 v131, 0x4b800000, v206
	s_waitcnt vmcnt(4)
	v_fmamk_f32 v207, v207, 0x3a800000, v187
	v_cndmask_b32_e32 v206, v206, v131, vcc
	v_rsq_f32_e32 v206, v206
	v_mul_f32_e32 v129, 0x4b800000, v207
	v_mul_f32_e32 v131, 0x45800000, v206
	v_cndmask_b32_e32 v180, v206, v131, vcc
	v_cmp_gt_f32_e32 vcc, s52, v207
	s_nop 1
	v_cndmask_b32_e32 v207, v207, v129, vcc
	v_rsq_f32_e32 v207, v207
	s_nop 0
	v_mul_f32_e32 v129, 0x45800000, v207
	v_cndmask_b32_e32 v178, v207, v129, vcc
	v_or_b32_e32 v128, s4, v181
	v_ashrrev_i32_e32 v129, 31, v128
	v_lshl_add_u64 v[132:133], v[128:129], 2, s[6:7]
	s_waitcnt vmcnt(0)
	v_mov_b32_e32 v136, v220
	v_mov_b32_e32 v137, v221
	v_mov_b32_e32 v138, v222
	v_mov_b32_e32 v139, v223
	v_mov_b32_e32 v140, v224
	v_mov_b32_e32 v141, v225
	v_mov_b32_e32 v142, v226
	v_mov_b32_e32 v143, v227
	v_mov_b32_e32 v128, v228
	v_mov_b32_e32 v129, v229
	v_mov_b32_e32 v130, v230
	v_mov_b32_e32 v131, v231
	v_mov_b32_e32 v132, v232
	v_mov_b32_e32 v133, v233
	v_mov_b32_e32 v134, v234
	v_mov_b32_e32 v135, v235
	s_nop 0
	s_nop 0
	s_nop 0
	s_nop 0
	s_nop 0
	s_nop 0
	s_nop 0
	s_nop 0
	s_nop 0
	s_nop 0
	s_nop 0
	s_nop 0
	s_lshl_b64 s[4:5], s[4:5], 1
	s_add_u32 s4, s8, s4
	s_addc_u32 s5, s9, s5
	s_add_u32 s4, s4, s53
	s_addc_u32 s5, s5, 0
	v_lshl_add_u64 v[194:195], s[4:5], 0, v[152:153]
	s_mov_b64 s[4:5], 0x100
	s_andn2_b64 vcc, exec, s[36:37]
	s_waitcnt vmcnt(3)
	v_pk_fma_f32 v[122:123], v[122:123], v[192:193], v[138:139] op_sel_hi:[1,0,1]
	s_waitcnt vmcnt(2)
; DI unsigned cvtpk(float lo, float hi) { f32x2 v = {lo, hi}; bf16x2_t b = __builtin_convertvector(v, bf16x2_t); return __builtin_bit_cast(unsigned, b); }
;     DI void operator()(const f32x4 (&acc)[2][2][4][2], const pg8::Unit& u, int wr, int wc, int fr, int fq) const {
;     ...
; #pragma unroll
;         for (int bj = 0; bj < 2; ++bj) { const f32x4 b0 = bb[bj][0], b1 = bb[bj][1];
; #pragma unroll
;             for (int ai = 0; ai < 2; ++ai)
; #pragma unroll
;                 for (int m = 0; m < 4; ++m) {
;                     f32x4 v0 = acc[ai][bj][m][0] * rstd[ai][m] + b0, v1 = acc[ai][bj][m][1] * rstd[ai][m] + b1;
;                     if (ACT == 1) {
; #pragma unroll
;                         for (int e = 0; e < 4; ++e) { float a = fmaxf(v0[e], 0.f), b = fmaxf(v1[e], 0.f); v0[e] = a * a; v1[e] = b * b; } }
;                     u32x4 w; w.x = cvtpk(v0[0], v0[1]); w.y = cvtpk(v0[2], v0[3]); w.z = cvtpk(v1[0], v1[1]); w.w = cvtpk(v1[2], v1[3]);
;                     *(u32x4*)(Ou + (wr * 64 + fr + ai * 128 + m * 16) * ldc + wc * 32 + 8 * fq + bj * 128) = w; } }
	v_pk_fma_f32 v[126:127], v[126:127], v[192:193], v[142:143] op_sel_hi:[1,0,1]
	v_pk_fma_f32 v[124:125], v[124:125], v[192:193], v[140:141] op_sel_hi:[1,0,1]
	v_pk_fma_f32 v[120:121], v[120:121], v[192:193], v[136:137] op_sel_hi:[1,0,1]
	v_max_f32_e32 v124, 0, v124
	v_max_f32_e32 v120, 0, v120
	v_max_f32_e32 v125, 0, v125
	v_max_f32_e32 v121, 0, v121
	v_max_f32_e32 v126, 0, v126
	v_max_f32_e32 v122, 0, v122
	v_max_f32_e32 v127, 0, v127
	v_max_f32_e32 v123, 0, v123
	v_pk_mul_f32 v[124:125], v[124:125], v[124:125]
	v_pk_mul_f32 v[120:121], v[120:121], v[120:121]
	v_pk_mul_f32 v[126:127], v[126:127], v[126:127]
	v_pk_mul_f32 v[196:197], v[122:123], v[122:123]
	v_pk_fma_f32 v[112:113], v[112:113], v[190:191], v[136:137] op_sel_hi:[1,0,1]
	v_cvt_pk_bf16_f32 v122, v124, v125
	v_cvt_pk_bf16_f32 v123, v126, v127
	v_cvt_pk_bf16_f32 v124, v120, v121
	v_cvt_pk_bf16_f32 v125, v196, v197
	v_lshl_add_u64 v[120:121], v[154:155], 1, v[194:195]
	v_pk_fma_f32 v[118:119], v[118:119], v[190:191], v[142:143] op_sel_hi:[1,0,1]
	v_pk_fma_f32 v[116:117], v[116:117], v[190:191], v[140:141] op_sel_hi:[1,0,1]
	v_pk_fma_f32 v[114:115], v[114:115], v[190:191], v[138:139] op_sel_hi:[1,0,1]
	v_max_f32_e32 v112, 0, v112
	v_max_f32_e32 v113, 0, v113
	global_store_dwordx4 v[120:121], v[122:125], off
	v_max_f32_e32 v116, 0, v116
	v_max_f32_e32 v117, 0, v117
	v_pk_mul_f32 v[122:123], v[112:113], v[112:113]
	v_max_f32_e32 v112, 0, v118
	v_max_f32_e32 v114, 0, v114
	v_max_f32_e32 v113, 0, v119
	v_max_f32_e32 v115, 0, v115
	v_pk_mul_f32 v[116:117], v[116:117], v[116:117]
	v_pk_mul_f32 v[118:119], v[112:113], v[112:113]
	v_pk_mul_f32 v[124:125], v[114:115], v[114:115]
	v_pk_fma_f32 v[104:105], v[104:105], v[188:189], v[136:137] op_sel_hi:[1,0,1]
	v_cvt_pk_bf16_f32 v112, v116, v117
	v_cvt_pk_bf16_f32 v113, v118, v119
	v_cvt_pk_bf16_f32 v114, v122, v123
	v_cvt_pk_bf16_f32 v115, v124, v125
	v_lshl_add_u64 v[116:117], v[194:195], 0, v[170:171]
	v_pk_fma_f32 v[110:111], v[110:111], v[188:189], v[142:143] op_sel_hi:[1,0,1]
	v_pk_fma_f32 v[108:109], v[108:109], v[188:189], v[140:141] op_sel_hi:[1,0,1]
	v_pk_fma_f32 v[106:107], v[106:107], v[188:189], v[138:139] op_sel_hi:[1,0,1]
	v_max_f32_e32 v104, 0, v104
	v_max_f32_e32 v105, 0, v105
	global_store_dwordx4 v[116:117], v[112:115], off
	v_max_f32_e32 v108, 0, v108
	v_max_f32_e32 v109, 0, v109
	v_pk_mul_f32 v[112:113], v[104:105], v[104:105]
	v_max_f32_e32 v104, 0, v110
	v_max_f32_e32 v106, 0, v106
	v_max_f32_e32 v105, 0, v111
	v_max_f32_e32 v107, 0, v107
	v_pk_mul_f32 v[108:109], v[108:109], v[108:109]
	v_pk_mul_f32 v[110:111], v[104:105], v[104:105]
	v_pk_mul_f32 v[114:115], v[106:107], v[106:107]
	v_pk_fma_f32 v[96:97], v[96:97], v[186:187], v[136:137] op_sel_hi:[1,0,1]
	v_cvt_pk_bf16_f32 v104, v108, v109
	v_cvt_pk_bf16_f32 v105, v110, v111
	v_cvt_pk_bf16_f32 v106, v112, v113
	v_cvt_pk_bf16_f32 v107, v114, v115
	v_lshl_add_u64 v[108:109], v[194:195], 0, v[172:173]
	v_pk_fma_f32 v[102:103], v[102:103], v[186:187], v[142:143] op_sel_hi:[1,0,1]
	v_pk_fma_f32 v[100:101], v[100:101], v[186:187], v[140:141] op_sel_hi:[1,0,1]
	v_pk_fma_f32 v[98:99], v[98:99], v[186:187], v[138:139] op_sel_hi:[1,0,1]
	v_max_f32_e32 v96, 0, v96
	v_max_f32_e32 v97, 0, v97
	global_store_dwordx4 v[108:109], v[104:107], off
	v_max_f32_e32 v100, 0, v100
	v_max_f32_e32 v101, 0, v101
	v_pk_mul_f32 v[104:105], v[96:97], v[96:97]
	v_max_f32_e32 v96, 0, v102
	v_max_f32_e32 v98, 0, v98
	v_max_f32_e32 v97, 0, v103
	v_max_f32_e32 v99, 0, v99
	v_pk_mul_f32 v[100:101], v[100:101], v[100:101]
	v_pk_mul_f32 v[102:103], v[96:97], v[96:97]
	v_pk_mul_f32 v[106:107], v[98:99], v[98:99]
	v_pk_fma_f32 v[94:95], v[94:95], v[184:185], v[142:143] op_sel_hi:[1,0,1]
	v_pk_fma_f32 v[92:93], v[92:93], v[184:185], v[140:141] op_sel_hi:[1,0,1]
	v_pk_fma_f32 v[90:91], v[90:91], v[184:185], v[138:139] op_sel_hi:[1,0,1]
	v_pk_fma_f32 v[88:89], v[88:89], v[184:185], v[136:137] op_sel_hi:[1,0,1]
	v_cvt_pk_bf16_f32 v96, v100, v101
	v_cvt_pk_bf16_f32 v97, v102, v103
	v_cvt_pk_bf16_f32 v98, v104, v105
	v_cvt_pk_bf16_f32 v99, v106, v107
	v_lshl_add_u64 v[100:101], v[194:195], 0, v[174:175]
	v_max_f32_e32 v92, 0, v92
	v_max_f32_e32 v88, 0, v88
	v_max_f32_e32 v93, 0, v93
	v_max_f32_e32 v89, 0, v89
	v_max_f32_e32 v94, 0, v94
	v_max_f32_e32 v90, 0, v90
	v_max_f32_e32 v95, 0, v95
	v_max_f32_e32 v91, 0, v91
	global_store_dwordx4 v[100:101], v[96:99], off
	v_pk_mul_f32 v[92:93], v[92:93], v[92:93]
	v_pk_mul_f32 v[88:89], v[88:89], v[88:89]
	v_pk_mul_f32 v[94:95], v[94:95], v[94:95]
	v_pk_mul_f32 v[96:97], v[90:91], v[90:91]
	v_pk_fma_f32 v[86:87], v[86:87], v[182:183], v[142:143] op_sel_hi:[1,0,1]
	v_pk_fma_f32 v[84:85], v[84:85], v[182:183], v[140:141] op_sel_hi:[1,0,1]
	v_pk_fma_f32 v[82:83], v[82:83], v[182:183], v[138:139] op_sel_hi:[1,0,1]
	v_pk_fma_f32 v[80:81], v[80:81], v[182:183], v[136:137] op_sel_hi:[1,0,1]
	v_cvt_pk_bf16_f32 v90, v92, v93
	v_cvt_pk_bf16_f32 v91, v94, v95
	v_cvt_pk_bf16_f32 v92, v88, v89
	v_cvt_pk_bf16_f32 v93, v96, v97
	v_lshl_add_u64 v[88:89], v[156:157], 1, v[194:195]
	v_max_f32_e32 v84, 0, v84
	v_max_f32_e32 v80, 0, v80
	v_max_f32_e32 v85, 0, v85
	v_max_f32_e32 v81, 0, v81
	v_max_f32_e32 v86, 0, v86
	v_max_f32_e32 v82, 0, v82
	v_max_f32_e32 v87, 0, v87
	v_max_f32_e32 v83, 0, v83
	global_store_dwordx4 v[88:89], v[90:93], off
	v_pk_mul_f32 v[84:85], v[84:85], v[84:85]
	v_pk_mul_f32 v[80:81], v[80:81], v[80:81]
	v_pk_mul_f32 v[86:87], v[86:87], v[86:87]
	v_pk_mul_f32 v[90:91], v[82:83], v[82:83]
	v_pk_fma_f32 v[78:79], v[78:79], v[180:181], v[142:143] op_sel_hi:[1,0,1]
	v_pk_fma_f32 v[76:77], v[76:77], v[180:181], v[140:141] op_sel_hi:[1,0,1]
; DI unsigned cvtpk(float lo, float hi) { f32x2 v = {lo, hi}; bf16x2_t b = __builtin_convertvector(v, bf16x2_t); return __builtin_bit_cast(unsigned, b); }
;     DI void operator()(const f32x4 (&acc)[2][2][4][2], const pg8::Unit& u, int wr, int wc, int fr, int fq) const {
;     ...
; #pragma unroll
;         for (int bj = 0; bj < 2; ++bj) { const f32x4 b0 = bb[bj][0], b1 = bb[bj][1];
; #pragma unroll
;             for (int ai = 0; ai < 2; ++ai)
; #pragma unroll
;                 for (int m = 0; m < 4; ++m) {
;                     f32x4 v0 = acc[ai][bj][m][0] * rstd[ai][m] + b0, v1 = acc[ai][bj][m][1] * rstd[ai][m] + b1;
;                     if (ACT == 1) {
; #pragma unroll
;                         for (int e = 0; e < 4; ++e) { float a = fmaxf(v0[e], 0.f), b = fmaxf(v1[e], 0.f); v0[e] = a * a; v1[e] = b * b; } }
;                     u32x4 w; w.x = cvtpk(v0[0], v0[1]); w.y = cvtpk(v0[2], v0[3]); w.z = cvtpk(v1[0], v1[1]); w.w = cvtpk(v1[2], v1[3]);
;                     *(u32x4*)(Ou + (wr * 64 + fr + ai * 128 + m * 16) * ldc + wc * 32 + 8 * fq + bj * 128) = w; } }
	v_pk_fma_f32 v[74:75], v[74:75], v[180:181], v[138:139] op_sel_hi:[1,0,1]
	v_pk_fma_f32 v[72:73], v[72:73], v[180:181], v[136:137] op_sel_hi:[1,0,1]
	v_cvt_pk_bf16_f32 v82, v84, v85
	v_cvt_pk_bf16_f32 v83, v86, v87
	v_cvt_pk_bf16_f32 v84, v80, v81
	v_cvt_pk_bf16_f32 v85, v90, v91
	v_lshl_add_u64 v[80:81], v[158:159], 1, v[194:195]
	v_max_f32_e32 v76, 0, v76
	v_max_f32_e32 v72, 0, v72
	v_max_f32_e32 v77, 0, v77
	v_max_f32_e32 v73, 0, v73
	v_max_f32_e32 v78, 0, v78
	v_max_f32_e32 v74, 0, v74
	v_max_f32_e32 v79, 0, v79
	v_max_f32_e32 v75, 0, v75
	global_store_dwordx4 v[80:81], v[82:85], off
	v_pk_mul_f32 v[76:77], v[76:77], v[76:77]
	v_pk_mul_f32 v[72:73], v[72:73], v[72:73]
	v_pk_mul_f32 v[78:79], v[78:79], v[78:79]
	v_pk_mul_f32 v[82:83], v[74:75], v[74:75]
	v_pk_fma_f32 v[62:63], v[62:63], v[178:179], v[142:143] op_sel_hi:[1,0,1]
	v_pk_fma_f32 v[60:61], v[60:61], v[178:179], v[140:141] op_sel_hi:[1,0,1]
	v_pk_fma_f32 v[58:59], v[58:59], v[178:179], v[138:139] op_sel_hi:[1,0,1]
	v_pk_fma_f32 v[56:57], v[56:57], v[178:179], v[136:137] op_sel_hi:[1,0,1]
	v_cvt_pk_bf16_f32 v74, v76, v77
	v_cvt_pk_bf16_f32 v75, v78, v79
	v_cvt_pk_bf16_f32 v76, v72, v73
	v_cvt_pk_bf16_f32 v77, v82, v83
	v_lshl_add_u64 v[72:73], v[160:161], 1, v[194:195]
	v_max_f32_e32 v60, 0, v60
	v_max_f32_e32 v56, 0, v56
	v_max_f32_e32 v61, 0, v61
	v_max_f32_e32 v57, 0, v57
	v_max_f32_e32 v62, 0, v62
	v_max_f32_e32 v58, 0, v58
	v_max_f32_e32 v63, 0, v63
	v_max_f32_e32 v59, 0, v59
	global_store_dwordx4 v[72:73], v[74:77], off
	v_pk_mul_f32 v[60:61], v[60:61], v[60:61]
	v_pk_mul_f32 v[56:57], v[56:57], v[56:57]
	v_pk_mul_f32 v[62:63], v[62:63], v[62:63]
	v_pk_mul_f32 v[74:75], v[58:59], v[58:59]
	v_cvt_pk_bf16_f32 v58, v60, v61
	v_cvt_pk_bf16_f32 v59, v62, v63
	v_cvt_pk_bf16_f32 v60, v56, v57
	v_cvt_pk_bf16_f32 v61, v74, v75
	v_lshl_add_u64 v[56:57], v[162:163], 1, v[194:195]
	global_store_dwordx4 v[56:57], v[58:61], off
	s_waitcnt vmcnt(9)
	v_pk_fma_f32 v[66:67], v[66:67], v[192:193], v[130:131] op_sel_hi:[1,0,1]
	v_pk_fma_f32 v[64:65], v[64:65], v[192:193], v[128:129] op_sel_hi:[1,0,1]
	s_waitcnt vmcnt(8)
	v_pk_fma_f32 v[58:59], v[70:71], v[192:193], v[134:135] op_sel_hi:[1,0,1]
	v_pk_fma_f32 v[60:61], v[68:69], v[192:193], v[132:133] op_sel_hi:[1,0,1]
	v_max_f32_e32 v64, 0, v64
	v_max_f32_e32 v60, 0, v60
	v_max_f32_e32 v61, 0, v61
	v_max_f32_e32 v65, 0, v65
	v_max_f32_e32 v58, 0, v58
	v_max_f32_e32 v66, 0, v66
	v_max_f32_e32 v59, 0, v59
	v_max_f32_e32 v67, 0, v67
	v_pk_mul_f32 v[60:61], v[60:61], v[60:61]
	v_pk_mul_f32 v[64:65], v[64:65], v[64:65]
	v_pk_mul_f32 v[68:69], v[58:59], v[58:59]
	v_pk_mul_f32 v[66:67], v[66:67], v[66:67]
	v_pk_fma_f32 v[48:49], v[48:49], v[190:191], v[128:129] op_sel_hi:[1,0,1]
	v_cvt_pk_bf16_f32 v58, v60, v61
	v_cvt_pk_bf16_f32 v59, v68, v69
	v_cvt_pk_bf16_f32 v60, v64, v65
	v_cvt_pk_bf16_f32 v61, v66, v67
	v_pk_fma_f32 v[54:55], v[54:55], v[190:191], v[134:135] op_sel_hi:[1,0,1]
	v_pk_fma_f32 v[52:53], v[52:53], v[190:191], v[132:133] op_sel_hi:[1,0,1]
	v_pk_fma_f32 v[50:51], v[50:51], v[190:191], v[130:131] op_sel_hi:[1,0,1]
	v_max_f32_e32 v48, 0, v48
	v_max_f32_e32 v49, 0, v49
	global_store_dwordx4 v[120:121], v[58:61], off offset:256
	v_max_f32_e32 v52, 0, v52
	v_max_f32_e32 v53, 0, v53
	v_pk_mul_f32 v[58:59], v[48:49], v[48:49]
	v_max_f32_e32 v48, 0, v54
	v_max_f32_e32 v50, 0, v50
	v_max_f32_e32 v49, 0, v55
	v_max_f32_e32 v51, 0, v51
	v_lshl_add_u64 v[62:63], v[194:195], 0, s[4:5]
	v_pk_mul_f32 v[52:53], v[52:53], v[52:53]
	v_pk_mul_f32 v[54:55], v[48:49], v[48:49]
	v_pk_mul_f32 v[60:61], v[50:51], v[50:51]
	v_pk_fma_f32 v[40:41], v[40:41], v[188:189], v[128:129] op_sel_hi:[1,0,1]
	v_cvt_pk_bf16_f32 v48, v52, v53
	v_cvt_pk_bf16_f32 v49, v54, v55
	v_cvt_pk_bf16_f32 v50, v58, v59
	v_cvt_pk_bf16_f32 v51, v60, v61
	v_lshl_add_u64 v[52:53], v[62:63], 0, v[170:171]
	v_pk_fma_f32 v[46:47], v[46:47], v[188:189], v[134:135] op_sel_hi:[1,0,1]
	v_pk_fma_f32 v[44:45], v[44:45], v[188:189], v[132:133] op_sel_hi:[1,0,1]
	v_pk_fma_f32 v[42:43], v[42:43], v[188:189], v[130:131] op_sel_hi:[1,0,1]
	v_max_f32_e32 v40, 0, v40
	v_max_f32_e32 v41, 0, v41
	global_store_dwordx4 v[52:53], v[48:51], off
	v_max_f32_e32 v44, 0, v44
	v_max_f32_e32 v45, 0, v45
	v_pk_mul_f32 v[48:49], v[40:41], v[40:41]
	v_max_f32_e32 v40, 0, v46
	v_max_f32_e32 v42, 0, v42
	v_max_f32_e32 v41, 0, v47
	v_max_f32_e32 v43, 0, v43
	v_pk_mul_f32 v[44:45], v[44:45], v[44:45]
	v_pk_mul_f32 v[46:47], v[40:41], v[40:41]
	v_pk_mul_f32 v[50:51], v[42:43], v[42:43]
	v_pk_fma_f32 v[32:33], v[32:33], v[186:187], v[128:129] op_sel_hi:[1,0,1]
	v_cvt_pk_bf16_f32 v40, v44, v45
; #define PG8_BAR __builtin_amdgcn_s_barrier()
; DI unsigned cvtpk(float lo, float hi) { f32x2 v = {lo, hi}; bf16x2_t b = __builtin_convertvector(v, bf16x2_t); return __builtin_bit_cast(unsigned, b); }
; template <class Epi, class Sched, bool ALIGN_EPI = false, bool SP2 = false>
; __device__ __forceinline__ void gemm_phase(PG8_LAS unsigned char* lds, const Gemm g, const Sched& S, const Epi& E, const int tid_in) {
;     ...
;         if (!has_next) break;
; #pragma unroll
;         for (int a = 0; a < 2; ++a)
; #pragma unroll
;             for (int b = 0; b < 2; ++b)
; #pragma unroll
;                 for (int m = 0; m < 4; ++m)
; #pragma unroll
;                     for (int n = 0; n < 2; ++n) acc[a][b][m][n] = (f32x4){0.f, 0.f, 0.f, 0.f};
;         cur = nxt; cA = nA; cB = nB; ++ui;
;         if constexpr (ALIGN_EPI) { if (wr == 1) PG8_BAR; }
;     DI void operator()(const f32x4 (&acc)[2][2][4][2], const pg8::Unit& u, int wr, int wc, int fr, int fq) const {
;     ...
; #pragma unroll
;         for (int bj = 0; bj < 2; ++bj) { const f32x4 b0 = bb[bj][0], b1 = bb[bj][1];
; #pragma unroll
;             for (int ai = 0; ai < 2; ++ai)
; #pragma unroll
;                 for (int m = 0; m < 4; ++m) {
;                     f32x4 v0 = acc[ai][bj][m][0] * rstd[ai][m] + b0, v1 = acc[ai][bj][m][1] * rstd[ai][m] + b1;
;                     if (ACT == 1) {
; #pragma unroll
;                         for (int e = 0; e < 4; ++e) { float a = fmaxf(v0[e], 0.f), b = fmaxf(v1[e], 0.f); v0[e] = a * a; v1[e] = b * b; } }
;                     u32x4 w; w.x = cvtpk(v0[0], v0[1]); w.y = cvtpk(v0[2], v0[3]); w.z = cvtpk(v1[0], v1[1]); w.w = cvtpk(v1[2], v1[3]);
;                     *(u32x4*)(Ou + (wr * 64 + fr + ai * 128 + m * 16) * ldc + wc * 32 + 8 * fq + bj * 128) = w; } }
	v_cvt_pk_bf16_f32 v41, v46, v47
	v_cvt_pk_bf16_f32 v42, v48, v49
	v_cvt_pk_bf16_f32 v43, v50, v51
	v_lshl_add_u64 v[44:45], v[62:63], 0, v[172:173]
	v_pk_fma_f32 v[38:39], v[38:39], v[186:187], v[134:135] op_sel_hi:[1,0,1]
	v_pk_fma_f32 v[36:37], v[36:37], v[186:187], v[132:133] op_sel_hi:[1,0,1]
	v_pk_fma_f32 v[34:35], v[34:35], v[186:187], v[130:131] op_sel_hi:[1,0,1]
	v_max_f32_e32 v32, 0, v32
	v_max_f32_e32 v33, 0, v33
	global_store_dwordx4 v[44:45], v[40:43], off
	v_max_f32_e32 v36, 0, v36
	v_max_f32_e32 v37, 0, v37
	v_pk_mul_f32 v[40:41], v[32:33], v[32:33]
	v_max_f32_e32 v32, 0, v38
	v_max_f32_e32 v34, 0, v34
	v_max_f32_e32 v33, 0, v39
	v_max_f32_e32 v35, 0, v35
	v_pk_mul_f32 v[36:37], v[36:37], v[36:37]
	v_pk_mul_f32 v[38:39], v[32:33], v[32:33]
	v_pk_mul_f32 v[42:43], v[34:35], v[34:35]
	v_pk_fma_f32 v[24:25], v[24:25], v[184:185], v[128:129] op_sel_hi:[1,0,1]
	v_cvt_pk_bf16_f32 v32, v36, v37
	v_cvt_pk_bf16_f32 v33, v38, v39
	v_cvt_pk_bf16_f32 v34, v40, v41
	v_cvt_pk_bf16_f32 v35, v42, v43
	v_lshl_add_u64 v[36:37], v[62:63], 0, v[174:175]
	v_pk_fma_f32 v[30:31], v[30:31], v[184:185], v[134:135] op_sel_hi:[1,0,1]
	v_pk_fma_f32 v[28:29], v[28:29], v[184:185], v[132:133] op_sel_hi:[1,0,1]
	v_pk_fma_f32 v[26:27], v[26:27], v[184:185], v[130:131] op_sel_hi:[1,0,1]
	v_max_f32_e32 v24, 0, v24
	v_max_f32_e32 v25, 0, v25
	global_store_dwordx4 v[36:37], v[32:35], off
	v_max_f32_e32 v28, 0, v28
	v_max_f32_e32 v29, 0, v29
	v_pk_mul_f32 v[32:33], v[24:25], v[24:25]
	v_max_f32_e32 v24, 0, v30
	v_max_f32_e32 v26, 0, v26
	v_max_f32_e32 v25, 0, v31
	v_max_f32_e32 v27, 0, v27
	v_pk_mul_f32 v[28:29], v[28:29], v[28:29]
	v_pk_mul_f32 v[30:31], v[24:25], v[24:25]
	v_pk_mul_f32 v[34:35], v[26:27], v[26:27]
	v_pk_fma_f32 v[16:17], v[16:17], v[182:183], v[128:129] op_sel_hi:[1,0,1]
	v_cvt_pk_bf16_f32 v24, v28, v29
	v_cvt_pk_bf16_f32 v25, v30, v31
	v_cvt_pk_bf16_f32 v26, v32, v33
	v_cvt_pk_bf16_f32 v27, v34, v35
	v_pk_fma_f32 v[22:23], v[22:23], v[182:183], v[134:135] op_sel_hi:[1,0,1]
	v_pk_fma_f32 v[20:21], v[20:21], v[182:183], v[132:133] op_sel_hi:[1,0,1]
	v_pk_fma_f32 v[18:19], v[18:19], v[182:183], v[130:131] op_sel_hi:[1,0,1]
	v_max_f32_e32 v16, 0, v16
	v_max_f32_e32 v17, 0, v17
	global_store_dwordx4 v[88:89], v[24:27], off offset:256
	v_max_f32_e32 v20, 0, v20
	v_max_f32_e32 v21, 0, v21
	v_pk_mul_f32 v[24:25], v[16:17], v[16:17]
	v_max_f32_e32 v16, 0, v22
	v_max_f32_e32 v18, 0, v18
	v_max_f32_e32 v17, 0, v23
	v_max_f32_e32 v19, 0, v19
	v_pk_mul_f32 v[20:21], v[20:21], v[20:21]
	v_pk_mul_f32 v[22:23], v[16:17], v[16:17]
	v_pk_mul_f32 v[26:27], v[18:19], v[18:19]
	v_pk_fma_f32 v[8:9], v[8:9], v[180:181], v[128:129] op_sel_hi:[1,0,1]
	v_cvt_pk_bf16_f32 v16, v20, v21
	v_cvt_pk_bf16_f32 v17, v22, v23
	v_cvt_pk_bf16_f32 v18, v24, v25
	v_cvt_pk_bf16_f32 v19, v26, v27
	v_pk_fma_f32 v[14:15], v[14:15], v[180:181], v[134:135] op_sel_hi:[1,0,1]
	v_pk_fma_f32 v[12:13], v[12:13], v[180:181], v[132:133] op_sel_hi:[1,0,1]
	v_pk_fma_f32 v[10:11], v[10:11], v[180:181], v[130:131] op_sel_hi:[1,0,1]
	v_max_f32_e32 v8, 0, v8
	v_max_f32_e32 v9, 0, v9
	global_store_dwordx4 v[80:81], v[16:19], off offset:256
	v_max_f32_e32 v12, 0, v12
	v_max_f32_e32 v13, 0, v13
	v_pk_mul_f32 v[16:17], v[8:9], v[8:9]
	v_max_f32_e32 v8, 0, v14
	v_max_f32_e32 v10, 0, v10
	v_max_f32_e32 v9, 0, v15
	v_max_f32_e32 v11, 0, v11
	v_pk_mul_f32 v[12:13], v[12:13], v[12:13]
	v_pk_mul_f32 v[14:15], v[8:9], v[8:9]
	v_pk_mul_f32 v[18:19], v[10:11], v[10:11]
	v_pk_fma_f32 v[0:1], v[0:1], v[178:179], v[128:129] op_sel_hi:[1,0,1]
	v_cvt_pk_bf16_f32 v8, v12, v13
	v_cvt_pk_bf16_f32 v9, v14, v15
	v_cvt_pk_bf16_f32 v10, v16, v17
	v_cvt_pk_bf16_f32 v11, v18, v19
	v_pk_fma_f32 v[6:7], v[6:7], v[178:179], v[134:135] op_sel_hi:[1,0,1]
	v_pk_fma_f32 v[4:5], v[4:5], v[178:179], v[132:133] op_sel_hi:[1,0,1]
	v_pk_fma_f32 v[2:3], v[2:3], v[178:179], v[130:131] op_sel_hi:[1,0,1]
	v_max_f32_e32 v0, 0, v0
	v_max_f32_e32 v1, 0, v1
	global_store_dwordx4 v[72:73], v[8:11], off offset:256
	v_max_f32_e32 v4, 0, v4
	v_max_f32_e32 v5, 0, v5
	v_pk_mul_f32 v[8:9], v[0:1], v[0:1]
	v_max_f32_e32 v0, 0, v6
	v_max_f32_e32 v2, 0, v2
	v_max_f32_e32 v1, 0, v7
	v_max_f32_e32 v3, 0, v3
	v_pk_mul_f32 v[4:5], v[4:5], v[4:5]
	v_pk_mul_f32 v[6:7], v[0:1], v[0:1]
	v_pk_mul_f32 v[10:11], v[2:3], v[2:3]
	v_cvt_pk_bf16_f32 v0, v4, v5
	v_cvt_pk_bf16_f32 v1, v6, v7
	v_cvt_pk_bf16_f32 v2, v8, v9
	v_cvt_pk_bf16_f32 v3, v10, v11
	s_mov_b64 s[4:5], -1
	global_store_dwordx4 v[56:57], v[0:3], off offset:256
	s_cbranch_vccnz .LBB0_1023
	s_andn2_b64 vcc, exec, s[0:1]
	s_cbranch_vccnz .LBB0_1022
	s_barrier
	s_branch .LBB0_1022

;     DI void operator()(const f32x4 (&acc)[2][2][4][2], const pg8::Unit& u, int wr, int wc, int fr, int fq) const {
;         const int lrow0 = u.pm * 256 + wr * 64 + fr, grow0 = row_base + u.pm * 256, col0 = u.pn * 256 + wc * 32 + 8 * fq;
;         bf16* Ou = O + (size_t)(u.pm * 256) * ldc + u.pn * 256;
;         const int mrow = grow0 < NCTX ? 8 : (grow0 - NCTX) >> 12;
;         float rstd[2][4];
; #pragma unroll
;         for (int ai = 0; ai < 2; ++ai)
; #pragma unroll
;             for (int m = 0; m < 4; ++m) rstd[ai][m] = rsqrtf(rss[row_base + lrow0 + ai * 128 + m * 16] * (1.f / DM) + EPS);
;         const float* bp = bias + mrow * 4096 + col0;
;         f32x4 bb[2][2];
; #pragma unroll
;         for (int bj = 0; bj < 2; ++bj) { bb[bj][0] = *(const f32x4*)(bp + bj * 128); bb[bj][1] = *(const f32x4*)(bp + bj * 128 + 4); }
;         asm volatile("" ::: "memory");
; #pragma unroll
;         for (int bj = 0; bj < 2; ++bj) { const f32x4 b0 = bb[bj][0], b1 = bb[bj][1];
; #pragma unroll
;             for (int ai = 0; ai < 2; ++ai)
; #pragma unroll
;                 for (int m = 0; m < 4; ++m) {
;                     f32x4 v0 = acc[ai][bj][m][0] * rstd[ai][m] + b0, v1 = acc[ai][bj][m][1] * rstd[ai][m] + b1;
.LBB0_1097:
	s_lshl_b32 s6, s48, 8
	v_add_u32_e32 v128, s6, v179
	v_ashrrev_i32_e32 v129, 31, v128
	v_lshl_add_u64 v[128:129], v[128:129], 2, s[86:87]
	global_load_dword v200, v[128:129], off
	global_load_dword v201, v[128:129], off offset:64
	global_load_dword v202, v[128:129], off offset:128
	global_load_dword v203, v[128:129], off offset:192
	global_load_dword v204, v[128:129], off offset:512
	global_load_dword v205, v[128:129], off offset:576
	global_load_dword v206, v[128:129], off offset:640
	global_load_dword v207, v[128:129], off offset:704
	s_lshl_b32 s4, s31, 8
	s_ashr_i32 s7, s6, 31
	s_ashr_i32 s5, s4, 31
	s_lshl_b64 s[8:9], s[6:7], 13
	s_add_u32 s8, s88, s8
	s_addc_u32 s9, s89, s9
	s_addk_i32 s6, 0xf800
	s_and_b32 s6, s6, 0xfffff000
	s_cmp_gt_i32 s48, 7
	s_cselect_b32 s6, s6, 0x8000
	s_ashr_i32 s7, s6, 31
	s_lshl_b64 s[6:7], s[6:7], 2
	v_readlane_b32 s22, v253, 61
	v_readlane_b32 s23, v253, 62
	s_add_u32 s6, s22, s6
	s_addc_u32 s7, s23, s7
	v_or_b32_e32 v208, s4, v183
	v_ashrrev_i32_e32 v209, 31, v208
	v_lshl_add_u64 v[208:209], v[208:209], 2, s[6:7]
	global_load_dwordx4 v[220:223], v[208:209], off offset:16
	global_load_dwordx4 v[224:227], v[208:209], off
	global_load_dwordx4 v[228:231], v[208:209], off offset:528
	global_load_dwordx4 v[232:235], v[208:209], off offset:512
	s_waitcnt vmcnt(11)
	v_fmamk_f32 v200, v200, 0x3a800000, v189
	v_cmp_gt_f32_e32 vcc, s60, v200
	v_mul_f32_e32 v131, 0x4b800000, v200
	s_nop 0
	v_cndmask_b32_e32 v200, v200, v131, vcc
	v_rsq_f32_e32 v200, v200
	s_nop 0
	v_mul_f32_e32 v131, 0x45800000, v200
	v_cndmask_b32_e32 v192, v200, v131, vcc
	s_waitcnt vmcnt(10)
	v_fmamk_f32 v201, v201, 0x3a800000, v189
	v_cmp_gt_f32_e32 vcc, s60, v201
	v_mul_f32_e32 v131, 0x4b800000, v201
	s_nop 0
	v_cndmask_b32_e32 v201, v201, v131, vcc
	v_rsq_f32_e32 v201, v201
	s_nop 0
	v_mul_f32_e32 v131, 0x45800000, v201
	v_cndmask_b32_e32 v190, v201, v131, vcc
	s_waitcnt vmcnt(9)
	v_fmamk_f32 v202, v202, 0x3a800000, v189
	v_cmp_gt_f32_e32 vcc, s60, v202
	v_mul_f32_e32 v131, 0x4b800000, v202
	s_nop 0
	v_cndmask_b32_e32 v202, v202, v131, vcc
	v_rsq_f32_e32 v202, v202
	s_nop 0
	v_mul_f32_e32 v131, 0x45800000, v202
	v_cndmask_b32_e32 v188, v202, v131, vcc
	s_waitcnt vmcnt(8)
	v_fmamk_f32 v203, v203, 0x3a800000, v189
	v_cmp_gt_f32_e32 vcc, s60, v203
	v_mul_f32_e32 v131, 0x4b800000, v203
	s_nop 0
	v_cndmask_b32_e32 v203, v203, v131, vcc
	v_rsq_f32_e32 v203, v203
	s_nop 0
	v_mul_f32_e32 v131, 0x45800000, v203
	v_cndmask_b32_e32 v186, v203, v131, vcc
	s_waitcnt vmcnt(7)
	v_fmamk_f32 v204, v204, 0x3a800000, v189
	v_cmp_gt_f32_e32 vcc, s60, v204
	v_mul_f32_e32 v131, 0x4b800000, v204
	s_nop 0
	v_cndmask_b32_e32 v204, v204, v131, vcc
	v_rsq_f32_e32 v204, v204
	s_nop 0
	v_mul_f32_e32 v131, 0x45800000, v204
	v_cndmask_b32_e32 v184, v204, v131, vcc
	s_waitcnt vmcnt(6)
	v_fmamk_f32 v205, v205, 0x3a800000, v189
	v_cmp_gt_f32_e32 vcc, s60, v205
	v_mul_f32_e32 v131, 0x4b800000, v205
	s_nop 0
	v_cndmask_b32_e32 v205, v205, v131, vcc
	v_rsq_f32_e32 v205, v205
	s_nop 0
	v_mul_f32_e32 v131, 0x45800000, v205
	v_cndmask_b32_e32 v182, v205, v131, vcc
	s_waitcnt vmcnt(5)
	v_fmamk_f32 v206, v206, 0x3a800000, v189
	v_cmp_gt_f32_e32 vcc, s60, v206
	v_mul_f32_e32 v131, 0x4b800000, v206
	s_waitcnt vmcnt(4)
	v_fmamk_f32 v207, v207, 0x3a800000, v189
	v_cndmask_b32_e32 v206, v206, v131, vcc
	v_rsq_f32_e32 v206, v206
	v_mul_f32_e32 v129, 0x4b800000, v207
	v_mul_f32_e32 v131, 0x45800000, v206
	v_cndmask_b32_e32 v180, v206, v131, vcc
	v_cmp_gt_f32_e32 vcc, s60, v207
	s_nop 1
	v_cndmask_b32_e32 v207, v207, v129, vcc
	v_rsq_f32_e32 v207, v207
	s_nop 0
	v_mul_f32_e32 v129, 0x45800000, v207
	v_cndmask_b32_e32 v178, v207, v129, vcc
	v_or_b32_e32 v128, s4, v183
	v_ashrrev_i32_e32 v129, 31, v128
	v_lshl_add_u64 v[132:133], v[128:129], 2, s[6:7]
	s_waitcnt vmcnt(0)
	v_mov_b32_e32 v136, v220
	v_mov_b32_e32 v137, v221
	v_mov_b32_e32 v138, v222
	v_mov_b32_e32 v139, v223
	v_mov_b32_e32 v140, v224
	v_mov_b32_e32 v141, v225
	v_mov_b32_e32 v142, v226
	v_mov_b32_e32 v143, v227
	v_mov_b32_e32 v128, v228
	v_mov_b32_e32 v129, v229
	v_mov_b32_e32 v130, v230
	v_mov_b32_e32 v131, v231
	v_mov_b32_e32 v132, v232
	v_mov_b32_e32 v133, v233
	v_mov_b32_e32 v134, v234
	v_mov_b32_e32 v135, v235
	s_nop 0
	s_nop 0
	s_nop 0
	s_nop 0
	s_nop 0
	s_nop 0
	s_nop 0
	s_nop 0
	s_nop 0
	s_nop 0
	s_nop 0
	s_nop 0
	s_lshl_b64 s[4:5], s[4:5], 1
	s_add_u32 s4, s8, s4
	s_addc_u32 s5, s9, s5
	s_add_u32 s4, s4, s61
	s_addc_u32 s5, s5, 0
	v_lshl_add_u64 v[194:195], s[4:5], 0, v[152:153]
	s_mov_b64 s[4:5], 0x100
	s_andn2_b64 vcc, exec, s[36:37]
	s_waitcnt vmcnt(3)
	v_pk_fma_f32 v[122:123], v[122:123], v[192:193], v[138:139] op_sel_hi:[1,0,1]
	s_waitcnt vmcnt(2)
; DI unsigned cvtpk(float lo, float hi) { f32x2 v = {lo, hi}; bf16x2_t b = __builtin_convertvector(v, bf16x2_t); return __builtin_bit_cast(unsigned, b); }
;     DI void operator()(const f32x4 (&acc)[2][2][4][2], const pg8::Unit& u, int wr, int wc, int fr, int fq) const {
;     ...
; #pragma unroll
;         for (int bj = 0; bj < 2; ++bj) { const f32x4 b0 = bb[bj][0], b1 = bb[bj][1];
; #pragma unroll
;             for (int ai = 0; ai < 2; ++ai)
; #pragma unroll
;                 for (int m = 0; m < 4; ++m) {
;                     f32x4 v0 = acc[ai][bj][m][0] * rstd[ai][m] + b0, v1 = acc[ai][bj][m][1] * rstd[ai][m] + b1;
;                     if (ACT == 1) {
; #pragma unroll
;                         for (int e = 0; e < 4; ++e) { float a = fmaxf(v0[e], 0.f), b = fmaxf(v1[e], 0.f); v0[e] = a * a; v1[e] = b * b; } }
;                     u32x4 w; w.x = cvtpk(v0[0], v0[1]); w.y = cvtpk(v0[2], v0[3]); w.z = cvtpk(v1[0], v1[1]); w.w = cvtpk(v1[2], v1[3]);
;                     *(u32x4*)(Ou + (wr * 64 + fr + ai * 128 + m * 16) * ldc + wc * 32 + 8 * fq + bj * 128) = w; } }
	v_pk_fma_f32 v[126:127], v[126:127], v[192:193], v[142:143] op_sel_hi:[1,0,1]
	v_pk_fma_f32 v[124:125], v[124:125], v[192:193], v[140:141] op_sel_hi:[1,0,1]
	v_pk_fma_f32 v[120:121], v[120:121], v[192:193], v[136:137] op_sel_hi:[1,0,1]
	v_max_f32_e32 v124, 0, v124
	v_max_f32_e32 v120, 0, v120
	v_max_f32_e32 v125, 0, v125
	v_max_f32_e32 v121, 0, v121
	v_max_f32_e32 v126, 0, v126
	v_max_f32_e32 v122, 0, v122
	v_max_f32_e32 v127, 0, v127
	v_max_f32_e32 v123, 0, v123
	v_pk_mul_f32 v[124:125], v[124:125], v[124:125]
	v_pk_mul_f32 v[120:121], v[120:121], v[120:121]
	v_pk_mul_f32 v[126:127], v[126:127], v[126:127]
	v_pk_mul_f32 v[196:197], v[122:123], v[122:123]
	v_pk_fma_f32 v[112:113], v[112:113], v[190:191], v[136:137] op_sel_hi:[1,0,1]
	v_cvt_pk_bf16_f32 v122, v124, v125
	v_cvt_pk_bf16_f32 v123, v126, v127
	v_cvt_pk_bf16_f32 v124, v120, v121
	v_cvt_pk_bf16_f32 v125, v196, v197
	v_lshl_add_u64 v[120:121], v[154:155], 1, v[194:195]
	v_pk_fma_f32 v[118:119], v[118:119], v[190:191], v[142:143] op_sel_hi:[1,0,1]
	v_pk_fma_f32 v[116:117], v[116:117], v[190:191], v[140:141] op_sel_hi:[1,0,1]
	v_pk_fma_f32 v[114:115], v[114:115], v[190:191], v[138:139] op_sel_hi:[1,0,1]
	v_max_f32_e32 v112, 0, v112
	v_max_f32_e32 v113, 0, v113
	global_store_dwordx4 v[120:121], v[122:125], off
	v_max_f32_e32 v116, 0, v116
	v_max_f32_e32 v117, 0, v117
	v_pk_mul_f32 v[122:123], v[112:113], v[112:113]
	v_max_f32_e32 v112, 0, v118
	v_max_f32_e32 v114, 0, v114
	v_max_f32_e32 v113, 0, v119
	v_max_f32_e32 v115, 0, v115
	v_pk_mul_f32 v[116:117], v[116:117], v[116:117]
	v_pk_mul_f32 v[118:119], v[112:113], v[112:113]
	v_pk_mul_f32 v[124:125], v[114:115], v[114:115]
	v_pk_fma_f32 v[104:105], v[104:105], v[188:189], v[136:137] op_sel_hi:[1,0,1]
	v_cvt_pk_bf16_f32 v112, v116, v117
	v_cvt_pk_bf16_f32 v113, v118, v119
	v_cvt_pk_bf16_f32 v114, v122, v123
	v_cvt_pk_bf16_f32 v115, v124, v125
	v_lshl_add_u64 v[116:117], v[194:195], 0, v[170:171]
	v_pk_fma_f32 v[110:111], v[110:111], v[188:189], v[142:143] op_sel_hi:[1,0,1]
	v_pk_fma_f32 v[108:109], v[108:109], v[188:189], v[140:141] op_sel_hi:[1,0,1]
	v_pk_fma_f32 v[106:107], v[106:107], v[188:189], v[138:139] op_sel_hi:[1,0,1]
	v_max_f32_e32 v104, 0, v104
	v_max_f32_e32 v105, 0, v105
	global_store_dwordx4 v[116:117], v[112:115], off
	v_max_f32_e32 v108, 0, v108
	v_max_f32_e32 v109, 0, v109
	v_pk_mul_f32 v[112:113], v[104:105], v[104:105]
	v_max_f32_e32 v104, 0, v110
	v_max_f32_e32 v106, 0, v106
	v_max_f32_e32 v105, 0, v111
	v_max_f32_e32 v107, 0, v107
	v_pk_mul_f32 v[108:109], v[108:109], v[108:109]
	v_pk_mul_f32 v[110:111], v[104:105], v[104:105]
	v_pk_mul_f32 v[114:115], v[106:107], v[106:107]
	v_pk_fma_f32 v[96:97], v[96:97], v[186:187], v[136:137] op_sel_hi:[1,0,1]
	v_cvt_pk_bf16_f32 v104, v108, v109
	v_cvt_pk_bf16_f32 v105, v110, v111
	v_cvt_pk_bf16_f32 v106, v112, v113
	v_cvt_pk_bf16_f32 v107, v114, v115
	v_lshl_add_u64 v[108:109], v[194:195], 0, v[172:173]
	v_pk_fma_f32 v[102:103], v[102:103], v[186:187], v[142:143] op_sel_hi:[1,0,1]
	v_pk_fma_f32 v[100:101], v[100:101], v[186:187], v[140:141] op_sel_hi:[1,0,1]
	v_pk_fma_f32 v[98:99], v[98:99], v[186:187], v[138:139] op_sel_hi:[1,0,1]
	v_max_f32_e32 v96, 0, v96
	v_max_f32_e32 v97, 0, v97
	global_store_dwordx4 v[108:109], v[104:107], off
	v_max_f32_e32 v100, 0, v100
	v_max_f32_e32 v101, 0, v101
	v_pk_mul_f32 v[104:105], v[96:97], v[96:97]
	v_max_f32_e32 v96, 0, v102
	v_max_f32_e32 v98, 0, v98
	v_max_f32_e32 v97, 0, v103
	v_max_f32_e32 v99, 0, v99
	v_pk_mul_f32 v[100:101], v[100:101], v[100:101]
	v_pk_mul_f32 v[102:103], v[96:97], v[96:97]
	v_pk_mul_f32 v[106:107], v[98:99], v[98:99]
	v_pk_fma_f32 v[94:95], v[94:95], v[184:185], v[142:143] op_sel_hi:[1,0,1]
	v_pk_fma_f32 v[92:93], v[92:93], v[184:185], v[140:141] op_sel_hi:[1,0,1]
	v_pk_fma_f32 v[90:91], v[90:91], v[184:185], v[138:139] op_sel_hi:[1,0,1]
	v_pk_fma_f32 v[88:89], v[88:89], v[184:185], v[136:137] op_sel_hi:[1,0,1]
	v_cvt_pk_bf16_f32 v96, v100, v101
	v_cvt_pk_bf16_f32 v97, v102, v103
	v_cvt_pk_bf16_f32 v98, v104, v105
	v_cvt_pk_bf16_f32 v99, v106, v107
	v_lshl_add_u64 v[100:101], v[194:195], 0, v[174:175]
	v_max_f32_e32 v92, 0, v92
	v_max_f32_e32 v88, 0, v88
	v_max_f32_e32 v93, 0, v93
	v_max_f32_e32 v89, 0, v89
	v_max_f32_e32 v94, 0, v94
	v_max_f32_e32 v90, 0, v90
	v_max_f32_e32 v95, 0, v95
	v_max_f32_e32 v91, 0, v91
	global_store_dwordx4 v[100:101], v[96:99], off
	v_pk_mul_f32 v[92:93], v[92:93], v[92:93]
	v_pk_mul_f32 v[88:89], v[88:89], v[88:89]
	v_pk_mul_f32 v[94:95], v[94:95], v[94:95]
	v_pk_mul_f32 v[96:97], v[90:91], v[90:91]
	v_pk_fma_f32 v[86:87], v[86:87], v[182:183], v[142:143] op_sel_hi:[1,0,1]
	v_pk_fma_f32 v[84:85], v[84:85], v[182:183], v[140:141] op_sel_hi:[1,0,1]
	v_pk_fma_f32 v[82:83], v[82:83], v[182:183], v[138:139] op_sel_hi:[1,0,1]
	v_pk_fma_f32 v[80:81], v[80:81], v[182:183], v[136:137] op_sel_hi:[1,0,1]
	v_cvt_pk_bf16_f32 v90, v92, v93
	v_cvt_pk_bf16_f32 v91, v94, v95
	v_cvt_pk_bf16_f32 v92, v88, v89
	v_cvt_pk_bf16_f32 v93, v96, v97
	v_lshl_add_u64 v[88:89], v[156:157], 1, v[194:195]
	v_max_f32_e32 v84, 0, v84
	v_max_f32_e32 v80, 0, v80
	v_max_f32_e32 v85, 0, v85
	v_max_f32_e32 v81, 0, v81
	v_max_f32_e32 v86, 0, v86
	v_max_f32_e32 v82, 0, v82
	v_max_f32_e32 v87, 0, v87
	v_max_f32_e32 v83, 0, v83
	global_store_dwordx4 v[88:89], v[90:93], off
	v_pk_mul_f32 v[84:85], v[84:85], v[84:85]
	v_pk_mul_f32 v[80:81], v[80:81], v[80:81]
	v_pk_mul_f32 v[86:87], v[86:87], v[86:87]
	v_pk_mul_f32 v[90:91], v[82:83], v[82:83]
	v_pk_fma_f32 v[78:79], v[78:79], v[180:181], v[142:143] op_sel_hi:[1,0,1]
	v_pk_fma_f32 v[76:77], v[76:77], v[180:181], v[140:141] op_sel_hi:[1,0,1]
; DI unsigned cvtpk(float lo, float hi) { f32x2 v = {lo, hi}; bf16x2_t b = __builtin_convertvector(v, bf16x2_t); return __builtin_bit_cast(unsigned, b); }
;     DI void operator()(const f32x4 (&acc)[2][2][4][2], const pg8::Unit& u, int wr, int wc, int fr, int fq) const {
;     ...
; #pragma unroll
;         for (int bj = 0; bj < 2; ++bj) { const f32x4 b0 = bb[bj][0], b1 = bb[bj][1];
; #pragma unroll
;             for (int ai = 0; ai < 2; ++ai)
; #pragma unroll
;                 for (int m = 0; m < 4; ++m) {
;                     f32x4 v0 = acc[ai][bj][m][0] * rstd[ai][m] + b0, v1 = acc[ai][bj][m][1] * rstd[ai][m] + b1;
;                     if (ACT == 1) {
; #pragma unroll
;                         for (int e = 0; e < 4; ++e) { float a = fmaxf(v0[e], 0.f), b = fmaxf(v1[e], 0.f); v0[e] = a * a; v1[e] = b * b; } }
;                     u32x4 w; w.x = cvtpk(v0[0], v0[1]); w.y = cvtpk(v0[2], v0[3]); w.z = cvtpk(v1[0], v1[1]); w.w = cvtpk(v1[2], v1[3]);
;                     *(u32x4*)(Ou + (wr * 64 + fr + ai * 128 + m * 16) * ldc + wc * 32 + 8 * fq + bj * 128) = w; } }
	v_pk_fma_f32 v[74:75], v[74:75], v[180:181], v[138:139] op_sel_hi:[1,0,1]
	v_pk_fma_f32 v[72:73], v[72:73], v[180:181], v[136:137] op_sel_hi:[1,0,1]
	v_cvt_pk_bf16_f32 v82, v84, v85
	v_cvt_pk_bf16_f32 v83, v86, v87
	v_cvt_pk_bf16_f32 v84, v80, v81
	v_cvt_pk_bf16_f32 v85, v90, v91
	v_lshl_add_u64 v[80:81], v[158:159], 1, v[194:195]
	v_max_f32_e32 v76, 0, v76
	v_max_f32_e32 v72, 0, v72
	v_max_f32_e32 v77, 0, v77
	v_max_f32_e32 v73, 0, v73
	v_max_f32_e32 v78, 0, v78
	v_max_f32_e32 v74, 0, v74
	v_max_f32_e32 v79, 0, v79
	v_max_f32_e32 v75, 0, v75
	global_store_dwordx4 v[80:81], v[82:85], off
	v_pk_mul_f32 v[76:77], v[76:77], v[76:77]
	v_pk_mul_f32 v[72:73], v[72:73], v[72:73]
	v_pk_mul_f32 v[78:79], v[78:79], v[78:79]
	v_pk_mul_f32 v[82:83], v[74:75], v[74:75]
	v_pk_fma_f32 v[62:63], v[62:63], v[178:179], v[142:143] op_sel_hi:[1,0,1]
	v_pk_fma_f32 v[60:61], v[60:61], v[178:179], v[140:141] op_sel_hi:[1,0,1]
	v_pk_fma_f32 v[58:59], v[58:59], v[178:179], v[138:139] op_sel_hi:[1,0,1]
	v_pk_fma_f32 v[56:57], v[56:57], v[178:179], v[136:137] op_sel_hi:[1,0,1]
	v_cvt_pk_bf16_f32 v74, v76, v77
	v_cvt_pk_bf16_f32 v75, v78, v79
	v_cvt_pk_bf16_f32 v76, v72, v73
	v_cvt_pk_bf16_f32 v77, v82, v83
	v_lshl_add_u64 v[72:73], v[160:161], 1, v[194:195]
	v_max_f32_e32 v60, 0, v60
	v_max_f32_e32 v56, 0, v56
	v_max_f32_e32 v61, 0, v61
	v_max_f32_e32 v57, 0, v57
	v_max_f32_e32 v62, 0, v62
	v_max_f32_e32 v58, 0, v58
	v_max_f32_e32 v63, 0, v63
	v_max_f32_e32 v59, 0, v59
	global_store_dwordx4 v[72:73], v[74:77], off
	v_pk_mul_f32 v[60:61], v[60:61], v[60:61]
	v_pk_mul_f32 v[56:57], v[56:57], v[56:57]
	v_pk_mul_f32 v[62:63], v[62:63], v[62:63]
	v_pk_mul_f32 v[74:75], v[58:59], v[58:59]
	v_cvt_pk_bf16_f32 v58, v60, v61
	v_cvt_pk_bf16_f32 v59, v62, v63
	v_cvt_pk_bf16_f32 v60, v56, v57
	v_cvt_pk_bf16_f32 v61, v74, v75
	v_lshl_add_u64 v[56:57], v[162:163], 1, v[194:195]
	global_store_dwordx4 v[56:57], v[58:61], off
	s_waitcnt vmcnt(9)
	v_pk_fma_f32 v[66:67], v[66:67], v[192:193], v[130:131] op_sel_hi:[1,0,1]
	v_pk_fma_f32 v[64:65], v[64:65], v[192:193], v[128:129] op_sel_hi:[1,0,1]
	s_waitcnt vmcnt(8)
	v_pk_fma_f32 v[58:59], v[70:71], v[192:193], v[134:135] op_sel_hi:[1,0,1]
	v_pk_fma_f32 v[60:61], v[68:69], v[192:193], v[132:133] op_sel_hi:[1,0,1]
	v_max_f32_e32 v64, 0, v64
	v_max_f32_e32 v60, 0, v60
	v_max_f32_e32 v61, 0, v61
	v_max_f32_e32 v65, 0, v65
	v_max_f32_e32 v58, 0, v58
	v_max_f32_e32 v66, 0, v66
	v_max_f32_e32 v59, 0, v59
	v_max_f32_e32 v67, 0, v67
	v_pk_mul_f32 v[60:61], v[60:61], v[60:61]
	v_pk_mul_f32 v[64:65], v[64:65], v[64:65]
	v_pk_mul_f32 v[68:69], v[58:59], v[58:59]
	v_pk_mul_f32 v[66:67], v[66:67], v[66:67]
	v_pk_fma_f32 v[48:49], v[48:49], v[190:191], v[128:129] op_sel_hi:[1,0,1]
	v_cvt_pk_bf16_f32 v58, v60, v61
	v_cvt_pk_bf16_f32 v59, v68, v69
	v_cvt_pk_bf16_f32 v60, v64, v65
	v_cvt_pk_bf16_f32 v61, v66, v67
	v_pk_fma_f32 v[54:55], v[54:55], v[190:191], v[134:135] op_sel_hi:[1,0,1]
	v_pk_fma_f32 v[52:53], v[52:53], v[190:191], v[132:133] op_sel_hi:[1,0,1]
	v_pk_fma_f32 v[50:51], v[50:51], v[190:191], v[130:131] op_sel_hi:[1,0,1]
	v_max_f32_e32 v48, 0, v48
	v_max_f32_e32 v49, 0, v49
	global_store_dwordx4 v[120:121], v[58:61], off offset:256
	v_max_f32_e32 v52, 0, v52
	v_max_f32_e32 v53, 0, v53
	v_pk_mul_f32 v[58:59], v[48:49], v[48:49]
	v_max_f32_e32 v48, 0, v54
	v_max_f32_e32 v50, 0, v50
	v_max_f32_e32 v49, 0, v55
	v_max_f32_e32 v51, 0, v51
	v_lshl_add_u64 v[62:63], v[194:195], 0, s[4:5]
	v_pk_mul_f32 v[52:53], v[52:53], v[52:53]
	v_pk_mul_f32 v[54:55], v[48:49], v[48:49]
	v_pk_mul_f32 v[60:61], v[50:51], v[50:51]
	v_pk_fma_f32 v[40:41], v[40:41], v[188:189], v[128:129] op_sel_hi:[1,0,1]
	v_cvt_pk_bf16_f32 v48, v52, v53
	v_cvt_pk_bf16_f32 v49, v54, v55
	v_cvt_pk_bf16_f32 v50, v58, v59
	v_cvt_pk_bf16_f32 v51, v60, v61
	v_lshl_add_u64 v[52:53], v[62:63], 0, v[170:171]
	v_pk_fma_f32 v[46:47], v[46:47], v[188:189], v[134:135] op_sel_hi:[1,0,1]
	v_pk_fma_f32 v[44:45], v[44:45], v[188:189], v[132:133] op_sel_hi:[1,0,1]
	v_pk_fma_f32 v[42:43], v[42:43], v[188:189], v[130:131] op_sel_hi:[1,0,1]
	v_max_f32_e32 v40, 0, v40
	v_max_f32_e32 v41, 0, v41
	global_store_dwordx4 v[52:53], v[48:51], off
	v_max_f32_e32 v44, 0, v44
	v_max_f32_e32 v45, 0, v45
	v_pk_mul_f32 v[48:49], v[40:41], v[40:41]
	v_max_f32_e32 v40, 0, v46
	v_max_f32_e32 v42, 0, v42
	v_max_f32_e32 v41, 0, v47
	v_max_f32_e32 v43, 0, v43
	v_pk_mul_f32 v[44:45], v[44:45], v[44:45]
	v_pk_mul_f32 v[46:47], v[40:41], v[40:41]
	v_pk_mul_f32 v[50:51], v[42:43], v[42:43]
	v_pk_fma_f32 v[32:33], v[32:33], v[186:187], v[128:129] op_sel_hi:[1,0,1]
	v_cvt_pk_bf16_f32 v40, v44, v45
; #define PG8_BAR __builtin_amdgcn_s_barrier()
; DI unsigned cvtpk(float lo, float hi) { f32x2 v = {lo, hi}; bf16x2_t b = __builtin_convertvector(v, bf16x2_t); return __builtin_bit_cast(unsigned, b); }
; template <class Epi, class Sched, bool ALIGN_EPI = false, bool SP2 = false>
; __device__ __forceinline__ void gemm_phase(PG8_LAS unsigned char* lds, const Gemm g, const Sched& S, const Epi& E, const int tid_in) {
;     ...
;         if (!has_next) break;
; #pragma unroll
;         for (int a = 0; a < 2; ++a)
; #pragma unroll
;             for (int b = 0; b < 2; ++b)
; #pragma unroll
;                 for (int m = 0; m < 4; ++m)
; #pragma unroll
;                     for (int n = 0; n < 2; ++n) acc[a][b][m][n] = (f32x4){0.f, 0.f, 0.f, 0.f};
;         cur = nxt; cA = nA; cB = nB; ++ui;
;         if constexpr (ALIGN_EPI) { if (wr == 1) PG8_BAR; }
;     DI void operator()(const f32x4 (&acc)[2][2][4][2], const pg8::Unit& u, int wr, int wc, int fr, int fq) const {
;     ...
; #pragma unroll
;         for (int bj = 0; bj < 2; ++bj) { const f32x4 b0 = bb[bj][0], b1 = bb[bj][1];
; #pragma unroll
;             for (int ai = 0; ai < 2; ++ai)
; #pragma unroll
;                 for (int m = 0; m < 4; ++m) {
;                     f32x4 v0 = acc[ai][bj][m][0] * rstd[ai][m] + b0, v1 = acc[ai][bj][m][1] * rstd[ai][m] + b1;
;                     if (ACT == 1) {
; #pragma unroll
;                         for (int e = 0; e < 4; ++e) { float a = fmaxf(v0[e], 0.f), b = fmaxf(v1[e], 0.f); v0[e] = a * a; v1[e] = b * b; } }
;                     u32x4 w; w.x = cvtpk(v0[0], v0[1]); w.y = cvtpk(v0[2], v0[3]); w.z = cvtpk(v1[0], v1[1]); w.w = cvtpk(v1[2], v1[3]);
;                     *(u32x4*)(Ou + (wr * 64 + fr + ai * 128 + m * 16) * ldc + wc * 32 + 8 * fq + bj * 128) = w; } }
	v_cvt_pk_bf16_f32 v41, v46, v47
	v_cvt_pk_bf16_f32 v42, v48, v49
	v_cvt_pk_bf16_f32 v43, v50, v51
	v_lshl_add_u64 v[44:45], v[62:63], 0, v[172:173]
	v_pk_fma_f32 v[38:39], v[38:39], v[186:187], v[134:135] op_sel_hi:[1,0,1]
	v_pk_fma_f32 v[36:37], v[36:37], v[186:187], v[132:133] op_sel_hi:[1,0,1]
	v_pk_fma_f32 v[34:35], v[34:35], v[186:187], v[130:131] op_sel_hi:[1,0,1]
	v_max_f32_e32 v32, 0, v32
	v_max_f32_e32 v33, 0, v33
	global_store_dwordx4 v[44:45], v[40:43], off
	v_max_f32_e32 v36, 0, v36
	v_max_f32_e32 v37, 0, v37
	v_pk_mul_f32 v[40:41], v[32:33], v[32:33]
	v_max_f32_e32 v32, 0, v38
	v_max_f32_e32 v34, 0, v34
	v_max_f32_e32 v33, 0, v39
	v_max_f32_e32 v35, 0, v35
	v_pk_mul_f32 v[36:37], v[36:37], v[36:37]
	v_pk_mul_f32 v[38:39], v[32:33], v[32:33]
	v_pk_mul_f32 v[42:43], v[34:35], v[34:35]
	v_pk_fma_f32 v[24:25], v[24:25], v[184:185], v[128:129] op_sel_hi:[1,0,1]
	v_cvt_pk_bf16_f32 v32, v36, v37
	v_cvt_pk_bf16_f32 v33, v38, v39
	v_cvt_pk_bf16_f32 v34, v40, v41
	v_cvt_pk_bf16_f32 v35, v42, v43
	v_lshl_add_u64 v[36:37], v[62:63], 0, v[174:175]
	v_pk_fma_f32 v[30:31], v[30:31], v[184:185], v[134:135] op_sel_hi:[1,0,1]
	v_pk_fma_f32 v[28:29], v[28:29], v[184:185], v[132:133] op_sel_hi:[1,0,1]
	v_pk_fma_f32 v[26:27], v[26:27], v[184:185], v[130:131] op_sel_hi:[1,0,1]
	v_max_f32_e32 v24, 0, v24
	v_max_f32_e32 v25, 0, v25
	global_store_dwordx4 v[36:37], v[32:35], off
	v_max_f32_e32 v28, 0, v28
	v_max_f32_e32 v29, 0, v29
	v_pk_mul_f32 v[32:33], v[24:25], v[24:25]
	v_max_f32_e32 v24, 0, v30
	v_max_f32_e32 v26, 0, v26
	v_max_f32_e32 v25, 0, v31
	v_max_f32_e32 v27, 0, v27
	v_pk_mul_f32 v[28:29], v[28:29], v[28:29]
	v_pk_mul_f32 v[30:31], v[24:25], v[24:25]
	v_pk_mul_f32 v[34:35], v[26:27], v[26:27]
	v_pk_fma_f32 v[16:17], v[16:17], v[182:183], v[128:129] op_sel_hi:[1,0,1]
	v_cvt_pk_bf16_f32 v24, v28, v29
	v_cvt_pk_bf16_f32 v25, v30, v31
	v_cvt_pk_bf16_f32 v26, v32, v33
	v_cvt_pk_bf16_f32 v27, v34, v35
	v_pk_fma_f32 v[22:23], v[22:23], v[182:183], v[134:135] op_sel_hi:[1,0,1]
	v_pk_fma_f32 v[20:21], v[20:21], v[182:183], v[132:133] op_sel_hi:[1,0,1]
	v_pk_fma_f32 v[18:19], v[18:19], v[182:183], v[130:131] op_sel_hi:[1,0,1]
	v_max_f32_e32 v16, 0, v16
	v_max_f32_e32 v17, 0, v17
	global_store_dwordx4 v[88:89], v[24:27], off offset:256
	v_max_f32_e32 v20, 0, v20
	v_max_f32_e32 v21, 0, v21
	v_pk_mul_f32 v[24:25], v[16:17], v[16:17]
	v_max_f32_e32 v16, 0, v22
	v_max_f32_e32 v18, 0, v18
	v_max_f32_e32 v17, 0, v23
	v_max_f32_e32 v19, 0, v19
	v_pk_mul_f32 v[20:21], v[20:21], v[20:21]
	v_pk_mul_f32 v[22:23], v[16:17], v[16:17]
	v_pk_mul_f32 v[26:27], v[18:19], v[18:19]
	v_pk_fma_f32 v[8:9], v[8:9], v[180:181], v[128:129] op_sel_hi:[1,0,1]
	v_cvt_pk_bf16_f32 v16, v20, v21
	v_cvt_pk_bf16_f32 v17, v22, v23
	v_cvt_pk_bf16_f32 v18, v24, v25
	v_cvt_pk_bf16_f32 v19, v26, v27
	v_pk_fma_f32 v[14:15], v[14:15], v[180:181], v[134:135] op_sel_hi:[1,0,1]
	v_pk_fma_f32 v[12:13], v[12:13], v[180:181], v[132:133] op_sel_hi:[1,0,1]
	v_pk_fma_f32 v[10:11], v[10:11], v[180:181], v[130:131] op_sel_hi:[1,0,1]
	v_max_f32_e32 v8, 0, v8
	v_max_f32_e32 v9, 0, v9
	global_store_dwordx4 v[80:81], v[16:19], off offset:256
	v_max_f32_e32 v12, 0, v12
	v_max_f32_e32 v13, 0, v13
	v_pk_mul_f32 v[16:17], v[8:9], v[8:9]
	v_max_f32_e32 v8, 0, v14
	v_max_f32_e32 v10, 0, v10
	v_max_f32_e32 v9, 0, v15
	v_max_f32_e32 v11, 0, v11
	v_pk_mul_f32 v[12:13], v[12:13], v[12:13]
	v_pk_mul_f32 v[14:15], v[8:9], v[8:9]
	v_pk_mul_f32 v[18:19], v[10:11], v[10:11]
	v_pk_fma_f32 v[0:1], v[0:1], v[178:179], v[128:129] op_sel_hi:[1,0,1]
	v_cvt_pk_bf16_f32 v8, v12, v13
	v_cvt_pk_bf16_f32 v9, v14, v15
	v_cvt_pk_bf16_f32 v10, v16, v17
	v_cvt_pk_bf16_f32 v11, v18, v19
	v_pk_fma_f32 v[6:7], v[6:7], v[178:179], v[134:135] op_sel_hi:[1,0,1]
	v_pk_fma_f32 v[4:5], v[4:5], v[178:179], v[132:133] op_sel_hi:[1,0,1]
	v_pk_fma_f32 v[2:3], v[2:3], v[178:179], v[130:131] op_sel_hi:[1,0,1]
	v_max_f32_e32 v0, 0, v0
	v_max_f32_e32 v1, 0, v1
	global_store_dwordx4 v[72:73], v[8:11], off offset:256
	v_max_f32_e32 v4, 0, v4
	v_max_f32_e32 v5, 0, v5
	v_pk_mul_f32 v[8:9], v[0:1], v[0:1]
	v_max_f32_e32 v0, 0, v6
	v_max_f32_e32 v2, 0, v2
	v_max_f32_e32 v1, 0, v7
	v_max_f32_e32 v3, 0, v3
	v_pk_mul_f32 v[4:5], v[4:5], v[4:5]
	v_pk_mul_f32 v[6:7], v[0:1], v[0:1]
	v_pk_mul_f32 v[10:11], v[2:3], v[2:3]
	v_cvt_pk_bf16_f32 v0, v4, v5
	v_cvt_pk_bf16_f32 v1, v6, v7
	v_cvt_pk_bf16_f32 v2, v8, v9
	v_cvt_pk_bf16_f32 v3, v10, v11
	s_mov_b64 s[4:5], -1
	global_store_dwordx4 v[56:57], v[0:3], off offset:256
	s_cbranch_vccnz .LBB0_1090
	s_andn2_b64 vcc, exec, s[12:13]
	s_cbranch_vccnz .LBB0_1089
	s_barrier
	s_branch .LBB0_1089

;     DI void operator()(const f32x4 (&acc)[2][2][4][2], const pg8::Unit& u, int wr, int wc, int fr, int fq) const {
;         const int lrow0 = u.pm * 256 + wr * 64 + fr, grow0 = row_base + u.pm * 256, col0 = u.pn * 256 + wc * 32 + 8 * fq;
;         bf16* Ou = O + (size_t)(u.pm * 256) * ldc + u.pn * 256;
;         const int mrow = grow0 < NCTX ? 8 : (grow0 - NCTX) >> 12;
;         float rstd[2][4];
; #pragma unroll
;         for (int ai = 0; ai < 2; ++ai)
; #pragma unroll
;             for (int m = 0; m < 4; ++m) rstd[ai][m] = rsqrtf(rss[row_base + lrow0 + ai * 128 + m * 16] * (1.f / DM) + EPS);
;         const float* bp = bias + mrow * 4096 + col0;
;         f32x4 bb[2][2];
; #pragma unroll
;         for (int bj = 0; bj < 2; ++bj) { bb[bj][0] = *(const f32x4*)(bp + bj * 128); bb[bj][1] = *(const f32x4*)(bp + bj * 128 + 4); }
;         asm volatile("" ::: "memory");
; #pragma unroll
;         for (int bj = 0; bj < 2; ++bj) { const f32x4 b0 = bb[bj][0], b1 = bb[bj][1];
; #pragma unroll
;             for (int ai = 0; ai < 2; ++ai)
; #pragma unroll
;                 for (int m = 0; m < 4; ++m) {
;                     f32x4 v0 = acc[ai][bj][m][0] * rstd[ai][m] + b0, v1 = acc[ai][bj][m][1] * rstd[ai][m] + b1;
.LBB0_1111:
	s_lshl_b32 s6, s46, 8
	v_add_u32_e32 v128, s6, v183
	v_ashrrev_i32_e32 v129, 31, v128
	v_lshl_add_u64 v[128:129], v[128:129], 2, s[86:87]
	global_load_dword v200, v[128:129], off
	global_load_dword v201, v[128:129], off offset:64
	global_load_dword v202, v[128:129], off offset:128
	global_load_dword v203, v[128:129], off offset:192
	global_load_dword v204, v[128:129], off offset:512
	global_load_dword v205, v[128:129], off offset:576
	global_load_dword v206, v[128:129], off offset:640
	global_load_dword v207, v[128:129], off offset:704
	s_lshl_b32 s4, s31, 8
	s_ashr_i32 s7, s6, 31
	s_ashr_i32 s5, s4, 31
	s_lshl_b64 s[8:9], s[6:7], 13
	s_add_u32 s8, s33, s8
	s_addc_u32 s9, s59, s9
	s_and_b32 s7, s6, 0xfffff000
	s_cmp_lt_u32 s6, 0x7ffff800
	s_cselect_b32 s6, s7, 0x8000
	s_ashr_i32 s7, s6, 31
	s_lshl_b64 s[6:7], s[6:7], 2
	v_readlane_b32 s22, v253, 61
	v_readlane_b32 s23, v253, 62
	s_add_u32 s6, s22, s6
	s_addc_u32 s7, s23, s7
	v_or_b32_e32 v208, s4, v181
	v_ashrrev_i32_e32 v209, 31, v208
	v_lshl_add_u64 v[208:209], v[208:209], 2, s[6:7]
	global_load_dwordx4 v[220:223], v[208:209], off offset:16
	global_load_dwordx4 v[224:227], v[208:209], off
	global_load_dwordx4 v[228:231], v[208:209], off offset:528
	global_load_dwordx4 v[232:235], v[208:209], off offset:512
	s_waitcnt vmcnt(11)
	v_fmamk_f32 v200, v200, 0x3a800000, v187
	v_cmp_gt_f32_e32 vcc, s57, v200
	v_mul_f32_e32 v131, 0x4b800000, v200
	s_nop 0
	v_cndmask_b32_e32 v200, v200, v131, vcc
	v_rsq_f32_e32 v200, v200
	s_nop 0
	v_mul_f32_e32 v131, 0x45800000, v200
	v_cndmask_b32_e32 v192, v200, v131, vcc
	s_waitcnt vmcnt(10)
	v_fmamk_f32 v201, v201, 0x3a800000, v187
	v_cmp_gt_f32_e32 vcc, s57, v201
	v_mul_f32_e32 v131, 0x4b800000, v201
	s_nop 0
	v_cndmask_b32_e32 v201, v201, v131, vcc
	v_rsq_f32_e32 v201, v201
	s_nop 0
	v_mul_f32_e32 v131, 0x45800000, v201
	v_cndmask_b32_e32 v190, v201, v131, vcc
	s_waitcnt vmcnt(9)
	v_fmamk_f32 v202, v202, 0x3a800000, v187
	v_cmp_gt_f32_e32 vcc, s57, v202
	v_mul_f32_e32 v131, 0x4b800000, v202
	s_nop 0
	v_cndmask_b32_e32 v202, v202, v131, vcc
	v_rsq_f32_e32 v202, v202
	s_nop 0
	v_mul_f32_e32 v131, 0x45800000, v202
	v_cndmask_b32_e32 v188, v202, v131, vcc
	s_waitcnt vmcnt(8)
	v_fmamk_f32 v203, v203, 0x3a800000, v187
	v_cmp_gt_f32_e32 vcc, s57, v203
	v_mul_f32_e32 v131, 0x4b800000, v203
	s_nop 0
	v_cndmask_b32_e32 v203, v203, v131, vcc
	v_rsq_f32_e32 v203, v203
	s_nop 0
	v_mul_f32_e32 v131, 0x45800000, v203
	v_cndmask_b32_e32 v186, v203, v131, vcc
	s_waitcnt vmcnt(7)
	v_fmamk_f32 v204, v204, 0x3a800000, v187
	v_cmp_gt_f32_e32 vcc, s57, v204
	v_mul_f32_e32 v131, 0x4b800000, v204
	s_nop 0
	v_cndmask_b32_e32 v204, v204, v131, vcc
	v_rsq_f32_e32 v204, v204
	s_nop 0
	v_mul_f32_e32 v131, 0x45800000, v204
	v_cndmask_b32_e32 v184, v204, v131, vcc
	s_waitcnt vmcnt(6)
	v_fmamk_f32 v205, v205, 0x3a800000, v187
	v_cmp_gt_f32_e32 vcc, s57, v205
	v_mul_f32_e32 v131, 0x4b800000, v205
	s_nop 0
	v_cndmask_b32_e32 v205, v205, v131, vcc
	v_rsq_f32_e32 v205, v205
	s_nop 0
	v_mul_f32_e32 v131, 0x45800000, v205
	v_cndmask_b32_e32 v182, v205, v131, vcc
	s_waitcnt vmcnt(5)
	v_fmamk_f32 v206, v206, 0x3a800000, v187
	v_cmp_gt_f32_e32 vcc, s57, v206
	v_mul_f32_e32 v131, 0x4b800000, v206
	s_waitcnt vmcnt(4)
	v_fmamk_f32 v207, v207, 0x3a800000, v187
	v_cndmask_b32_e32 v206, v206, v131, vcc
	v_rsq_f32_e32 v206, v206
	v_mul_f32_e32 v129, 0x4b800000, v207
	v_mul_f32_e32 v131, 0x45800000, v206
	v_cndmask_b32_e32 v180, v206, v131, vcc
	v_cmp_gt_f32_e32 vcc, s57, v207
	s_nop 1
	v_cndmask_b32_e32 v207, v207, v129, vcc
	v_rsq_f32_e32 v207, v207
	s_nop 0
	v_mul_f32_e32 v129, 0x45800000, v207
	v_cndmask_b32_e32 v178, v207, v129, vcc
	v_or_b32_e32 v128, s4, v181
	v_ashrrev_i32_e32 v129, 31, v128
	v_lshl_add_u64 v[132:133], v[128:129], 2, s[6:7]
	s_waitcnt vmcnt(0)
	v_mov_b32_e32 v136, v220
	v_mov_b32_e32 v137, v221
	v_mov_b32_e32 v138, v222
	v_mov_b32_e32 v139, v223
	v_mov_b32_e32 v140, v224
	v_mov_b32_e32 v141, v225
	v_mov_b32_e32 v142, v226
	v_mov_b32_e32 v143, v227
	v_mov_b32_e32 v128, v228
	v_mov_b32_e32 v129, v229
	v_mov_b32_e32 v130, v230
	v_mov_b32_e32 v131, v231
	v_mov_b32_e32 v132, v232
	v_mov_b32_e32 v133, v233
	v_mov_b32_e32 v134, v234
	v_mov_b32_e32 v135, v235
	s_nop 0
	s_nop 0
	s_nop 0
	s_nop 0
	s_nop 0
	s_nop 0
	s_nop 0
	s_nop 0
	s_nop 0
	s_nop 0
	s_nop 0
	s_nop 0
	s_lshl_b64 s[4:5], s[4:5], 1
	s_add_u32 s4, s8, s4
	s_addc_u32 s5, s9, s5
	s_add_u32 s4, s4, s60
	s_addc_u32 s5, s5, 0
	v_lshl_add_u64 v[194:195], s[4:5], 0, v[152:153]
	s_mov_b64 s[4:5], 0x100
	s_andn2_b64 vcc, exec, s[36:37]
	s_waitcnt vmcnt(3)
	v_pk_fma_f32 v[122:123], v[122:123], v[192:193], v[138:139] op_sel_hi:[1,0,1]
	s_waitcnt vmcnt(2)
; DI unsigned cvtpk(float lo, float hi) { f32x2 v = {lo, hi}; bf16x2_t b = __builtin_convertvector(v, bf16x2_t); return __builtin_bit_cast(unsigned, b); }
;     DI void operator()(const f32x4 (&acc)[2][2][4][2], const pg8::Unit& u, int wr, int wc, int fr, int fq) const {
;     ...
; #pragma unroll
;         for (int bj = 0; bj < 2; ++bj) { const f32x4 b0 = bb[bj][0], b1 = bb[bj][1];
; #pragma unroll
;             for (int ai = 0; ai < 2; ++ai)
; #pragma unroll
;                 for (int m = 0; m < 4; ++m) {
;                     f32x4 v0 = acc[ai][bj][m][0] * rstd[ai][m] + b0, v1 = acc[ai][bj][m][1] * rstd[ai][m] + b1;
;                     if (ACT == 1) {
; #pragma unroll
;                         for (int e = 0; e < 4; ++e) { float a = fmaxf(v0[e], 0.f), b = fmaxf(v1[e], 0.f); v0[e] = a * a; v1[e] = b * b; } }
;                     u32x4 w; w.x = cvtpk(v0[0], v0[1]); w.y = cvtpk(v0[2], v0[3]); w.z = cvtpk(v1[0], v1[1]); w.w = cvtpk(v1[2], v1[3]);
;                     *(u32x4*)(Ou + (wr * 64 + fr + ai * 128 + m * 16) * ldc + wc * 32 + 8 * fq + bj * 128) = w; } }
	v_pk_fma_f32 v[126:127], v[126:127], v[192:193], v[142:143] op_sel_hi:[1,0,1]
	v_pk_fma_f32 v[124:125], v[124:125], v[192:193], v[140:141] op_sel_hi:[1,0,1]
	v_pk_fma_f32 v[120:121], v[120:121], v[192:193], v[136:137] op_sel_hi:[1,0,1]
	v_max_f32_e32 v124, 0, v124
	v_max_f32_e32 v120, 0, v120
	v_max_f32_e32 v125, 0, v125
	v_max_f32_e32 v121, 0, v121
	v_max_f32_e32 v126, 0, v126
	v_max_f32_e32 v122, 0, v122
	v_max_f32_e32 v127, 0, v127
	v_max_f32_e32 v123, 0, v123
	v_pk_mul_f32 v[124:125], v[124:125], v[124:125]
	v_pk_mul_f32 v[120:121], v[120:121], v[120:121]
	v_pk_mul_f32 v[126:127], v[126:127], v[126:127]
	v_pk_mul_f32 v[196:197], v[122:123], v[122:123]
	v_pk_fma_f32 v[112:113], v[112:113], v[190:191], v[136:137] op_sel_hi:[1,0,1]
	v_cvt_pk_bf16_f32 v122, v124, v125
	v_cvt_pk_bf16_f32 v123, v126, v127
	v_cvt_pk_bf16_f32 v124, v120, v121
	v_cvt_pk_bf16_f32 v125, v196, v197
	v_lshl_add_u64 v[120:121], v[154:155], 1, v[194:195]
	v_pk_fma_f32 v[118:119], v[118:119], v[190:191], v[142:143] op_sel_hi:[1,0,1]
	v_pk_fma_f32 v[116:117], v[116:117], v[190:191], v[140:141] op_sel_hi:[1,0,1]
	v_pk_fma_f32 v[114:115], v[114:115], v[190:191], v[138:139] op_sel_hi:[1,0,1]
	v_max_f32_e32 v112, 0, v112
	v_max_f32_e32 v113, 0, v113
	global_store_dwordx4 v[120:121], v[122:125], off
	v_max_f32_e32 v116, 0, v116
	v_max_f32_e32 v117, 0, v117
	v_pk_mul_f32 v[122:123], v[112:113], v[112:113]
	v_max_f32_e32 v112, 0, v118
	v_max_f32_e32 v114, 0, v114
	v_max_f32_e32 v113, 0, v119
	v_max_f32_e32 v115, 0, v115
	v_pk_mul_f32 v[116:117], v[116:117], v[116:117]
	v_pk_mul_f32 v[118:119], v[112:113], v[112:113]
	v_pk_mul_f32 v[124:125], v[114:115], v[114:115]
	v_pk_fma_f32 v[104:105], v[104:105], v[188:189], v[136:137] op_sel_hi:[1,0,1]
	v_cvt_pk_bf16_f32 v112, v116, v117
	v_cvt_pk_bf16_f32 v113, v118, v119
	v_cvt_pk_bf16_f32 v114, v122, v123
	v_cvt_pk_bf16_f32 v115, v124, v125
	v_lshl_add_u64 v[116:117], v[194:195], 0, v[170:171]
	v_pk_fma_f32 v[110:111], v[110:111], v[188:189], v[142:143] op_sel_hi:[1,0,1]
	v_pk_fma_f32 v[108:109], v[108:109], v[188:189], v[140:141] op_sel_hi:[1,0,1]
	v_pk_fma_f32 v[106:107], v[106:107], v[188:189], v[138:139] op_sel_hi:[1,0,1]
	v_max_f32_e32 v104, 0, v104
	v_max_f32_e32 v105, 0, v105
	global_store_dwordx4 v[116:117], v[112:115], off
	v_max_f32_e32 v108, 0, v108
	v_max_f32_e32 v109, 0, v109
	v_pk_mul_f32 v[112:113], v[104:105], v[104:105]
	v_max_f32_e32 v104, 0, v110
	v_max_f32_e32 v106, 0, v106
	v_max_f32_e32 v105, 0, v111
	v_max_f32_e32 v107, 0, v107
	v_pk_mul_f32 v[108:109], v[108:109], v[108:109]
	v_pk_mul_f32 v[110:111], v[104:105], v[104:105]
	v_pk_mul_f32 v[114:115], v[106:107], v[106:107]
	v_pk_fma_f32 v[96:97], v[96:97], v[186:187], v[136:137] op_sel_hi:[1,0,1]
	v_cvt_pk_bf16_f32 v104, v108, v109
	v_cvt_pk_bf16_f32 v105, v110, v111
	v_cvt_pk_bf16_f32 v106, v112, v113
	v_cvt_pk_bf16_f32 v107, v114, v115
	v_lshl_add_u64 v[108:109], v[194:195], 0, v[172:173]
	v_pk_fma_f32 v[102:103], v[102:103], v[186:187], v[142:143] op_sel_hi:[1,0,1]
	v_pk_fma_f32 v[100:101], v[100:101], v[186:187], v[140:141] op_sel_hi:[1,0,1]
	v_pk_fma_f32 v[98:99], v[98:99], v[186:187], v[138:139] op_sel_hi:[1,0,1]
	v_max_f32_e32 v96, 0, v96
	v_max_f32_e32 v97, 0, v97
	global_store_dwordx4 v[108:109], v[104:107], off
	v_max_f32_e32 v100, 0, v100
	v_max_f32_e32 v101, 0, v101
	v_pk_mul_f32 v[104:105], v[96:97], v[96:97]
	v_max_f32_e32 v96, 0, v102
	v_max_f32_e32 v98, 0, v98
	v_max_f32_e32 v97, 0, v103
	v_max_f32_e32 v99, 0, v99
	v_pk_mul_f32 v[100:101], v[100:101], v[100:101]
	v_pk_mul_f32 v[102:103], v[96:97], v[96:97]
	v_pk_mul_f32 v[106:107], v[98:99], v[98:99]
	v_pk_fma_f32 v[94:95], v[94:95], v[184:185], v[142:143] op_sel_hi:[1,0,1]
	v_pk_fma_f32 v[92:93], v[92:93], v[184:185], v[140:141] op_sel_hi:[1,0,1]
	v_pk_fma_f32 v[90:91], v[90:91], v[184:185], v[138:139] op_sel_hi:[1,0,1]
	v_pk_fma_f32 v[88:89], v[88:89], v[184:185], v[136:137] op_sel_hi:[1,0,1]
	v_cvt_pk_bf16_f32 v96, v100, v101
	v_cvt_pk_bf16_f32 v97, v102, v103
	v_cvt_pk_bf16_f32 v98, v104, v105
	v_cvt_pk_bf16_f32 v99, v106, v107
	v_lshl_add_u64 v[100:101], v[194:195], 0, v[174:175]
	v_max_f32_e32 v92, 0, v92
	v_max_f32_e32 v88, 0, v88
	v_max_f32_e32 v93, 0, v93
	v_max_f32_e32 v89, 0, v89
	v_max_f32_e32 v94, 0, v94
	v_max_f32_e32 v90, 0, v90
	v_max_f32_e32 v95, 0, v95
	v_max_f32_e32 v91, 0, v91
	global_store_dwordx4 v[100:101], v[96:99], off
	v_pk_mul_f32 v[92:93], v[92:93], v[92:93]
	v_pk_mul_f32 v[88:89], v[88:89], v[88:89]
	v_pk_mul_f32 v[94:95], v[94:95], v[94:95]
	v_pk_mul_f32 v[96:97], v[90:91], v[90:91]
	v_pk_fma_f32 v[86:87], v[86:87], v[182:183], v[142:143] op_sel_hi:[1,0,1]
	v_pk_fma_f32 v[84:85], v[84:85], v[182:183], v[140:141] op_sel_hi:[1,0,1]
	v_pk_fma_f32 v[82:83], v[82:83], v[182:183], v[138:139] op_sel_hi:[1,0,1]
	v_pk_fma_f32 v[80:81], v[80:81], v[182:183], v[136:137] op_sel_hi:[1,0,1]
	v_cvt_pk_bf16_f32 v90, v92, v93
	v_cvt_pk_bf16_f32 v91, v94, v95
	v_cvt_pk_bf16_f32 v92, v88, v89
	v_cvt_pk_bf16_f32 v93, v96, v97
	v_lshl_add_u64 v[88:89], v[156:157], 1, v[194:195]
	v_max_f32_e32 v84, 0, v84
	v_max_f32_e32 v80, 0, v80
	v_max_f32_e32 v85, 0, v85
	v_max_f32_e32 v81, 0, v81
	v_max_f32_e32 v86, 0, v86
	v_max_f32_e32 v82, 0, v82
	v_max_f32_e32 v87, 0, v87
	v_max_f32_e32 v83, 0, v83
	global_store_dwordx4 v[88:89], v[90:93], off
	v_pk_mul_f32 v[84:85], v[84:85], v[84:85]
	v_pk_mul_f32 v[80:81], v[80:81], v[80:81]
	v_pk_mul_f32 v[86:87], v[86:87], v[86:87]
	v_pk_mul_f32 v[90:91], v[82:83], v[82:83]
	v_pk_fma_f32 v[78:79], v[78:79], v[180:181], v[142:143] op_sel_hi:[1,0,1]
	v_pk_fma_f32 v[76:77], v[76:77], v[180:181], v[140:141] op_sel_hi:[1,0,1]
; DI unsigned cvtpk(float lo, float hi) { f32x2 v = {lo, hi}; bf16x2_t b = __builtin_convertvector(v, bf16x2_t); return __builtin_bit_cast(unsigned, b); }
;     DI void operator()(const f32x4 (&acc)[2][2][4][2], const pg8::Unit& u, int wr, int wc, int fr, int fq) const {
;     ...
; #pragma unroll
;         for (int bj = 0; bj < 2; ++bj) { const f32x4 b0 = bb[bj][0], b1 = bb[bj][1];
; #pragma unroll
;             for (int ai = 0; ai < 2; ++ai)
; #pragma unroll
;                 for (int m = 0; m < 4; ++m) {
;                     f32x4 v0 = acc[ai][bj][m][0] * rstd[ai][m] + b0, v1 = acc[ai][bj][m][1] * rstd[ai][m] + b1;
;                     if (ACT == 1) {
; #pragma unroll
;                         for (int e = 0; e < 4; ++e) { float a = fmaxf(v0[e], 0.f), b = fmaxf(v1[e], 0.f); v0[e] = a * a; v1[e] = b * b; } }
;                     u32x4 w; w.x = cvtpk(v0[0], v0[1]); w.y = cvtpk(v0[2], v0[3]); w.z = cvtpk(v1[0], v1[1]); w.w = cvtpk(v1[2], v1[3]);
;                     *(u32x4*)(Ou + (wr * 64 + fr + ai * 128 + m * 16) * ldc + wc * 32 + 8 * fq + bj * 128) = w; } }
	v_pk_fma_f32 v[74:75], v[74:75], v[180:181], v[138:139] op_sel_hi:[1,0,1]
	v_pk_fma_f32 v[72:73], v[72:73], v[180:181], v[136:137] op_sel_hi:[1,0,1]
	v_cvt_pk_bf16_f32 v82, v84, v85
	v_cvt_pk_bf16_f32 v83, v86, v87
	v_cvt_pk_bf16_f32 v84, v80, v81
	v_cvt_pk_bf16_f32 v85, v90, v91
	v_lshl_add_u64 v[80:81], v[158:159], 1, v[194:195]
	v_max_f32_e32 v76, 0, v76
	v_max_f32_e32 v72, 0, v72
	v_max_f32_e32 v77, 0, v77
	v_max_f32_e32 v73, 0, v73
	v_max_f32_e32 v78, 0, v78
	v_max_f32_e32 v74, 0, v74
	v_max_f32_e32 v79, 0, v79
	v_max_f32_e32 v75, 0, v75
	global_store_dwordx4 v[80:81], v[82:85], off
	v_pk_mul_f32 v[76:77], v[76:77], v[76:77]
	v_pk_mul_f32 v[72:73], v[72:73], v[72:73]
	v_pk_mul_f32 v[78:79], v[78:79], v[78:79]
	v_pk_mul_f32 v[82:83], v[74:75], v[74:75]
	v_pk_fma_f32 v[62:63], v[62:63], v[178:179], v[142:143] op_sel_hi:[1,0,1]
	v_pk_fma_f32 v[60:61], v[60:61], v[178:179], v[140:141] op_sel_hi:[1,0,1]
	v_pk_fma_f32 v[58:59], v[58:59], v[178:179], v[138:139] op_sel_hi:[1,0,1]
	v_pk_fma_f32 v[56:57], v[56:57], v[178:179], v[136:137] op_sel_hi:[1,0,1]
	v_cvt_pk_bf16_f32 v74, v76, v77
	v_cvt_pk_bf16_f32 v75, v78, v79
	v_cvt_pk_bf16_f32 v76, v72, v73
	v_cvt_pk_bf16_f32 v77, v82, v83
	v_lshl_add_u64 v[72:73], v[160:161], 1, v[194:195]
	v_max_f32_e32 v60, 0, v60
	v_max_f32_e32 v56, 0, v56
	v_max_f32_e32 v61, 0, v61
	v_max_f32_e32 v57, 0, v57
	v_max_f32_e32 v62, 0, v62
	v_max_f32_e32 v58, 0, v58
	v_max_f32_e32 v63, 0, v63
	v_max_f32_e32 v59, 0, v59
	global_store_dwordx4 v[72:73], v[74:77], off
	v_pk_mul_f32 v[60:61], v[60:61], v[60:61]
	v_pk_mul_f32 v[56:57], v[56:57], v[56:57]
	v_pk_mul_f32 v[62:63], v[62:63], v[62:63]
	v_pk_mul_f32 v[74:75], v[58:59], v[58:59]
	v_cvt_pk_bf16_f32 v58, v60, v61
	v_cvt_pk_bf16_f32 v59, v62, v63
	v_cvt_pk_bf16_f32 v60, v56, v57
	v_cvt_pk_bf16_f32 v61, v74, v75
	v_lshl_add_u64 v[56:57], v[162:163], 1, v[194:195]
	global_store_dwordx4 v[56:57], v[58:61], off
	s_waitcnt vmcnt(9)
	v_pk_fma_f32 v[66:67], v[66:67], v[192:193], v[130:131] op_sel_hi:[1,0,1]
	v_pk_fma_f32 v[64:65], v[64:65], v[192:193], v[128:129] op_sel_hi:[1,0,1]
	s_waitcnt vmcnt(8)
	v_pk_fma_f32 v[58:59], v[70:71], v[192:193], v[134:135] op_sel_hi:[1,0,1]
	v_pk_fma_f32 v[60:61], v[68:69], v[192:193], v[132:133] op_sel_hi:[1,0,1]
	v_max_f32_e32 v64, 0, v64
	v_max_f32_e32 v60, 0, v60
	v_max_f32_e32 v61, 0, v61
	v_max_f32_e32 v65, 0, v65
	v_max_f32_e32 v58, 0, v58
	v_max_f32_e32 v66, 0, v66
	v_max_f32_e32 v59, 0, v59
	v_max_f32_e32 v67, 0, v67
	v_pk_mul_f32 v[60:61], v[60:61], v[60:61]
	v_pk_mul_f32 v[64:65], v[64:65], v[64:65]
	v_pk_mul_f32 v[68:69], v[58:59], v[58:59]
	v_pk_mul_f32 v[66:67], v[66:67], v[66:67]
	v_pk_fma_f32 v[48:49], v[48:49], v[190:191], v[128:129] op_sel_hi:[1,0,1]
	v_cvt_pk_bf16_f32 v58, v60, v61
	v_cvt_pk_bf16_f32 v59, v68, v69
	v_cvt_pk_bf16_f32 v60, v64, v65
	v_cvt_pk_bf16_f32 v61, v66, v67
	v_pk_fma_f32 v[54:55], v[54:55], v[190:191], v[134:135] op_sel_hi:[1,0,1]
	v_pk_fma_f32 v[52:53], v[52:53], v[190:191], v[132:133] op_sel_hi:[1,0,1]
	v_pk_fma_f32 v[50:51], v[50:51], v[190:191], v[130:131] op_sel_hi:[1,0,1]
	v_max_f32_e32 v48, 0, v48
	v_max_f32_e32 v49, 0, v49
	global_store_dwordx4 v[120:121], v[58:61], off offset:256
	v_max_f32_e32 v52, 0, v52
	v_max_f32_e32 v53, 0, v53
	v_pk_mul_f32 v[58:59], v[48:49], v[48:49]
	v_max_f32_e32 v48, 0, v54
	v_max_f32_e32 v50, 0, v50
	v_max_f32_e32 v49, 0, v55
	v_max_f32_e32 v51, 0, v51
	v_lshl_add_u64 v[62:63], v[194:195], 0, s[4:5]
	v_pk_mul_f32 v[52:53], v[52:53], v[52:53]
	v_pk_mul_f32 v[54:55], v[48:49], v[48:49]
	v_pk_mul_f32 v[60:61], v[50:51], v[50:51]
	v_pk_fma_f32 v[40:41], v[40:41], v[188:189], v[128:129] op_sel_hi:[1,0,1]
	v_cvt_pk_bf16_f32 v48, v52, v53
	v_cvt_pk_bf16_f32 v49, v54, v55
	v_cvt_pk_bf16_f32 v50, v58, v59
	v_cvt_pk_bf16_f32 v51, v60, v61
	v_lshl_add_u64 v[52:53], v[62:63], 0, v[170:171]
	v_pk_fma_f32 v[46:47], v[46:47], v[188:189], v[134:135] op_sel_hi:[1,0,1]
	v_pk_fma_f32 v[44:45], v[44:45], v[188:189], v[132:133] op_sel_hi:[1,0,1]
	v_pk_fma_f32 v[42:43], v[42:43], v[188:189], v[130:131] op_sel_hi:[1,0,1]
	v_max_f32_e32 v40, 0, v40
	v_max_f32_e32 v41, 0, v41
	global_store_dwordx4 v[52:53], v[48:51], off
	v_max_f32_e32 v44, 0, v44
	v_max_f32_e32 v45, 0, v45
	v_pk_mul_f32 v[48:49], v[40:41], v[40:41]
	v_max_f32_e32 v40, 0, v46
	v_max_f32_e32 v42, 0, v42
	v_max_f32_e32 v41, 0, v47
	v_max_f32_e32 v43, 0, v43
	v_pk_mul_f32 v[44:45], v[44:45], v[44:45]
	v_pk_mul_f32 v[46:47], v[40:41], v[40:41]
	v_pk_mul_f32 v[50:51], v[42:43], v[42:43]
	v_pk_fma_f32 v[32:33], v[32:33], v[186:187], v[128:129] op_sel_hi:[1,0,1]
	v_cvt_pk_bf16_f32 v40, v44, v45
; #define PG8_BAR __builtin_amdgcn_s_barrier()
; DI unsigned cvtpk(float lo, float hi) { f32x2 v = {lo, hi}; bf16x2_t b = __builtin_convertvector(v, bf16x2_t); return __builtin_bit_cast(unsigned, b); }
; template <class Epi, class Sched, bool ALIGN_EPI = false, bool SP2 = false>
; __device__ __forceinline__ void gemm_phase(PG8_LAS unsigned char* lds, const Gemm g, const Sched& S, const Epi& E, const int tid_in) {
;     ...
;         if (!has_next) break;
; #pragma unroll
;         for (int a = 0; a < 2; ++a)
; #pragma unroll
;             for (int b = 0; b < 2; ++b)
; #pragma unroll
;                 for (int m = 0; m < 4; ++m)
; #pragma unroll
;                     for (int n = 0; n < 2; ++n) acc[a][b][m][n] = (f32x4){0.f, 0.f, 0.f, 0.f};
;         cur = nxt; cA = nA; cB = nB; ++ui;
;         if constexpr (ALIGN_EPI) { if (wr == 1) PG8_BAR; }
;     DI void operator()(const f32x4 (&acc)[2][2][4][2], const pg8::Unit& u, int wr, int wc, int fr, int fq) const {
;     ...
; #pragma unroll
;         for (int bj = 0; bj < 2; ++bj) { const f32x4 b0 = bb[bj][0], b1 = bb[bj][1];
; #pragma unroll
;             for (int ai = 0; ai < 2; ++ai)
; #pragma unroll
;                 for (int m = 0; m < 4; ++m) {
;                     f32x4 v0 = acc[ai][bj][m][0] * rstd[ai][m] + b0, v1 = acc[ai][bj][m][1] * rstd[ai][m] + b1;
;                     if (ACT == 1) {
; #pragma unroll
;                         for (int e = 0; e < 4; ++e) { float a = fmaxf(v0[e], 0.f), b = fmaxf(v1[e], 0.f); v0[e] = a * a; v1[e] = b * b; } }
;                     u32x4 w; w.x = cvtpk(v0[0], v0[1]); w.y = cvtpk(v0[2], v0[3]); w.z = cvtpk(v1[0], v1[1]); w.w = cvtpk(v1[2], v1[3]);
;                     *(u32x4*)(Ou + (wr * 64 + fr + ai * 128 + m * 16) * ldc + wc * 32 + 8 * fq + bj * 128) = w; } }
	v_cvt_pk_bf16_f32 v41, v46, v47
	v_cvt_pk_bf16_f32 v42, v48, v49
	v_cvt_pk_bf16_f32 v43, v50, v51
	v_lshl_add_u64 v[44:45], v[62:63], 0, v[172:173]
	v_pk_fma_f32 v[38:39], v[38:39], v[186:187], v[134:135] op_sel_hi:[1,0,1]
	v_pk_fma_f32 v[36:37], v[36:37], v[186:187], v[132:133] op_sel_hi:[1,0,1]
	v_pk_fma_f32 v[34:35], v[34:35], v[186:187], v[130:131] op_sel_hi:[1,0,1]
	v_max_f32_e32 v32, 0, v32
	v_max_f32_e32 v33, 0, v33
	global_store_dwordx4 v[44:45], v[40:43], off
	v_max_f32_e32 v36, 0, v36
	v_max_f32_e32 v37, 0, v37
	v_pk_mul_f32 v[40:41], v[32:33], v[32:33]
	v_max_f32_e32 v32, 0, v38
	v_max_f32_e32 v34, 0, v34
	v_max_f32_e32 v33, 0, v39
	v_max_f32_e32 v35, 0, v35
	v_pk_mul_f32 v[36:37], v[36:37], v[36:37]
	v_pk_mul_f32 v[38:39], v[32:33], v[32:33]
	v_pk_mul_f32 v[42:43], v[34:35], v[34:35]
	v_pk_fma_f32 v[24:25], v[24:25], v[184:185], v[128:129] op_sel_hi:[1,0,1]
	v_cvt_pk_bf16_f32 v32, v36, v37
	v_cvt_pk_bf16_f32 v33, v38, v39
	v_cvt_pk_bf16_f32 v34, v40, v41
	v_cvt_pk_bf16_f32 v35, v42, v43
	v_lshl_add_u64 v[36:37], v[62:63], 0, v[174:175]
	v_pk_fma_f32 v[30:31], v[30:31], v[184:185], v[134:135] op_sel_hi:[1,0,1]
	v_pk_fma_f32 v[28:29], v[28:29], v[184:185], v[132:133] op_sel_hi:[1,0,1]
	v_pk_fma_f32 v[26:27], v[26:27], v[184:185], v[130:131] op_sel_hi:[1,0,1]
	v_max_f32_e32 v24, 0, v24
	v_max_f32_e32 v25, 0, v25
	global_store_dwordx4 v[36:37], v[32:35], off
	v_max_f32_e32 v28, 0, v28
	v_max_f32_e32 v29, 0, v29
	v_pk_mul_f32 v[32:33], v[24:25], v[24:25]
	v_max_f32_e32 v24, 0, v30
	v_max_f32_e32 v26, 0, v26
	v_max_f32_e32 v25, 0, v31
	v_max_f32_e32 v27, 0, v27
	v_pk_mul_f32 v[28:29], v[28:29], v[28:29]
	v_pk_mul_f32 v[30:31], v[24:25], v[24:25]
	v_pk_mul_f32 v[34:35], v[26:27], v[26:27]
	v_pk_fma_f32 v[16:17], v[16:17], v[182:183], v[128:129] op_sel_hi:[1,0,1]
	v_cvt_pk_bf16_f32 v24, v28, v29
	v_cvt_pk_bf16_f32 v25, v30, v31
	v_cvt_pk_bf16_f32 v26, v32, v33
	v_cvt_pk_bf16_f32 v27, v34, v35
	v_pk_fma_f32 v[22:23], v[22:23], v[182:183], v[134:135] op_sel_hi:[1,0,1]
	v_pk_fma_f32 v[20:21], v[20:21], v[182:183], v[132:133] op_sel_hi:[1,0,1]
	v_pk_fma_f32 v[18:19], v[18:19], v[182:183], v[130:131] op_sel_hi:[1,0,1]
	v_max_f32_e32 v16, 0, v16
	v_max_f32_e32 v17, 0, v17
	global_store_dwordx4 v[88:89], v[24:27], off offset:256
	v_max_f32_e32 v20, 0, v20
	v_max_f32_e32 v21, 0, v21
	v_pk_mul_f32 v[24:25], v[16:17], v[16:17]
	v_max_f32_e32 v16, 0, v22
	v_max_f32_e32 v18, 0, v18
	v_max_f32_e32 v17, 0, v23
	v_max_f32_e32 v19, 0, v19
	v_pk_mul_f32 v[20:21], v[20:21], v[20:21]
	v_pk_mul_f32 v[22:23], v[16:17], v[16:17]
	v_pk_mul_f32 v[26:27], v[18:19], v[18:19]
	v_pk_fma_f32 v[8:9], v[8:9], v[180:181], v[128:129] op_sel_hi:[1,0,1]
	v_cvt_pk_bf16_f32 v16, v20, v21
	v_cvt_pk_bf16_f32 v17, v22, v23
	v_cvt_pk_bf16_f32 v18, v24, v25
	v_cvt_pk_bf16_f32 v19, v26, v27
	v_pk_fma_f32 v[14:15], v[14:15], v[180:181], v[134:135] op_sel_hi:[1,0,1]
	v_pk_fma_f32 v[12:13], v[12:13], v[180:181], v[132:133] op_sel_hi:[1,0,1]
	v_pk_fma_f32 v[10:11], v[10:11], v[180:181], v[130:131] op_sel_hi:[1,0,1]
	v_max_f32_e32 v8, 0, v8
	v_max_f32_e32 v9, 0, v9
	global_store_dwordx4 v[80:81], v[16:19], off offset:256
	v_max_f32_e32 v12, 0, v12
	v_max_f32_e32 v13, 0, v13
	v_pk_mul_f32 v[16:17], v[8:9], v[8:9]
	v_max_f32_e32 v8, 0, v14
	v_max_f32_e32 v10, 0, v10
	v_max_f32_e32 v9, 0, v15
	v_max_f32_e32 v11, 0, v11
	v_pk_mul_f32 v[12:13], v[12:13], v[12:13]
	v_pk_mul_f32 v[14:15], v[8:9], v[8:9]
	v_pk_mul_f32 v[18:19], v[10:11], v[10:11]
	v_pk_fma_f32 v[0:1], v[0:1], v[178:179], v[128:129] op_sel_hi:[1,0,1]
	v_cvt_pk_bf16_f32 v8, v12, v13
	v_cvt_pk_bf16_f32 v9, v14, v15
	v_cvt_pk_bf16_f32 v10, v16, v17
	v_cvt_pk_bf16_f32 v11, v18, v19
	v_pk_fma_f32 v[6:7], v[6:7], v[178:179], v[134:135] op_sel_hi:[1,0,1]
	v_pk_fma_f32 v[4:5], v[4:5], v[178:179], v[132:133] op_sel_hi:[1,0,1]
	v_pk_fma_f32 v[2:3], v[2:3], v[178:179], v[130:131] op_sel_hi:[1,0,1]
	v_max_f32_e32 v0, 0, v0
	v_max_f32_e32 v1, 0, v1
	global_store_dwordx4 v[72:73], v[8:11], off offset:256
	v_max_f32_e32 v4, 0, v4
	v_max_f32_e32 v5, 0, v5
	v_pk_mul_f32 v[8:9], v[0:1], v[0:1]
	v_max_f32_e32 v0, 0, v6
	v_max_f32_e32 v2, 0, v2
	v_max_f32_e32 v1, 0, v7
	v_max_f32_e32 v3, 0, v3
	v_pk_mul_f32 v[4:5], v[4:5], v[4:5]
	v_pk_mul_f32 v[6:7], v[0:1], v[0:1]
	v_pk_mul_f32 v[10:11], v[2:3], v[2:3]
	v_cvt_pk_bf16_f32 v0, v4, v5
	v_cvt_pk_bf16_f32 v1, v6, v7
	v_cvt_pk_bf16_f32 v2, v8, v9
	v_cvt_pk_bf16_f32 v3, v10, v11
	s_mov_b64 s[4:5], -1
	global_store_dwordx4 v[56:57], v[0:3], off offset:256
	s_cbranch_vccnz .LBB0_1104
	s_andn2_b64 vcc, exec, s[10:11]
	s_cbranch_vccnz .LBB0_1103
	s_barrier
	s_branch .LBB0_1103

;     DI void operator()(const f32x4 (&acc)[2][2][4][2], const pg8::Unit& u, int wr, int wc, int fr, int fq) const {
;         const int lrow0 = u.pm * 256 + wr * 64 + fr, grow0 = row_base + u.pm * 256, col0 = u.pn * 256 + wc * 32 + 8 * fq;
;         bf16* Ou = O + (size_t)(u.pm * 256) * ldc + u.pn * 256;
;         const int mrow = grow0 < NCTX ? 8 : (grow0 - NCTX) >> 12;
;         float rstd[2][4];
; #pragma unroll
;         for (int ai = 0; ai < 2; ++ai)
; #pragma unroll
;             for (int m = 0; m < 4; ++m) rstd[ai][m] = rsqrtf(rss[row_base + lrow0 + ai * 128 + m * 16] * (1.f / DM) + EPS);
;         const float* bp = bias + mrow * 4096 + col0;
;         f32x4 bb[2][2];
; #pragma unroll
;         for (int bj = 0; bj < 2; ++bj) { bb[bj][0] = *(const f32x4*)(bp + bj * 128); bb[bj][1] = *(const f32x4*)(bp + bj * 128 + 4); }
;         asm volatile("" ::: "memory");
; #pragma unroll
;         for (int bj = 0; bj < 2; ++bj) { const f32x4 b0 = bb[bj][0], b1 = bb[bj][1];
; #pragma unroll
;             for (int ai = 0; ai < 2; ++ai)
; #pragma unroll
;                 for (int m = 0; m < 4; ++m) {
;                     f32x4 v0 = acc[ai][bj][m][0] * rstd[ai][m] + b0, v1 = acc[ai][bj][m][1] * rstd[ai][m] + b1;
.LBB0_1278:
	s_lshl_b32 s6, s63, 8
	v_add_u32_e32 v128, s6, v185
	v_ashrrev_i32_e32 v129, 31, v128
	v_lshl_add_u64 v[128:129], v[128:129], 2, s[60:61]
	global_load_dword v200, v[128:129], off
	global_load_dword v201, v[128:129], off offset:64
	global_load_dword v202, v[128:129], off offset:128
	global_load_dword v203, v[128:129], off offset:192
	global_load_dword v204, v[128:129], off offset:512
	global_load_dword v205, v[128:129], off offset:576
	global_load_dword v206, v[128:129], off offset:640
	global_load_dword v207, v[128:129], off offset:704
	s_lshl_b32 s4, s31, 8
	s_ashr_i32 s5, s4, 31
	s_mul_i32 s7, s63, 0xc0000
	s_mul_hi_i32 s8, s6, 0xc00
	s_add_u32 s9, s46, s7
	s_addc_u32 s8, s47, s8
	s_and_b32 s7, s6, 0xfffff000
	s_cmp_lt_u32 s6, 0x7ffff800
	s_cselect_b32 s6, s7, 0x8000
	s_ashr_i32 s7, s6, 31
	s_lshl_b64 s[6:7], s[6:7], 2
	s_add_u32 s6, s48, s6
	s_addc_u32 s7, s49, s7
	v_readlane_b32 s66, v254, 12
	v_or_b32_e32 v208, s4, v183
	v_ashrrev_i32_e32 v209, 31, v208
	v_lshl_add_u64 v[208:209], v[208:209], 2, s[6:7]
	global_load_dwordx4 v[220:223], v[208:209], off offset:16
	global_load_dwordx4 v[224:227], v[208:209], off
	global_load_dwordx4 v[228:231], v[208:209], off offset:528
	global_load_dwordx4 v[232:235], v[208:209], off offset:512
	s_waitcnt vmcnt(11)
	v_fmamk_f32 v200, v200, 0x3a800000, v189
	v_cmp_gt_f32_e32 vcc, s59, v200
	v_mul_f32_e32 v131, 0x4b800000, v200
	s_nop 0
	v_cndmask_b32_e32 v200, v200, v131, vcc
	v_rsq_f32_e32 v200, v200
	s_nop 0
	v_mul_f32_e32 v131, 0x45800000, v200
	v_cndmask_b32_e32 v178, v200, v131, vcc
	s_waitcnt vmcnt(10)
	v_fmamk_f32 v201, v201, 0x3a800000, v189
	v_cmp_gt_f32_e32 vcc, s59, v201
	v_mul_f32_e32 v131, 0x4b800000, v201
	s_nop 0
	v_cndmask_b32_e32 v201, v201, v131, vcc
	v_rsq_f32_e32 v201, v201
	s_nop 0
	v_mul_f32_e32 v131, 0x45800000, v201
	v_cndmask_b32_e32 v180, v201, v131, vcc
	s_waitcnt vmcnt(9)
	v_fmamk_f32 v202, v202, 0x3a800000, v189
	v_cmp_gt_f32_e32 vcc, s59, v202
	v_mul_f32_e32 v131, 0x4b800000, v202
	s_nop 0
	v_cndmask_b32_e32 v202, v202, v131, vcc
	v_rsq_f32_e32 v202, v202
	s_nop 0
	v_mul_f32_e32 v131, 0x45800000, v202
	v_cndmask_b32_e32 v182, v202, v131, vcc
	s_waitcnt vmcnt(8)
	v_fmamk_f32 v203, v203, 0x3a800000, v189
	v_cmp_gt_f32_e32 vcc, s59, v203
	v_mul_f32_e32 v131, 0x4b800000, v203
	s_nop 0
	v_cndmask_b32_e32 v203, v203, v131, vcc
	v_rsq_f32_e32 v203, v203
	s_nop 0
	v_mul_f32_e32 v131, 0x45800000, v203
	v_cndmask_b32_e32 v184, v203, v131, vcc
	s_waitcnt vmcnt(7)
	v_fmamk_f32 v204, v204, 0x3a800000, v189
	v_cmp_gt_f32_e32 vcc, s59, v204
	v_mul_f32_e32 v131, 0x4b800000, v204
	s_nop 0
	v_cndmask_b32_e32 v204, v204, v131, vcc
	v_rsq_f32_e32 v204, v204
	s_nop 0
	v_mul_f32_e32 v131, 0x45800000, v204
	v_cndmask_b32_e32 v186, v204, v131, vcc
	s_waitcnt vmcnt(6)
	v_fmamk_f32 v205, v205, 0x3a800000, v189
	v_cmp_gt_f32_e32 vcc, s59, v205
	v_mul_f32_e32 v131, 0x4b800000, v205
	s_nop 0
	v_cndmask_b32_e32 v205, v205, v131, vcc
	v_rsq_f32_e32 v205, v205
	s_nop 0
	v_mul_f32_e32 v131, 0x45800000, v205
	v_cndmask_b32_e32 v188, v205, v131, vcc
	s_waitcnt vmcnt(5)
	v_fmamk_f32 v206, v206, 0x3a800000, v189
	v_cmp_gt_f32_e32 vcc, s59, v206
	v_mul_f32_e32 v131, 0x4b800000, v206
	s_waitcnt vmcnt(4)
	v_fmamk_f32 v207, v207, 0x3a800000, v189
	v_cndmask_b32_e32 v206, v206, v131, vcc
	v_rsq_f32_e32 v206, v206
	v_mul_f32_e32 v129, 0x4b800000, v207
	v_mul_f32_e32 v131, 0x45800000, v206
	v_cndmask_b32_e32 v190, v206, v131, vcc
	v_cmp_gt_f32_e32 vcc, s59, v207
	s_nop 1
	v_cndmask_b32_e32 v207, v207, v129, vcc
	v_rsq_f32_e32 v207, v207
	s_nop 0
	v_mul_f32_e32 v129, 0x45800000, v207
	v_cndmask_b32_e32 v192, v207, v129, vcc
	v_or_b32_e32 v128, s4, v183
	v_ashrrev_i32_e32 v129, 31, v128
	v_lshl_add_u64 v[132:133], v[128:129], 2, s[6:7]
	s_waitcnt vmcnt(0)
	v_mov_b32_e32 v136, v220
	v_mov_b32_e32 v137, v221
	v_mov_b32_e32 v138, v222
	v_mov_b32_e32 v139, v223
	v_mov_b32_e32 v140, v224
	v_mov_b32_e32 v141, v225
	v_mov_b32_e32 v142, v226
	v_mov_b32_e32 v143, v227
	v_mov_b32_e32 v128, v228
	v_mov_b32_e32 v129, v229
	v_mov_b32_e32 v130, v230
	v_mov_b32_e32 v131, v231
	v_mov_b32_e32 v132, v232
	v_mov_b32_e32 v133, v233
	v_mov_b32_e32 v134, v234
	v_mov_b32_e32 v135, v235
	s_nop 0
	s_nop 0
	s_nop 0
	s_nop 0
	s_nop 0
	s_nop 0
	s_nop 0
	s_nop 0
	s_nop 0
	s_nop 0
	s_nop 0
	s_nop 0
	s_lshl_b64 s[4:5], s[4:5], 1
	s_add_u32 s4, s9, s4
	s_addc_u32 s5, s8, s5
	s_add_u32 s4, s4, s62
	s_addc_u32 s5, s5, 0
	v_lshl_add_u64 v[194:195], s[4:5], 0, v[152:153]
	s_mov_b64 s[4:5], -1
	s_andn2_b64 vcc, exec, s[36:37]
	s_waitcnt vmcnt(3)
	v_pk_fma_f32 v[196:197], v[122:123], v[178:179], v[138:139] op_sel_hi:[1,0,1]
	s_waitcnt vmcnt(2)
; DI unsigned cvtpk(float lo, float hi) { f32x2 v = {lo, hi}; bf16x2_t b = __builtin_convertvector(v, bf16x2_t); return __builtin_bit_cast(unsigned, b); }
;     DI void operator()(const f32x4 (&acc)[2][2][4][2], const pg8::Unit& u, int wr, int wc, int fr, int fq) const {
;     ...
; #pragma unroll
;         for (int bj = 0; bj < 2; ++bj) { const f32x4 b0 = bb[bj][0], b1 = bb[bj][1];
; #pragma unroll
;             for (int ai = 0; ai < 2; ++ai)
; #pragma unroll
;                 for (int m = 0; m < 4; ++m) {
;                     f32x4 v0 = acc[ai][bj][m][0] * rstd[ai][m] + b0, v1 = acc[ai][bj][m][1] * rstd[ai][m] + b1;
;                     if (ACT == 1) {
; #pragma unroll
;                         for (int e = 0; e < 4; ++e) { float a = fmaxf(v0[e], 0.f), b = fmaxf(v1[e], 0.f); v0[e] = a * a; v1[e] = b * b; } }
;                     u32x4 w; w.x = cvtpk(v0[0], v0[1]); w.y = cvtpk(v0[2], v0[3]); w.z = cvtpk(v1[0], v1[1]); w.w = cvtpk(v1[2], v1[3]);
;                     *(u32x4*)(Ou + (wr * 64 + fr + ai * 128 + m * 16) * ldc + wc * 32 + 8 * fq + bj * 128) = w; } }
	v_pk_fma_f32 v[126:127], v[126:127], v[178:179], v[142:143] op_sel_hi:[1,0,1]
	v_pk_fma_f32 v[124:125], v[124:125], v[178:179], v[140:141] op_sel_hi:[1,0,1]
	v_pk_fma_f32 v[122:123], v[120:121], v[178:179], v[136:137] op_sel_hi:[1,0,1]
	v_cvt_pk_bf16_f32 v120, v124, v125
	v_cvt_pk_bf16_f32 v121, v126, v127
	v_cvt_pk_bf16_f32 v122, v122, v123
	v_cvt_pk_bf16_f32 v123, v196, v197
	v_lshl_add_u64 v[124:125], v[154:155], 1, v[194:195]
	global_store_dwordx4 v[124:125], v[120:123], off
	v_pk_fma_f32 v[118:119], v[118:119], v[180:181], v[142:143] op_sel_hi:[1,0,1]
	v_pk_fma_f32 v[116:117], v[116:117], v[180:181], v[140:141] op_sel_hi:[1,0,1]
	v_pk_fma_f32 v[120:121], v[114:115], v[180:181], v[138:139] op_sel_hi:[1,0,1]
	v_pk_fma_f32 v[114:115], v[112:113], v[180:181], v[136:137] op_sel_hi:[1,0,1]
	v_cvt_pk_bf16_f32 v112, v116, v117
	v_cvt_pk_bf16_f32 v113, v118, v119
	v_cvt_pk_bf16_f32 v114, v114, v115
	v_cvt_pk_bf16_f32 v115, v120, v121
	v_lshl_add_u64 v[116:117], v[156:157], 1, v[194:195]
	global_store_dwordx4 v[116:117], v[112:115], off
	v_pk_fma_f32 v[110:111], v[110:111], v[182:183], v[142:143] op_sel_hi:[1,0,1]
	v_pk_fma_f32 v[108:109], v[108:109], v[182:183], v[140:141] op_sel_hi:[1,0,1]
	v_pk_fma_f32 v[112:113], v[106:107], v[182:183], v[138:139] op_sel_hi:[1,0,1]
	v_pk_fma_f32 v[106:107], v[104:105], v[182:183], v[136:137] op_sel_hi:[1,0,1]
	v_cvt_pk_bf16_f32 v104, v108, v109
	v_cvt_pk_bf16_f32 v105, v110, v111
	v_cvt_pk_bf16_f32 v106, v106, v107
	v_cvt_pk_bf16_f32 v107, v112, v113
	v_lshl_add_u64 v[108:109], v[158:159], 1, v[194:195]
	global_store_dwordx4 v[108:109], v[104:107], off
	v_pk_fma_f32 v[102:103], v[102:103], v[184:185], v[142:143] op_sel_hi:[1,0,1]
	v_pk_fma_f32 v[100:101], v[100:101], v[184:185], v[140:141] op_sel_hi:[1,0,1]
	v_pk_fma_f32 v[104:105], v[98:99], v[184:185], v[138:139] op_sel_hi:[1,0,1]
	v_pk_fma_f32 v[98:99], v[96:97], v[184:185], v[136:137] op_sel_hi:[1,0,1]
	v_cvt_pk_bf16_f32 v96, v100, v101
	v_cvt_pk_bf16_f32 v97, v102, v103
	v_cvt_pk_bf16_f32 v98, v98, v99
	v_cvt_pk_bf16_f32 v99, v104, v105
	v_lshl_add_u64 v[100:101], v[160:161], 1, v[194:195]
	global_store_dwordx4 v[100:101], v[96:99], off
	v_pk_fma_f32 v[94:95], v[94:95], v[186:187], v[142:143] op_sel_hi:[1,0,1]
	v_pk_fma_f32 v[92:93], v[92:93], v[186:187], v[140:141] op_sel_hi:[1,0,1]
	v_pk_fma_f32 v[96:97], v[90:91], v[186:187], v[138:139] op_sel_hi:[1,0,1]
	v_pk_fma_f32 v[90:91], v[88:89], v[186:187], v[136:137] op_sel_hi:[1,0,1]
	v_cvt_pk_bf16_f32 v88, v92, v93
	v_cvt_pk_bf16_f32 v89, v94, v95
	v_cvt_pk_bf16_f32 v90, v90, v91
	v_cvt_pk_bf16_f32 v91, v96, v97
	v_lshl_add_u64 v[92:93], v[162:163], 1, v[194:195]
	global_store_dwordx4 v[92:93], v[88:91], off
	v_pk_fma_f32 v[86:87], v[86:87], v[188:189], v[142:143] op_sel_hi:[1,0,1]
	v_pk_fma_f32 v[84:85], v[84:85], v[188:189], v[140:141] op_sel_hi:[1,0,1]
	v_pk_fma_f32 v[88:89], v[82:83], v[188:189], v[138:139] op_sel_hi:[1,0,1]
	v_pk_fma_f32 v[82:83], v[80:81], v[188:189], v[136:137] op_sel_hi:[1,0,1]
	v_cvt_pk_bf16_f32 v80, v84, v85
	v_cvt_pk_bf16_f32 v81, v86, v87
	v_cvt_pk_bf16_f32 v82, v82, v83
	v_cvt_pk_bf16_f32 v83, v88, v89
	v_lshl_add_u64 v[84:85], v[164:165], 1, v[194:195]
	global_store_dwordx4 v[84:85], v[80:83], off
	v_pk_fma_f32 v[74:75], v[74:75], v[190:191], v[142:143] op_sel_hi:[1,0,1]
	v_pk_fma_f32 v[72:73], v[72:73], v[190:191], v[140:141] op_sel_hi:[1,0,1]
	v_pk_fma_f32 v[80:81], v[66:67], v[190:191], v[138:139] op_sel_hi:[1,0,1]
	v_pk_fma_f32 v[66:67], v[64:65], v[190:191], v[136:137] op_sel_hi:[1,0,1]
	v_cvt_pk_bf16_f32 v64, v72, v73
	v_cvt_pk_bf16_f32 v65, v74, v75
	v_cvt_pk_bf16_f32 v66, v66, v67
	v_cvt_pk_bf16_f32 v67, v80, v81
	v_lshl_add_u64 v[72:73], v[166:167], 1, v[194:195]
	global_store_dwordx4 v[72:73], v[64:67], off
	v_pk_fma_f32 v[54:55], v[54:55], v[192:193], v[142:143] op_sel_hi:[1,0,1]
	v_pk_fma_f32 v[52:53], v[52:53], v[192:193], v[140:141] op_sel_hi:[1,0,1]
	v_pk_fma_f32 v[64:65], v[50:51], v[192:193], v[138:139] op_sel_hi:[1,0,1]
	v_pk_fma_f32 v[50:51], v[48:49], v[192:193], v[136:137] op_sel_hi:[1,0,1]
	v_cvt_pk_bf16_f32 v48, v52, v53
	v_cvt_pk_bf16_f32 v49, v54, v55
	v_cvt_pk_bf16_f32 v50, v50, v51
	v_cvt_pk_bf16_f32 v51, v64, v65
	v_lshl_add_u64 v[52:53], v[168:169], 1, v[194:195]
	global_store_dwordx4 v[52:53], v[48:51], off
	s_waitcnt vmcnt(9)
; #define PG8_BAR __builtin_amdgcn_s_barrier()
; DI unsigned cvtpk(float lo, float hi) { f32x2 v = {lo, hi}; bf16x2_t b = __builtin_convertvector(v, bf16x2_t); return __builtin_bit_cast(unsigned, b); }
; template <class Epi, class Sched, bool ALIGN_EPI = false, bool SP2 = false>
; __device__ __forceinline__ void gemm_phase(PG8_LAS unsigned char* lds, const Gemm g, const Sched& S, const Epi& E, const int tid_in) {
;     ...
;         if (!has_next) break;
; #pragma unroll
;         for (int a = 0; a < 2; ++a)
; #pragma unroll
;             for (int b = 0; b < 2; ++b)
; #pragma unroll
;                 for (int m = 0; m < 4; ++m)
; #pragma unroll
;                     for (int n = 0; n < 2; ++n) acc[a][b][m][n] = (f32x4){0.f, 0.f, 0.f, 0.f};
;         cur = nxt; cA = nA; cB = nB; ++ui;
;         if constexpr (ALIGN_EPI) { if (wr == 1) PG8_BAR; }
;     DI void operator()(const f32x4 (&acc)[2][2][4][2], const pg8::Unit& u, int wr, int wc, int fr, int fq) const {
;     ...
; #pragma unroll
;         for (int bj = 0; bj < 2; ++bj) { const f32x4 b0 = bb[bj][0], b1 = bb[bj][1];
; #pragma unroll
;             for (int ai = 0; ai < 2; ++ai)
; #pragma unroll
;                 for (int m = 0; m < 4; ++m) {
;                     f32x4 v0 = acc[ai][bj][m][0] * rstd[ai][m] + b0, v1 = acc[ai][bj][m][1] * rstd[ai][m] + b1;
;                     if (ACT == 1) {
; #pragma unroll
;                         for (int e = 0; e < 4; ++e) { float a = fmaxf(v0[e], 0.f), b = fmaxf(v1[e], 0.f); v0[e] = a * a; v1[e] = b * b; } }
;                     u32x4 w; w.x = cvtpk(v0[0], v0[1]); w.y = cvtpk(v0[2], v0[3]); w.z = cvtpk(v1[0], v1[1]); w.w = cvtpk(v1[2], v1[3]);
;                     *(u32x4*)(Ou + (wr * 64 + fr + ai * 128 + m * 16) * ldc + wc * 32 + 8 * fq + bj * 128) = w; } }
	v_pk_fma_f32 v[54:55], v[70:71], v[178:179], v[130:131] op_sel_hi:[1,0,1]
	v_pk_fma_f32 v[64:65], v[68:69], v[178:179], v[128:129] op_sel_hi:[1,0,1]
	s_waitcnt vmcnt(8)
	v_pk_fma_f32 v[50:51], v[78:79], v[178:179], v[134:135] op_sel_hi:[1,0,1]
	v_pk_fma_f32 v[48:49], v[76:77], v[178:179], v[132:133] op_sel_hi:[1,0,1]
	v_pk_fma_f32 v[56:57], v[56:57], v[180:181], v[128:129] op_sel_hi:[1,0,1]
	v_cvt_pk_bf16_f32 v48, v48, v49
	v_cvt_pk_bf16_f32 v49, v50, v51
	v_cvt_pk_bf16_f32 v50, v64, v65
	v_cvt_pk_bf16_f32 v51, v54, v55
	global_store_dwordx4 v[124:125], v[48:51], off offset:256
	v_pk_fma_f32 v[54:55], v[58:59], v[180:181], v[130:131] op_sel_hi:[1,0,1]
	v_pk_fma_f32 v[46:47], v[46:47], v[182:183], v[134:135] op_sel_hi:[1,0,1]
	v_pk_fma_f32 v[50:51], v[62:63], v[180:181], v[134:135] op_sel_hi:[1,0,1]
	v_pk_fma_f32 v[48:49], v[60:61], v[180:181], v[132:133] op_sel_hi:[1,0,1]
	v_pk_fma_f32 v[44:45], v[44:45], v[182:183], v[132:133] op_sel_hi:[1,0,1]
	v_cvt_pk_bf16_f32 v48, v48, v49
	v_cvt_pk_bf16_f32 v49, v50, v51
	v_cvt_pk_bf16_f32 v50, v56, v57
	v_cvt_pk_bf16_f32 v51, v54, v55
	global_store_dwordx4 v[116:117], v[48:51], off offset:256
	v_pk_fma_f32 v[38:39], v[38:39], v[184:185], v[134:135] op_sel_hi:[1,0,1]
	v_pk_fma_f32 v[36:37], v[36:37], v[184:185], v[132:133] op_sel_hi:[1,0,1]
	v_pk_fma_f32 v[48:49], v[42:43], v[182:183], v[130:131] op_sel_hi:[1,0,1]
	v_pk_fma_f32 v[42:43], v[40:41], v[182:183], v[128:129] op_sel_hi:[1,0,1]
	v_cvt_pk_bf16_f32 v40, v44, v45
	v_cvt_pk_bf16_f32 v41, v46, v47
	v_cvt_pk_bf16_f32 v42, v42, v43
	v_cvt_pk_bf16_f32 v43, v48, v49
	global_store_dwordx4 v[108:109], v[40:43], off offset:256
	v_pk_fma_f32 v[30:31], v[30:31], v[186:187], v[134:135] op_sel_hi:[1,0,1]
	v_pk_fma_f32 v[28:29], v[28:29], v[186:187], v[132:133] op_sel_hi:[1,0,1]
	v_pk_fma_f32 v[40:41], v[34:35], v[184:185], v[130:131] op_sel_hi:[1,0,1]
	v_pk_fma_f32 v[34:35], v[32:33], v[184:185], v[128:129] op_sel_hi:[1,0,1]
	v_cvt_pk_bf16_f32 v32, v36, v37
	v_cvt_pk_bf16_f32 v33, v38, v39
	v_cvt_pk_bf16_f32 v34, v34, v35
	v_cvt_pk_bf16_f32 v35, v40, v41
	global_store_dwordx4 v[100:101], v[32:35], off offset:256
	v_pk_fma_f32 v[22:23], v[22:23], v[188:189], v[134:135] op_sel_hi:[1,0,1]
	v_pk_fma_f32 v[20:21], v[20:21], v[188:189], v[132:133] op_sel_hi:[1,0,1]
	v_pk_fma_f32 v[32:33], v[26:27], v[186:187], v[130:131] op_sel_hi:[1,0,1]
	v_pk_fma_f32 v[26:27], v[24:25], v[186:187], v[128:129] op_sel_hi:[1,0,1]
	v_cvt_pk_bf16_f32 v24, v28, v29
	v_cvt_pk_bf16_f32 v25, v30, v31
	v_cvt_pk_bf16_f32 v26, v26, v27
	v_cvt_pk_bf16_f32 v27, v32, v33
	global_store_dwordx4 v[92:93], v[24:27], off offset:256
	v_pk_fma_f32 v[14:15], v[14:15], v[190:191], v[134:135] op_sel_hi:[1,0,1]
	v_pk_fma_f32 v[12:13], v[12:13], v[190:191], v[132:133] op_sel_hi:[1,0,1]
	v_pk_fma_f32 v[24:25], v[18:19], v[188:189], v[130:131] op_sel_hi:[1,0,1]
	v_pk_fma_f32 v[18:19], v[16:17], v[188:189], v[128:129] op_sel_hi:[1,0,1]
	v_cvt_pk_bf16_f32 v16, v20, v21
	v_cvt_pk_bf16_f32 v17, v22, v23
	v_cvt_pk_bf16_f32 v18, v18, v19
	v_cvt_pk_bf16_f32 v19, v24, v25
	global_store_dwordx4 v[84:85], v[16:19], off offset:256
	v_pk_fma_f32 v[6:7], v[6:7], v[192:193], v[134:135] op_sel_hi:[1,0,1]
	v_pk_fma_f32 v[4:5], v[4:5], v[192:193], v[132:133] op_sel_hi:[1,0,1]
	v_pk_fma_f32 v[16:17], v[10:11], v[190:191], v[130:131] op_sel_hi:[1,0,1]
	v_pk_fma_f32 v[10:11], v[8:9], v[190:191], v[128:129] op_sel_hi:[1,0,1]
	v_cvt_pk_bf16_f32 v8, v12, v13
	v_cvt_pk_bf16_f32 v9, v14, v15
	v_cvt_pk_bf16_f32 v10, v10, v11
	v_cvt_pk_bf16_f32 v11, v16, v17
	global_store_dwordx4 v[72:73], v[8:11], off offset:256
	s_nop 1
	v_pk_fma_f32 v[8:9], v[2:3], v[192:193], v[130:131] op_sel_hi:[1,0,1]
	v_pk_fma_f32 v[2:3], v[0:1], v[192:193], v[128:129] op_sel_hi:[1,0,1]
	v_cvt_pk_bf16_f32 v0, v4, v5
	v_cvt_pk_bf16_f32 v1, v6, v7
	v_cvt_pk_bf16_f32 v2, v2, v3
	v_cvt_pk_bf16_f32 v3, v8, v9
	global_store_dwordx4 v[52:53], v[0:3], off offset:256
	s_cbranch_vccnz .LBB0_1271
	s_andn2_b64 vcc, exec, s[10:11]
	s_cbranch_vccnz .LBB0_1270
	s_barrier
	s_branch .LBB0_1270

;     DI void operator()(const f32x4 (&acc)[2][2][4][2], const pg8::Unit& u, int wr, int wc, int fr, int fq) const {
;         const int lrow0 = u.pm * 256 + wr * 64 + fr, grow0 = row_base + u.pm * 256, col0 = u.pn * 256 + wc * 32 + 8 * fq;
;         bf16* Ou = O + (size_t)(u.pm * 256) * ldc + u.pn * 256;
;         const int mrow = grow0 < NCTX ? 8 : (grow0 - NCTX) >> 12;
;         float rstd[2][4];
; #pragma unroll
;         for (int ai = 0; ai < 2; ++ai)
; #pragma unroll
;             for (int m = 0; m < 4; ++m) rstd[ai][m] = rsqrtf(rss[row_base + lrow0 + ai * 128 + m * 16] * (1.f / DM) + EPS);
;         const float* bp = bias + mrow * 4096 + col0;
;         f32x4 bb[2][2];
; #pragma unroll
;         for (int bj = 0; bj < 2; ++bj) { bb[bj][0] = *(const f32x4*)(bp + bj * 128); bb[bj][1] = *(const f32x4*)(bp + bj * 128 + 4); }
;         asm volatile("" ::: "memory");
; #pragma unroll
;         for (int bj = 0; bj < 2; ++bj) { const f32x4 b0 = bb[bj][0], b1 = bb[bj][1];
; #pragma unroll
;             for (int ai = 0; ai < 2; ++ai)
; #pragma unroll
;                 for (int m = 0; m < 4; ++m) {
;                     f32x4 v0 = acc[ai][bj][m][0] * rstd[ai][m] + b0, v1 = acc[ai][bj][m][1] * rstd[ai][m] + b1;
.LBB0_1447:
	s_lshl_b32 s6, s44, 8
	v_add_u32_e32 v128, s6, v179
	v_ashrrev_i32_e32 v129, 31, v128
	v_lshl_add_u64 v[128:129], v[128:129], 2, s[60:61]
	global_load_dword v200, v[128:129], off
	global_load_dword v201, v[128:129], off offset:64
	global_load_dword v202, v[128:129], off offset:128
	global_load_dword v203, v[128:129], off offset:192
	global_load_dword v204, v[128:129], off offset:512
	global_load_dword v205, v[128:129], off offset:576
	global_load_dword v206, v[128:129], off offset:640
	global_load_dword v207, v[128:129], off offset:704
	s_lshl_b32 s4, s31, 8
	s_ashr_i32 s5, s4, 31
	s_mul_i32 s7, s44, 0xc0000
	s_mul_hi_i32 s6, s6, 0xc00
	s_add_u32 s7, s24, s7
	s_addc_u32 s6, s25, s6
	v_or_b32_e32 v208, s4, v183
	v_ashrrev_i32_e32 v209, 31, v208
	v_lshl_add_u64 v[208:209], v[208:209], 2, s[18:19]
	global_load_dwordx4 v[220:223], v[208:209], off offset:16
	global_load_dwordx4 v[224:227], v[208:209], off
	global_load_dwordx4 v[228:231], v[208:209], off offset:528
	global_load_dwordx4 v[232:235], v[208:209], off offset:512
	s_waitcnt vmcnt(11)
	v_fmamk_f32 v200, v200, 0x3a800000, v189
	v_cmp_gt_f32_e32 vcc, s48, v200
	v_mul_f32_e32 v131, 0x4b800000, v200
	s_nop 0
	v_cndmask_b32_e32 v200, v200, v131, vcc
	v_rsq_f32_e32 v200, v200
	s_nop 0
	v_mul_f32_e32 v131, 0x45800000, v200
	v_cndmask_b32_e32 v174, v200, v131, vcc
	s_waitcnt vmcnt(10)
	v_fmamk_f32 v201, v201, 0x3a800000, v189
	v_cmp_gt_f32_e32 vcc, s48, v201
	v_mul_f32_e32 v131, 0x4b800000, v201
	s_nop 0
	v_cndmask_b32_e32 v201, v201, v131, vcc
	v_rsq_f32_e32 v201, v201
	s_nop 0
	v_mul_f32_e32 v131, 0x45800000, v201
	v_cndmask_b32_e32 v176, v201, v131, vcc
	s_waitcnt vmcnt(9)
	v_fmamk_f32 v202, v202, 0x3a800000, v189
	v_cmp_gt_f32_e32 vcc, s48, v202
	v_mul_f32_e32 v131, 0x4b800000, v202
	s_nop 0
	v_cndmask_b32_e32 v202, v202, v131, vcc
	v_rsq_f32_e32 v202, v202
	s_nop 0
	v_mul_f32_e32 v131, 0x45800000, v202
	v_cndmask_b32_e32 v178, v202, v131, vcc
	s_waitcnt vmcnt(8)
	v_fmamk_f32 v203, v203, 0x3a800000, v189
	v_cmp_gt_f32_e32 vcc, s48, v203
	v_mul_f32_e32 v131, 0x4b800000, v203
	s_nop 0
	v_cndmask_b32_e32 v203, v203, v131, vcc
	v_rsq_f32_e32 v203, v203
	s_nop 0
	v_mul_f32_e32 v131, 0x45800000, v203
	v_cndmask_b32_e32 v180, v203, v131, vcc
	s_waitcnt vmcnt(7)
	v_fmamk_f32 v204, v204, 0x3a800000, v189
	v_cmp_gt_f32_e32 vcc, s48, v204
	v_mul_f32_e32 v131, 0x4b800000, v204
	s_nop 0
	v_cndmask_b32_e32 v204, v204, v131, vcc
	v_rsq_f32_e32 v204, v204
	s_nop 0
	v_mul_f32_e32 v131, 0x45800000, v204
	v_cndmask_b32_e32 v182, v204, v131, vcc
	s_waitcnt vmcnt(6)
	v_fmamk_f32 v205, v205, 0x3a800000, v189
	v_cmp_gt_f32_e32 vcc, s48, v205
	v_mul_f32_e32 v131, 0x4b800000, v205
	s_nop 0
	v_cndmask_b32_e32 v205, v205, v131, vcc
	v_rsq_f32_e32 v205, v205
	s_nop 0
	v_mul_f32_e32 v131, 0x45800000, v205
	v_cndmask_b32_e32 v184, v205, v131, vcc
	s_waitcnt vmcnt(5)
	v_fmamk_f32 v206, v206, 0x3a800000, v189
	v_cmp_gt_f32_e32 vcc, s48, v206
	v_mul_f32_e32 v131, 0x4b800000, v206
	s_waitcnt vmcnt(4)
	v_fmamk_f32 v207, v207, 0x3a800000, v189
	v_cndmask_b32_e32 v206, v206, v131, vcc
	v_rsq_f32_e32 v206, v206
	v_mul_f32_e32 v129, 0x4b800000, v207
	v_mul_f32_e32 v131, 0x45800000, v206
	v_cndmask_b32_e32 v186, v206, v131, vcc
	v_cmp_gt_f32_e32 vcc, s48, v207
	s_nop 1
	v_cndmask_b32_e32 v207, v207, v129, vcc
	v_rsq_f32_e32 v207, v207
	s_nop 0
	v_mul_f32_e32 v129, 0x45800000, v207
	v_cndmask_b32_e32 v188, v207, v129, vcc
	v_or_b32_e32 v128, s4, v183
	v_ashrrev_i32_e32 v129, 31, v128
	v_lshl_add_u64 v[132:133], v[128:129], 2, s[18:19]
	s_waitcnt vmcnt(0)
	v_mov_b32_e32 v136, v220
	v_mov_b32_e32 v137, v221
	v_mov_b32_e32 v138, v222
	v_mov_b32_e32 v139, v223
	v_mov_b32_e32 v140, v224
	v_mov_b32_e32 v141, v225
	v_mov_b32_e32 v142, v226
	v_mov_b32_e32 v143, v227
	v_mov_b32_e32 v128, v228
	v_mov_b32_e32 v129, v229
	v_mov_b32_e32 v130, v230
	v_mov_b32_e32 v131, v231
	v_mov_b32_e32 v132, v232
	v_mov_b32_e32 v133, v233
	v_mov_b32_e32 v134, v234
	v_mov_b32_e32 v135, v235
	s_nop 0
	s_nop 0
	s_nop 0
	s_nop 0
	s_nop 0
	s_nop 0
	s_nop 0
	s_nop 0
	s_nop 0
	s_nop 0
	s_nop 0
	s_nop 0
	s_lshl_b64 s[4:5], s[4:5], 1
	s_add_u32 s4, s7, s4
	s_addc_u32 s5, s6, s5
	s_add_u32 s4, s4, s49
	s_addc_u32 s5, s5, 0
	v_lshl_add_u64 v[190:191], s[4:5], 0, v[152:153]
	s_mov_b64 s[4:5], -1
	s_andn2_b64 vcc, exec, s[38:39]
	s_waitcnt vmcnt(3)
	v_pk_fma_f32 v[194:195], v[122:123], v[174:175], v[138:139] op_sel_hi:[1,0,1]
	s_waitcnt vmcnt(2)
; DI unsigned cvtpk(float lo, float hi) { f32x2 v = {lo, hi}; bf16x2_t b = __builtin_convertvector(v, bf16x2_t); return __builtin_bit_cast(unsigned, b); }
;     DI void operator()(const f32x4 (&acc)[2][2][4][2], const pg8::Unit& u, int wr, int wc, int fr, int fq) const {
;     ...
; #pragma unroll
;         for (int bj = 0; bj < 2; ++bj) { const f32x4 b0 = bb[bj][0], b1 = bb[bj][1];
; #pragma unroll
;             for (int ai = 0; ai < 2; ++ai)
; #pragma unroll
;                 for (int m = 0; m < 4; ++m) {
;                     f32x4 v0 = acc[ai][bj][m][0] * rstd[ai][m] + b0, v1 = acc[ai][bj][m][1] * rstd[ai][m] + b1;
;                     if (ACT == 1) {
; #pragma unroll
;                         for (int e = 0; e < 4; ++e) { float a = fmaxf(v0[e], 0.f), b = fmaxf(v1[e], 0.f); v0[e] = a * a; v1[e] = b * b; } }
;                     u32x4 w; w.x = cvtpk(v0[0], v0[1]); w.y = cvtpk(v0[2], v0[3]); w.z = cvtpk(v1[0], v1[1]); w.w = cvtpk(v1[2], v1[3]);
;                     *(u32x4*)(Ou + (wr * 64 + fr + ai * 128 + m * 16) * ldc + wc * 32 + 8 * fq + bj * 128) = w; } }
	v_pk_fma_f32 v[126:127], v[126:127], v[174:175], v[142:143] op_sel_hi:[1,0,1]
	v_pk_fma_f32 v[124:125], v[124:125], v[174:175], v[140:141] op_sel_hi:[1,0,1]
	v_pk_fma_f32 v[122:123], v[120:121], v[174:175], v[136:137] op_sel_hi:[1,0,1]
	v_cvt_pk_bf16_f32 v120, v124, v125
	v_cvt_pk_bf16_f32 v121, v126, v127
	v_cvt_pk_bf16_f32 v122, v122, v123
	v_cvt_pk_bf16_f32 v123, v194, v195
	v_lshl_add_u64 v[124:125], v[154:155], 1, v[190:191]
	global_store_dwordx4 v[124:125], v[120:123], off
	v_pk_fma_f32 v[118:119], v[118:119], v[176:177], v[142:143] op_sel_hi:[1,0,1]
	v_pk_fma_f32 v[116:117], v[116:117], v[176:177], v[140:141] op_sel_hi:[1,0,1]
	v_pk_fma_f32 v[120:121], v[114:115], v[176:177], v[138:139] op_sel_hi:[1,0,1]
	v_pk_fma_f32 v[114:115], v[112:113], v[176:177], v[136:137] op_sel_hi:[1,0,1]
	v_cvt_pk_bf16_f32 v112, v116, v117
	v_cvt_pk_bf16_f32 v113, v118, v119
	v_cvt_pk_bf16_f32 v114, v114, v115
	v_cvt_pk_bf16_f32 v115, v120, v121
	v_lshl_add_u64 v[116:117], v[156:157], 1, v[190:191]
	global_store_dwordx4 v[116:117], v[112:115], off
	v_pk_fma_f32 v[110:111], v[110:111], v[178:179], v[142:143] op_sel_hi:[1,0,1]
	v_pk_fma_f32 v[108:109], v[108:109], v[178:179], v[140:141] op_sel_hi:[1,0,1]
	v_pk_fma_f32 v[112:113], v[106:107], v[178:179], v[138:139] op_sel_hi:[1,0,1]
	v_pk_fma_f32 v[106:107], v[104:105], v[178:179], v[136:137] op_sel_hi:[1,0,1]
	v_cvt_pk_bf16_f32 v104, v108, v109
	v_cvt_pk_bf16_f32 v105, v110, v111
	v_cvt_pk_bf16_f32 v106, v106, v107
	v_cvt_pk_bf16_f32 v107, v112, v113
	v_lshl_add_u64 v[108:109], v[158:159], 1, v[190:191]
	global_store_dwordx4 v[108:109], v[104:107], off
	v_pk_fma_f32 v[102:103], v[102:103], v[180:181], v[142:143] op_sel_hi:[1,0,1]
	v_pk_fma_f32 v[100:101], v[100:101], v[180:181], v[140:141] op_sel_hi:[1,0,1]
	v_pk_fma_f32 v[104:105], v[98:99], v[180:181], v[138:139] op_sel_hi:[1,0,1]
	v_pk_fma_f32 v[98:99], v[96:97], v[180:181], v[136:137] op_sel_hi:[1,0,1]
	v_cvt_pk_bf16_f32 v96, v100, v101
	v_cvt_pk_bf16_f32 v97, v102, v103
	v_cvt_pk_bf16_f32 v98, v98, v99
	v_cvt_pk_bf16_f32 v99, v104, v105
	v_lshl_add_u64 v[100:101], v[160:161], 1, v[190:191]
	global_store_dwordx4 v[100:101], v[96:99], off
	v_pk_fma_f32 v[94:95], v[94:95], v[182:183], v[142:143] op_sel_hi:[1,0,1]
	v_pk_fma_f32 v[92:93], v[92:93], v[182:183], v[140:141] op_sel_hi:[1,0,1]
	v_pk_fma_f32 v[96:97], v[90:91], v[182:183], v[138:139] op_sel_hi:[1,0,1]
	v_pk_fma_f32 v[90:91], v[88:89], v[182:183], v[136:137] op_sel_hi:[1,0,1]
	v_cvt_pk_bf16_f32 v88, v92, v93
	v_cvt_pk_bf16_f32 v89, v94, v95
	v_cvt_pk_bf16_f32 v90, v90, v91
	v_cvt_pk_bf16_f32 v91, v96, v97
	v_lshl_add_u64 v[92:93], v[162:163], 1, v[190:191]
	global_store_dwordx4 v[92:93], v[88:91], off
	v_pk_fma_f32 v[86:87], v[86:87], v[184:185], v[142:143] op_sel_hi:[1,0,1]
	v_pk_fma_f32 v[84:85], v[84:85], v[184:185], v[140:141] op_sel_hi:[1,0,1]
	v_pk_fma_f32 v[88:89], v[82:83], v[184:185], v[138:139] op_sel_hi:[1,0,1]
	v_pk_fma_f32 v[82:83], v[80:81], v[184:185], v[136:137] op_sel_hi:[1,0,1]
	v_cvt_pk_bf16_f32 v80, v84, v85
	v_cvt_pk_bf16_f32 v81, v86, v87
	v_cvt_pk_bf16_f32 v82, v82, v83
	v_cvt_pk_bf16_f32 v83, v88, v89
	v_lshl_add_u64 v[84:85], v[164:165], 1, v[190:191]
	global_store_dwordx4 v[84:85], v[80:83], off
	v_pk_fma_f32 v[74:75], v[74:75], v[186:187], v[142:143] op_sel_hi:[1,0,1]
	v_pk_fma_f32 v[72:73], v[72:73], v[186:187], v[140:141] op_sel_hi:[1,0,1]
	v_pk_fma_f32 v[80:81], v[66:67], v[186:187], v[138:139] op_sel_hi:[1,0,1]
	v_pk_fma_f32 v[66:67], v[64:65], v[186:187], v[136:137] op_sel_hi:[1,0,1]
	v_cvt_pk_bf16_f32 v64, v72, v73
	v_cvt_pk_bf16_f32 v65, v74, v75
	v_cvt_pk_bf16_f32 v66, v66, v67
	v_cvt_pk_bf16_f32 v67, v80, v81
	v_lshl_add_u64 v[72:73], v[166:167], 1, v[190:191]
	global_store_dwordx4 v[72:73], v[64:67], off
	v_pk_fma_f32 v[54:55], v[54:55], v[188:189], v[142:143] op_sel_hi:[1,0,1]
	v_pk_fma_f32 v[52:53], v[52:53], v[188:189], v[140:141] op_sel_hi:[1,0,1]
	v_pk_fma_f32 v[64:65], v[50:51], v[188:189], v[138:139] op_sel_hi:[1,0,1]
	v_pk_fma_f32 v[50:51], v[48:49], v[188:189], v[136:137] op_sel_hi:[1,0,1]
	v_cvt_pk_bf16_f32 v48, v52, v53
	v_cvt_pk_bf16_f32 v49, v54, v55
	v_cvt_pk_bf16_f32 v50, v50, v51
	v_cvt_pk_bf16_f32 v51, v64, v65
	v_lshl_add_u64 v[52:53], v[168:169], 1, v[190:191]
	global_store_dwordx4 v[52:53], v[48:51], off
	s_waitcnt vmcnt(9)
; #define PG8_BAR __builtin_amdgcn_s_barrier()
; DI unsigned cvtpk(float lo, float hi) { f32x2 v = {lo, hi}; bf16x2_t b = __builtin_convertvector(v, bf16x2_t); return __builtin_bit_cast(unsigned, b); }
; template <class Epi, class Sched, bool ALIGN_EPI = false, bool SP2 = false>
; __device__ __forceinline__ void gemm_phase(PG8_LAS unsigned char* lds, const Gemm g, const Sched& S, const Epi& E, const int tid_in) {
;     ...
;         if (!has_next) break;
; #pragma unroll
;         for (int a = 0; a < 2; ++a)
; #pragma unroll
;             for (int b = 0; b < 2; ++b)
; #pragma unroll
;                 for (int m = 0; m < 4; ++m)
; #pragma unroll
;                     for (int n = 0; n < 2; ++n) acc[a][b][m][n] = (f32x4){0.f, 0.f, 0.f, 0.f};
;         cur = nxt; cA = nA; cB = nB; ++ui;
;         if constexpr (ALIGN_EPI) { if (wr == 1) PG8_BAR; }
;     DI void operator()(const f32x4 (&acc)[2][2][4][2], const pg8::Unit& u, int wr, int wc, int fr, int fq) const {
;     ...
; #pragma unroll
;         for (int bj = 0; bj < 2; ++bj) { const f32x4 b0 = bb[bj][0], b1 = bb[bj][1];
; #pragma unroll
;             for (int ai = 0; ai < 2; ++ai)
; #pragma unroll
;                 for (int m = 0; m < 4; ++m) {
;                     f32x4 v0 = acc[ai][bj][m][0] * rstd[ai][m] + b0, v1 = acc[ai][bj][m][1] * rstd[ai][m] + b1;
;                     if (ACT == 1) {
; #pragma unroll
;                         for (int e = 0; e < 4; ++e) { float a = fmaxf(v0[e], 0.f), b = fmaxf(v1[e], 0.f); v0[e] = a * a; v1[e] = b * b; } }
;                     u32x4 w; w.x = cvtpk(v0[0], v0[1]); w.y = cvtpk(v0[2], v0[3]); w.z = cvtpk(v1[0], v1[1]); w.w = cvtpk(v1[2], v1[3]);
;                     *(u32x4*)(Ou + (wr * 64 + fr + ai * 128 + m * 16) * ldc + wc * 32 + 8 * fq + bj * 128) = w; } }
	v_pk_fma_f32 v[54:55], v[70:71], v[174:175], v[130:131] op_sel_hi:[1,0,1]
	v_pk_fma_f32 v[64:65], v[68:69], v[174:175], v[128:129] op_sel_hi:[1,0,1]
	s_waitcnt vmcnt(8)
	v_pk_fma_f32 v[50:51], v[78:79], v[174:175], v[134:135] op_sel_hi:[1,0,1]
	v_pk_fma_f32 v[48:49], v[76:77], v[174:175], v[132:133] op_sel_hi:[1,0,1]
	v_pk_fma_f32 v[56:57], v[56:57], v[176:177], v[128:129] op_sel_hi:[1,0,1]
	v_cvt_pk_bf16_f32 v48, v48, v49
	v_cvt_pk_bf16_f32 v49, v50, v51
	v_cvt_pk_bf16_f32 v50, v64, v65
	v_cvt_pk_bf16_f32 v51, v54, v55
	global_store_dwordx4 v[124:125], v[48:51], off offset:256
	v_pk_fma_f32 v[54:55], v[58:59], v[176:177], v[130:131] op_sel_hi:[1,0,1]
	v_pk_fma_f32 v[46:47], v[46:47], v[178:179], v[134:135] op_sel_hi:[1,0,1]
	v_pk_fma_f32 v[50:51], v[62:63], v[176:177], v[134:135] op_sel_hi:[1,0,1]
	v_pk_fma_f32 v[48:49], v[60:61], v[176:177], v[132:133] op_sel_hi:[1,0,1]
	v_pk_fma_f32 v[44:45], v[44:45], v[178:179], v[132:133] op_sel_hi:[1,0,1]
	v_cvt_pk_bf16_f32 v48, v48, v49
	v_cvt_pk_bf16_f32 v49, v50, v51
	v_cvt_pk_bf16_f32 v50, v56, v57
	v_cvt_pk_bf16_f32 v51, v54, v55
	global_store_dwordx4 v[116:117], v[48:51], off offset:256
	v_pk_fma_f32 v[38:39], v[38:39], v[180:181], v[134:135] op_sel_hi:[1,0,1]
	v_pk_fma_f32 v[36:37], v[36:37], v[180:181], v[132:133] op_sel_hi:[1,0,1]
	v_pk_fma_f32 v[48:49], v[42:43], v[178:179], v[130:131] op_sel_hi:[1,0,1]
	v_pk_fma_f32 v[42:43], v[40:41], v[178:179], v[128:129] op_sel_hi:[1,0,1]
	v_cvt_pk_bf16_f32 v40, v44, v45
	v_cvt_pk_bf16_f32 v41, v46, v47
	v_cvt_pk_bf16_f32 v42, v42, v43
	v_cvt_pk_bf16_f32 v43, v48, v49
	global_store_dwordx4 v[108:109], v[40:43], off offset:256
	v_pk_fma_f32 v[30:31], v[30:31], v[182:183], v[134:135] op_sel_hi:[1,0,1]
	v_pk_fma_f32 v[28:29], v[28:29], v[182:183], v[132:133] op_sel_hi:[1,0,1]
	v_pk_fma_f32 v[40:41], v[34:35], v[180:181], v[130:131] op_sel_hi:[1,0,1]
	v_pk_fma_f32 v[34:35], v[32:33], v[180:181], v[128:129] op_sel_hi:[1,0,1]
	v_cvt_pk_bf16_f32 v32, v36, v37
	v_cvt_pk_bf16_f32 v33, v38, v39
	v_cvt_pk_bf16_f32 v34, v34, v35
	v_cvt_pk_bf16_f32 v35, v40, v41
	global_store_dwordx4 v[100:101], v[32:35], off offset:256
	v_pk_fma_f32 v[22:23], v[22:23], v[184:185], v[134:135] op_sel_hi:[1,0,1]
	v_pk_fma_f32 v[20:21], v[20:21], v[184:185], v[132:133] op_sel_hi:[1,0,1]
	v_pk_fma_f32 v[32:33], v[26:27], v[182:183], v[130:131] op_sel_hi:[1,0,1]
	v_pk_fma_f32 v[26:27], v[24:25], v[182:183], v[128:129] op_sel_hi:[1,0,1]
	v_cvt_pk_bf16_f32 v24, v28, v29
	v_cvt_pk_bf16_f32 v25, v30, v31
	v_cvt_pk_bf16_f32 v26, v26, v27
	v_cvt_pk_bf16_f32 v27, v32, v33
	global_store_dwordx4 v[92:93], v[24:27], off offset:256
	v_pk_fma_f32 v[14:15], v[14:15], v[186:187], v[134:135] op_sel_hi:[1,0,1]
	v_pk_fma_f32 v[12:13], v[12:13], v[186:187], v[132:133] op_sel_hi:[1,0,1]
	v_pk_fma_f32 v[24:25], v[18:19], v[184:185], v[130:131] op_sel_hi:[1,0,1]
	v_pk_fma_f32 v[18:19], v[16:17], v[184:185], v[128:129] op_sel_hi:[1,0,1]
	v_cvt_pk_bf16_f32 v16, v20, v21
	v_cvt_pk_bf16_f32 v17, v22, v23
	v_cvt_pk_bf16_f32 v18, v18, v19
	v_cvt_pk_bf16_f32 v19, v24, v25
	global_store_dwordx4 v[84:85], v[16:19], off offset:256
	v_pk_fma_f32 v[6:7], v[6:7], v[188:189], v[134:135] op_sel_hi:[1,0,1]
	v_pk_fma_f32 v[4:5], v[4:5], v[188:189], v[132:133] op_sel_hi:[1,0,1]
	v_pk_fma_f32 v[16:17], v[10:11], v[186:187], v[130:131] op_sel_hi:[1,0,1]
	v_pk_fma_f32 v[10:11], v[8:9], v[186:187], v[128:129] op_sel_hi:[1,0,1]
	v_cvt_pk_bf16_f32 v8, v12, v13
	v_cvt_pk_bf16_f32 v9, v14, v15
	v_cvt_pk_bf16_f32 v10, v10, v11
	v_cvt_pk_bf16_f32 v11, v16, v17
	global_store_dwordx4 v[72:73], v[8:11], off offset:256
	s_nop 1
	v_pk_fma_f32 v[8:9], v[2:3], v[188:189], v[130:131] op_sel_hi:[1,0,1]
	v_pk_fma_f32 v[2:3], v[0:1], v[188:189], v[128:129] op_sel_hi:[1,0,1]
	v_cvt_pk_bf16_f32 v0, v4, v5
	v_cvt_pk_bf16_f32 v1, v6, v7
	v_cvt_pk_bf16_f32 v2, v2, v3
	v_cvt_pk_bf16_f32 v3, v8, v9
	global_store_dwordx4 v[52:53], v[0:3], off offset:256
	s_cbranch_vccnz .LBB0_1440
	s_andn2_b64 vcc, exec, s[0:1]
	s_cbranch_vccnz .LBB0_1439
	s_barrier
	s_branch .LBB0_1439

;     DI void operator()(const f32x4 (&acc)[2][2][4][2], const pg8::Unit& u, int wr, int wc, int fr, int fq) const {
;         const int lrow0 = u.pm * 256 + wr * 64 + fr, grow0 = row_base + u.pm * 256, col0 = u.pn * 256 + wc * 32 + 8 * fq;
;         bf16* Ou = O + (size_t)(u.pm * 256) * ldc + u.pn * 256;
;         const int mrow = grow0 < NCTX ? 8 : (grow0 - NCTX) >> 12;
;         float rstd[2][4];
; #pragma unroll
;         for (int ai = 0; ai < 2; ++ai)
; #pragma unroll
;             for (int m = 0; m < 4; ++m) rstd[ai][m] = rsqrtf(rss[row_base + lrow0 + ai * 128 + m * 16] * (1.f / DM) + EPS);
;         const float* bp = bias + mrow * 4096 + col0;
;         f32x4 bb[2][2];
; #pragma unroll
;         for (int bj = 0; bj < 2; ++bj) { bb[bj][0] = *(const f32x4*)(bp + bj * 128); bb[bj][1] = *(const f32x4*)(bp + bj * 128 + 4); }
;         asm volatile("" ::: "memory");
; #pragma unroll
;         for (int bj = 0; bj < 2; ++bj) { const f32x4 b0 = bb[bj][0], b1 = bb[bj][1];
; #pragma unroll
;             for (int ai = 0; ai < 2; ++ai)
; #pragma unroll
;                 for (int m = 0; m < 4; ++m) {
;                     f32x4 v0 = acc[ai][bj][m][0] * rstd[ai][m] + b0, v1 = acc[ai][bj][m][1] * rstd[ai][m] + b1;
.LBB0_1709:
	s_lshl_b32 s6, s38, 8
	v_add_u32_e32 v128, s6, v183
	v_ashrrev_i32_e32 v129, 31, v128
	v_lshl_add_u64 v[128:129], v[128:129], 2, s[0:1]
	global_load_dword v200, v[128:129], off
	global_load_dword v201, v[128:129], off offset:64
	global_load_dword v202, v[128:129], off offset:128
	global_load_dword v203, v[128:129], off offset:192
	global_load_dword v204, v[128:129], off offset:512
	global_load_dword v205, v[128:129], off offset:576
	global_load_dword v206, v[128:129], off offset:640
	global_load_dword v207, v[128:129], off offset:704
	s_lshl_b32 s4, s31, 8
	s_ashr_i32 s7, s6, 31
	s_ashr_i32 s5, s4, 31
	s_lshl_b64 s[8:9], s[6:7], 13
	v_readlane_b32 s52, v254, 36
	v_readlane_b32 s53, v254, 37
	s_add_u32 s8, s52, s8
	s_addc_u32 s9, s53, s9
	s_and_b32 s7, s6, 0xfffff000
	s_cmp_lt_u32 s6, 0x7ffff800
	s_cselect_b32 s6, s7, 0x8000
	s_ashr_i32 s7, s6, 31
	s_lshl_b64 s[6:7], s[6:7], 2
	s_add_u32 s6, s44, s6
	s_addc_u32 s7, s45, s7
	v_or_b32_e32 v208, s4, v181
	v_ashrrev_i32_e32 v209, 31, v208
	v_lshl_add_u64 v[208:209], v[208:209], 2, s[6:7]
	global_load_dwordx4 v[220:223], v[208:209], off offset:16
	global_load_dwordx4 v[224:227], v[208:209], off
	global_load_dwordx4 v[228:231], v[208:209], off offset:528
	global_load_dwordx4 v[232:235], v[208:209], off offset:512
	s_waitcnt vmcnt(11)
	v_fmamk_f32 v200, v200, 0x3a800000, v187
	v_cmp_gt_f32_e32 vcc, s49, v200
	v_mul_f32_e32 v131, 0x4b800000, v200
	s_nop 0
	v_cndmask_b32_e32 v200, v200, v131, vcc
	v_rsq_f32_e32 v200, v200
	s_nop 0
	v_mul_f32_e32 v131, 0x45800000, v200
	v_cndmask_b32_e32 v192, v200, v131, vcc
	s_waitcnt vmcnt(10)
	v_fmamk_f32 v201, v201, 0x3a800000, v187
	v_cmp_gt_f32_e32 vcc, s49, v201
	v_mul_f32_e32 v131, 0x4b800000, v201
	s_nop 0
	v_cndmask_b32_e32 v201, v201, v131, vcc
	v_rsq_f32_e32 v201, v201
	s_nop 0
	v_mul_f32_e32 v131, 0x45800000, v201
	v_cndmask_b32_e32 v190, v201, v131, vcc
	s_waitcnt vmcnt(9)
	v_fmamk_f32 v202, v202, 0x3a800000, v187
	v_cmp_gt_f32_e32 vcc, s49, v202
	v_mul_f32_e32 v131, 0x4b800000, v202
	s_nop 0
	v_cndmask_b32_e32 v202, v202, v131, vcc
	v_rsq_f32_e32 v202, v202
	s_nop 0
	v_mul_f32_e32 v131, 0x45800000, v202
	v_cndmask_b32_e32 v188, v202, v131, vcc
	s_waitcnt vmcnt(8)
	v_fmamk_f32 v203, v203, 0x3a800000, v187
	v_cmp_gt_f32_e32 vcc, s49, v203
	v_mul_f32_e32 v131, 0x4b800000, v203
	s_nop 0
	v_cndmask_b32_e32 v203, v203, v131, vcc
	v_rsq_f32_e32 v203, v203
	s_nop 0
	v_mul_f32_e32 v131, 0x45800000, v203
	v_cndmask_b32_e32 v186, v203, v131, vcc
	s_waitcnt vmcnt(7)
	v_fmamk_f32 v204, v204, 0x3a800000, v187
	v_cmp_gt_f32_e32 vcc, s49, v204
	v_mul_f32_e32 v131, 0x4b800000, v204
	s_nop 0
	v_cndmask_b32_e32 v204, v204, v131, vcc
	v_rsq_f32_e32 v204, v204
	s_nop 0
	v_mul_f32_e32 v131, 0x45800000, v204
	v_cndmask_b32_e32 v184, v204, v131, vcc
	s_waitcnt vmcnt(6)
	v_fmamk_f32 v205, v205, 0x3a800000, v187
	v_cmp_gt_f32_e32 vcc, s49, v205
	v_mul_f32_e32 v131, 0x4b800000, v205
	s_nop 0
	v_cndmask_b32_e32 v205, v205, v131, vcc
	v_rsq_f32_e32 v205, v205
	s_nop 0
	v_mul_f32_e32 v131, 0x45800000, v205
	v_cndmask_b32_e32 v182, v205, v131, vcc
	s_waitcnt vmcnt(5)
	v_fmamk_f32 v206, v206, 0x3a800000, v187
	v_cmp_gt_f32_e32 vcc, s49, v206
	v_mul_f32_e32 v131, 0x4b800000, v206
	s_waitcnt vmcnt(4)
	v_fmamk_f32 v207, v207, 0x3a800000, v187
	v_cndmask_b32_e32 v206, v206, v131, vcc
	v_rsq_f32_e32 v206, v206
	v_mul_f32_e32 v129, 0x4b800000, v207
	v_mul_f32_e32 v131, 0x45800000, v206
	v_cndmask_b32_e32 v180, v206, v131, vcc
	v_cmp_gt_f32_e32 vcc, s49, v207
	s_nop 1
	v_cndmask_b32_e32 v207, v207, v129, vcc
	v_rsq_f32_e32 v207, v207
	s_nop 0
	v_mul_f32_e32 v129, 0x45800000, v207
	v_cndmask_b32_e32 v178, v207, v129, vcc
	v_or_b32_e32 v128, s4, v181
	v_ashrrev_i32_e32 v129, 31, v128
	v_lshl_add_u64 v[132:133], v[128:129], 2, s[6:7]
	s_waitcnt vmcnt(0)
	v_mov_b32_e32 v136, v220
	v_mov_b32_e32 v137, v221
	v_mov_b32_e32 v138, v222
	v_mov_b32_e32 v139, v223
	v_mov_b32_e32 v140, v224
	v_mov_b32_e32 v141, v225
	v_mov_b32_e32 v142, v226
	v_mov_b32_e32 v143, v227
	v_mov_b32_e32 v128, v228
	v_mov_b32_e32 v129, v229
	v_mov_b32_e32 v130, v230
	v_mov_b32_e32 v131, v231
	v_mov_b32_e32 v132, v232
	v_mov_b32_e32 v133, v233
	v_mov_b32_e32 v134, v234
	v_mov_b32_e32 v135, v235
	s_nop 0
	s_nop 0
	s_nop 0
	s_nop 0
	s_nop 0
	s_nop 0
	s_nop 0
	s_nop 0
	s_nop 0
	s_nop 0
	s_nop 0
	s_nop 0
	s_lshl_b64 s[4:5], s[4:5], 1
	s_add_u32 s4, s8, s4
	s_addc_u32 s5, s9, s5
	s_add_u32 s4, s4, s50
	s_addc_u32 s5, s5, 0
	v_lshl_add_u64 v[194:195], s[4:5], 0, v[152:153]
	s_mov_b64 s[4:5], 0x100
	s_andn2_b64 vcc, exec, s[34:35]
	s_waitcnt vmcnt(3)
	v_pk_fma_f32 v[122:123], v[122:123], v[192:193], v[138:139] op_sel_hi:[1,0,1]
	s_waitcnt vmcnt(2)
; DI unsigned cvtpk(float lo, float hi) { f32x2 v = {lo, hi}; bf16x2_t b = __builtin_convertvector(v, bf16x2_t); return __builtin_bit_cast(unsigned, b); }
;     DI void operator()(const f32x4 (&acc)[2][2][4][2], const pg8::Unit& u, int wr, int wc, int fr, int fq) const {
;     ...
; #pragma unroll
;         for (int bj = 0; bj < 2; ++bj) { const f32x4 b0 = bb[bj][0], b1 = bb[bj][1];
; #pragma unroll
;             for (int ai = 0; ai < 2; ++ai)
; #pragma unroll
;                 for (int m = 0; m < 4; ++m) {
;                     f32x4 v0 = acc[ai][bj][m][0] * rstd[ai][m] + b0, v1 = acc[ai][bj][m][1] * rstd[ai][m] + b1;
;                     if (ACT == 1) {
; #pragma unroll
;                         for (int e = 0; e < 4; ++e) { float a = fmaxf(v0[e], 0.f), b = fmaxf(v1[e], 0.f); v0[e] = a * a; v1[e] = b * b; } }
;                     u32x4 w; w.x = cvtpk(v0[0], v0[1]); w.y = cvtpk(v0[2], v0[3]); w.z = cvtpk(v1[0], v1[1]); w.w = cvtpk(v1[2], v1[3]);
;                     *(u32x4*)(Ou + (wr * 64 + fr + ai * 128 + m * 16) * ldc + wc * 32 + 8 * fq + bj * 128) = w; } }
	v_pk_fma_f32 v[126:127], v[126:127], v[192:193], v[142:143] op_sel_hi:[1,0,1]
	v_pk_fma_f32 v[124:125], v[124:125], v[192:193], v[140:141] op_sel_hi:[1,0,1]
	v_pk_fma_f32 v[120:121], v[120:121], v[192:193], v[136:137] op_sel_hi:[1,0,1]
	v_max_f32_e32 v124, 0, v124
	v_max_f32_e32 v120, 0, v120
	v_max_f32_e32 v125, 0, v125
	v_max_f32_e32 v121, 0, v121
	v_max_f32_e32 v126, 0, v126
	v_max_f32_e32 v122, 0, v122
	v_max_f32_e32 v127, 0, v127
	v_max_f32_e32 v123, 0, v123
	v_pk_mul_f32 v[124:125], v[124:125], v[124:125]
	v_pk_mul_f32 v[120:121], v[120:121], v[120:121]
	v_pk_mul_f32 v[126:127], v[126:127], v[126:127]
	v_pk_mul_f32 v[196:197], v[122:123], v[122:123]
	v_pk_fma_f32 v[112:113], v[112:113], v[190:191], v[136:137] op_sel_hi:[1,0,1]
	v_cvt_pk_bf16_f32 v122, v124, v125
	v_cvt_pk_bf16_f32 v123, v126, v127
	v_cvt_pk_bf16_f32 v124, v120, v121
	v_cvt_pk_bf16_f32 v125, v196, v197
	v_lshl_add_u64 v[120:121], v[154:155], 1, v[194:195]
	v_pk_fma_f32 v[118:119], v[118:119], v[190:191], v[142:143] op_sel_hi:[1,0,1]
	v_pk_fma_f32 v[116:117], v[116:117], v[190:191], v[140:141] op_sel_hi:[1,0,1]
	v_pk_fma_f32 v[114:115], v[114:115], v[190:191], v[138:139] op_sel_hi:[1,0,1]
	v_max_f32_e32 v112, 0, v112
	v_max_f32_e32 v113, 0, v113
	global_store_dwordx4 v[120:121], v[122:125], off
	v_max_f32_e32 v116, 0, v116
	v_max_f32_e32 v117, 0, v117
	v_pk_mul_f32 v[122:123], v[112:113], v[112:113]
	v_max_f32_e32 v112, 0, v118
	v_max_f32_e32 v114, 0, v114
	v_max_f32_e32 v113, 0, v119
	v_max_f32_e32 v115, 0, v115
	v_pk_mul_f32 v[116:117], v[116:117], v[116:117]
	v_pk_mul_f32 v[118:119], v[112:113], v[112:113]
	v_pk_mul_f32 v[124:125], v[114:115], v[114:115]
	v_pk_fma_f32 v[104:105], v[104:105], v[188:189], v[136:137] op_sel_hi:[1,0,1]
	v_cvt_pk_bf16_f32 v112, v116, v117
	v_cvt_pk_bf16_f32 v113, v118, v119
	v_cvt_pk_bf16_f32 v114, v122, v123
	v_cvt_pk_bf16_f32 v115, v124, v125
	v_lshl_add_u64 v[116:117], v[194:195], 0, v[170:171]
	v_pk_fma_f32 v[110:111], v[110:111], v[188:189], v[142:143] op_sel_hi:[1,0,1]
	v_pk_fma_f32 v[108:109], v[108:109], v[188:189], v[140:141] op_sel_hi:[1,0,1]
	v_pk_fma_f32 v[106:107], v[106:107], v[188:189], v[138:139] op_sel_hi:[1,0,1]
	v_max_f32_e32 v104, 0, v104
	v_max_f32_e32 v105, 0, v105
	global_store_dwordx4 v[116:117], v[112:115], off
	v_max_f32_e32 v108, 0, v108
	v_max_f32_e32 v109, 0, v109
	v_pk_mul_f32 v[112:113], v[104:105], v[104:105]
	v_max_f32_e32 v104, 0, v110
	v_max_f32_e32 v106, 0, v106
	v_max_f32_e32 v105, 0, v111
	v_max_f32_e32 v107, 0, v107
	v_pk_mul_f32 v[108:109], v[108:109], v[108:109]
	v_pk_mul_f32 v[110:111], v[104:105], v[104:105]
	v_pk_mul_f32 v[114:115], v[106:107], v[106:107]
	v_pk_fma_f32 v[96:97], v[96:97], v[186:187], v[136:137] op_sel_hi:[1,0,1]
	v_cvt_pk_bf16_f32 v104, v108, v109
	v_cvt_pk_bf16_f32 v105, v110, v111
	v_cvt_pk_bf16_f32 v106, v112, v113
	v_cvt_pk_bf16_f32 v107, v114, v115
	v_lshl_add_u64 v[108:109], v[194:195], 0, v[172:173]
	v_pk_fma_f32 v[102:103], v[102:103], v[186:187], v[142:143] op_sel_hi:[1,0,1]
	v_pk_fma_f32 v[100:101], v[100:101], v[186:187], v[140:141] op_sel_hi:[1,0,1]
	v_pk_fma_f32 v[98:99], v[98:99], v[186:187], v[138:139] op_sel_hi:[1,0,1]
	v_max_f32_e32 v96, 0, v96
	v_max_f32_e32 v97, 0, v97
	global_store_dwordx4 v[108:109], v[104:107], off
	v_max_f32_e32 v100, 0, v100
	v_max_f32_e32 v101, 0, v101
	v_pk_mul_f32 v[104:105], v[96:97], v[96:97]
	v_max_f32_e32 v96, 0, v102
	v_max_f32_e32 v98, 0, v98
	v_max_f32_e32 v97, 0, v103
	v_max_f32_e32 v99, 0, v99
	v_pk_mul_f32 v[100:101], v[100:101], v[100:101]
	v_pk_mul_f32 v[102:103], v[96:97], v[96:97]
	v_pk_mul_f32 v[106:107], v[98:99], v[98:99]
	v_pk_fma_f32 v[94:95], v[94:95], v[184:185], v[142:143] op_sel_hi:[1,0,1]
	v_pk_fma_f32 v[92:93], v[92:93], v[184:185], v[140:141] op_sel_hi:[1,0,1]
	v_pk_fma_f32 v[90:91], v[90:91], v[184:185], v[138:139] op_sel_hi:[1,0,1]
	v_pk_fma_f32 v[88:89], v[88:89], v[184:185], v[136:137] op_sel_hi:[1,0,1]
	v_cvt_pk_bf16_f32 v96, v100, v101
	v_cvt_pk_bf16_f32 v97, v102, v103
	v_cvt_pk_bf16_f32 v98, v104, v105
	v_cvt_pk_bf16_f32 v99, v106, v107
	v_lshl_add_u64 v[100:101], v[194:195], 0, v[174:175]
	v_max_f32_e32 v92, 0, v92
	v_max_f32_e32 v88, 0, v88
	v_max_f32_e32 v93, 0, v93
	v_max_f32_e32 v89, 0, v89
	v_max_f32_e32 v94, 0, v94
	v_max_f32_e32 v90, 0, v90
	v_max_f32_e32 v95, 0, v95
	v_max_f32_e32 v91, 0, v91
	global_store_dwordx4 v[100:101], v[96:99], off
	v_pk_mul_f32 v[92:93], v[92:93], v[92:93]
	v_pk_mul_f32 v[88:89], v[88:89], v[88:89]
	v_pk_mul_f32 v[94:95], v[94:95], v[94:95]
	v_pk_mul_f32 v[96:97], v[90:91], v[90:91]
	v_pk_fma_f32 v[86:87], v[86:87], v[182:183], v[142:143] op_sel_hi:[1,0,1]
	v_pk_fma_f32 v[84:85], v[84:85], v[182:183], v[140:141] op_sel_hi:[1,0,1]
	v_pk_fma_f32 v[82:83], v[82:83], v[182:183], v[138:139] op_sel_hi:[1,0,1]
	v_pk_fma_f32 v[80:81], v[80:81], v[182:183], v[136:137] op_sel_hi:[1,0,1]
	v_cvt_pk_bf16_f32 v90, v92, v93
	v_cvt_pk_bf16_f32 v91, v94, v95
	v_cvt_pk_bf16_f32 v92, v88, v89
	v_cvt_pk_bf16_f32 v93, v96, v97
	v_lshl_add_u64 v[88:89], v[156:157], 1, v[194:195]
	v_max_f32_e32 v84, 0, v84
	v_max_f32_e32 v80, 0, v80
	v_max_f32_e32 v85, 0, v85
	v_max_f32_e32 v81, 0, v81
	v_max_f32_e32 v86, 0, v86
	v_max_f32_e32 v82, 0, v82
	v_max_f32_e32 v87, 0, v87
	v_max_f32_e32 v83, 0, v83
	global_store_dwordx4 v[88:89], v[90:93], off
	v_pk_mul_f32 v[84:85], v[84:85], v[84:85]
	v_pk_mul_f32 v[80:81], v[80:81], v[80:81]
	v_pk_mul_f32 v[86:87], v[86:87], v[86:87]
	v_pk_mul_f32 v[90:91], v[82:83], v[82:83]
	v_pk_fma_f32 v[78:79], v[78:79], v[180:181], v[142:143] op_sel_hi:[1,0,1]
	v_pk_fma_f32 v[76:77], v[76:77], v[180:181], v[140:141] op_sel_hi:[1,0,1]
; DI unsigned cvtpk(float lo, float hi) { f32x2 v = {lo, hi}; bf16x2_t b = __builtin_convertvector(v, bf16x2_t); return __builtin_bit_cast(unsigned, b); }
;     DI void operator()(const f32x4 (&acc)[2][2][4][2], const pg8::Unit& u, int wr, int wc, int fr, int fq) const {
;     ...
; #pragma unroll
;         for (int bj = 0; bj < 2; ++bj) { const f32x4 b0 = bb[bj][0], b1 = bb[bj][1];
; #pragma unroll
;             for (int ai = 0; ai < 2; ++ai)
; #pragma unroll
;                 for (int m = 0; m < 4; ++m) {
;                     f32x4 v0 = acc[ai][bj][m][0] * rstd[ai][m] + b0, v1 = acc[ai][bj][m][1] * rstd[ai][m] + b1;
;                     if (ACT == 1) {
; #pragma unroll
;                         for (int e = 0; e < 4; ++e) { float a = fmaxf(v0[e], 0.f), b = fmaxf(v1[e], 0.f); v0[e] = a * a; v1[e] = b * b; } }
;                     u32x4 w; w.x = cvtpk(v0[0], v0[1]); w.y = cvtpk(v0[2], v0[3]); w.z = cvtpk(v1[0], v1[1]); w.w = cvtpk(v1[2], v1[3]);
;                     *(u32x4*)(Ou + (wr * 64 + fr + ai * 128 + m * 16) * ldc + wc * 32 + 8 * fq + bj * 128) = w; } }
	v_pk_fma_f32 v[74:75], v[74:75], v[180:181], v[138:139] op_sel_hi:[1,0,1]
	v_pk_fma_f32 v[72:73], v[72:73], v[180:181], v[136:137] op_sel_hi:[1,0,1]
	v_cvt_pk_bf16_f32 v82, v84, v85
	v_cvt_pk_bf16_f32 v83, v86, v87
	v_cvt_pk_bf16_f32 v84, v80, v81
	v_cvt_pk_bf16_f32 v85, v90, v91
	v_lshl_add_u64 v[80:81], v[158:159], 1, v[194:195]
	v_max_f32_e32 v76, 0, v76
	v_max_f32_e32 v72, 0, v72
	v_max_f32_e32 v77, 0, v77
	v_max_f32_e32 v73, 0, v73
	v_max_f32_e32 v78, 0, v78
	v_max_f32_e32 v74, 0, v74
	v_max_f32_e32 v79, 0, v79
	v_max_f32_e32 v75, 0, v75
	global_store_dwordx4 v[80:81], v[82:85], off
	v_pk_mul_f32 v[76:77], v[76:77], v[76:77]
	v_pk_mul_f32 v[72:73], v[72:73], v[72:73]
	v_pk_mul_f32 v[78:79], v[78:79], v[78:79]
	v_pk_mul_f32 v[82:83], v[74:75], v[74:75]
	v_pk_fma_f32 v[62:63], v[62:63], v[178:179], v[142:143] op_sel_hi:[1,0,1]
	v_pk_fma_f32 v[60:61], v[60:61], v[178:179], v[140:141] op_sel_hi:[1,0,1]
	v_pk_fma_f32 v[58:59], v[58:59], v[178:179], v[138:139] op_sel_hi:[1,0,1]
	v_pk_fma_f32 v[56:57], v[56:57], v[178:179], v[136:137] op_sel_hi:[1,0,1]
	v_cvt_pk_bf16_f32 v74, v76, v77
	v_cvt_pk_bf16_f32 v75, v78, v79
	v_cvt_pk_bf16_f32 v76, v72, v73
	v_cvt_pk_bf16_f32 v77, v82, v83
	v_lshl_add_u64 v[72:73], v[160:161], 1, v[194:195]
	v_max_f32_e32 v60, 0, v60
	v_max_f32_e32 v56, 0, v56
	v_max_f32_e32 v61, 0, v61
	v_max_f32_e32 v57, 0, v57
	v_max_f32_e32 v62, 0, v62
	v_max_f32_e32 v58, 0, v58
	v_max_f32_e32 v63, 0, v63
	v_max_f32_e32 v59, 0, v59
	global_store_dwordx4 v[72:73], v[74:77], off
	v_pk_mul_f32 v[60:61], v[60:61], v[60:61]
	v_pk_mul_f32 v[56:57], v[56:57], v[56:57]
	v_pk_mul_f32 v[62:63], v[62:63], v[62:63]
	v_pk_mul_f32 v[74:75], v[58:59], v[58:59]
	v_cvt_pk_bf16_f32 v58, v60, v61
	v_cvt_pk_bf16_f32 v59, v62, v63
	v_cvt_pk_bf16_f32 v60, v56, v57
	v_cvt_pk_bf16_f32 v61, v74, v75
	v_lshl_add_u64 v[56:57], v[162:163], 1, v[194:195]
	global_store_dwordx4 v[56:57], v[58:61], off
	s_waitcnt vmcnt(9)
	v_pk_fma_f32 v[66:67], v[66:67], v[192:193], v[130:131] op_sel_hi:[1,0,1]
	v_pk_fma_f32 v[64:65], v[64:65], v[192:193], v[128:129] op_sel_hi:[1,0,1]
	s_waitcnt vmcnt(8)
	v_pk_fma_f32 v[58:59], v[70:71], v[192:193], v[134:135] op_sel_hi:[1,0,1]
	v_pk_fma_f32 v[60:61], v[68:69], v[192:193], v[132:133] op_sel_hi:[1,0,1]
	v_max_f32_e32 v64, 0, v64
	v_max_f32_e32 v60, 0, v60
	v_max_f32_e32 v61, 0, v61
	v_max_f32_e32 v65, 0, v65
	v_max_f32_e32 v58, 0, v58
	v_max_f32_e32 v66, 0, v66
	v_max_f32_e32 v59, 0, v59
	v_max_f32_e32 v67, 0, v67
	v_pk_mul_f32 v[60:61], v[60:61], v[60:61]
	v_pk_mul_f32 v[64:65], v[64:65], v[64:65]
	v_pk_mul_f32 v[68:69], v[58:59], v[58:59]
	v_pk_mul_f32 v[66:67], v[66:67], v[66:67]
	v_pk_fma_f32 v[48:49], v[48:49], v[190:191], v[128:129] op_sel_hi:[1,0,1]
	v_cvt_pk_bf16_f32 v58, v60, v61
	v_cvt_pk_bf16_f32 v59, v68, v69
	v_cvt_pk_bf16_f32 v60, v64, v65
	v_cvt_pk_bf16_f32 v61, v66, v67
	v_pk_fma_f32 v[54:55], v[54:55], v[190:191], v[134:135] op_sel_hi:[1,0,1]
	v_pk_fma_f32 v[52:53], v[52:53], v[190:191], v[132:133] op_sel_hi:[1,0,1]
	v_pk_fma_f32 v[50:51], v[50:51], v[190:191], v[130:131] op_sel_hi:[1,0,1]
	v_max_f32_e32 v48, 0, v48
	v_max_f32_e32 v49, 0, v49
	global_store_dwordx4 v[120:121], v[58:61], off offset:256
	v_max_f32_e32 v52, 0, v52
	v_max_f32_e32 v53, 0, v53
	v_pk_mul_f32 v[58:59], v[48:49], v[48:49]
	v_max_f32_e32 v48, 0, v54
	v_max_f32_e32 v50, 0, v50
	v_max_f32_e32 v49, 0, v55
	v_max_f32_e32 v51, 0, v51
	v_lshl_add_u64 v[62:63], v[194:195], 0, s[4:5]
	v_pk_mul_f32 v[52:53], v[52:53], v[52:53]
	v_pk_mul_f32 v[54:55], v[48:49], v[48:49]
	v_pk_mul_f32 v[60:61], v[50:51], v[50:51]
	v_pk_fma_f32 v[40:41], v[40:41], v[188:189], v[128:129] op_sel_hi:[1,0,1]
	v_cvt_pk_bf16_f32 v48, v52, v53
	v_cvt_pk_bf16_f32 v49, v54, v55
	v_cvt_pk_bf16_f32 v50, v58, v59
	v_cvt_pk_bf16_f32 v51, v60, v61
	v_lshl_add_u64 v[52:53], v[62:63], 0, v[170:171]
	v_pk_fma_f32 v[46:47], v[46:47], v[188:189], v[134:135] op_sel_hi:[1,0,1]
	v_pk_fma_f32 v[44:45], v[44:45], v[188:189], v[132:133] op_sel_hi:[1,0,1]
	v_pk_fma_f32 v[42:43], v[42:43], v[188:189], v[130:131] op_sel_hi:[1,0,1]
	v_max_f32_e32 v40, 0, v40
	v_max_f32_e32 v41, 0, v41
	global_store_dwordx4 v[52:53], v[48:51], off
	v_max_f32_e32 v44, 0, v44
	v_max_f32_e32 v45, 0, v45
	v_pk_mul_f32 v[48:49], v[40:41], v[40:41]
	v_max_f32_e32 v40, 0, v46
	v_max_f32_e32 v42, 0, v42
	v_max_f32_e32 v41, 0, v47
	v_max_f32_e32 v43, 0, v43
	v_pk_mul_f32 v[44:45], v[44:45], v[44:45]
	v_pk_mul_f32 v[46:47], v[40:41], v[40:41]
	v_pk_mul_f32 v[50:51], v[42:43], v[42:43]
	v_pk_fma_f32 v[32:33], v[32:33], v[186:187], v[128:129] op_sel_hi:[1,0,1]
	v_cvt_pk_bf16_f32 v40, v44, v45
; DI unsigned cvtpk(float lo, float hi) { f32x2 v = {lo, hi}; bf16x2_t b = __builtin_convertvector(v, bf16x2_t); return __builtin_bit_cast(unsigned, b); }
;     DI void operator()(const f32x4 (&acc)[2][2][4][2], const pg8::Unit& u, int wr, int wc, int fr, int fq) const {
;     ...
;         for (int bj = 0; bj < 2; ++bj) { const f32x4 b0 = bb[bj][0], b1 = bb[bj][1];
; #pragma unroll
;             for (int ai = 0; ai < 2; ++ai)
; #pragma unroll
;                 for (int m = 0; m < 4; ++m) {
;                     f32x4 v0 = acc[ai][bj][m][0] * rstd[ai][m] + b0, v1 = acc[ai][bj][m][1] * rstd[ai][m] + b1;
;                     if (ACT == 1) {
; #pragma unroll
;                         for (int e = 0; e < 4; ++e) { float a = fmaxf(v0[e], 0.f), b = fmaxf(v1[e], 0.f); v0[e] = a * a; v1[e] = b * b; } }
;                     u32x4 w; w.x = cvtpk(v0[0], v0[1]); w.y = cvtpk(v0[2], v0[3]); w.z = cvtpk(v1[0], v1[1]); w.w = cvtpk(v1[2], v1[3]);
;                     *(u32x4*)(Ou + (wr * 64 + fr + ai * 128 + m * 16) * ldc + wc * 32 + 8 * fq + bj * 128) = w; } }
	v_cvt_pk_bf16_f32 v41, v46, v47
	v_cvt_pk_bf16_f32 v42, v48, v49
	v_cvt_pk_bf16_f32 v43, v50, v51
	v_lshl_add_u64 v[44:45], v[62:63], 0, v[172:173]
	v_pk_fma_f32 v[38:39], v[38:39], v[186:187], v[134:135] op_sel_hi:[1,0,1]
	v_pk_fma_f32 v[36:37], v[36:37], v[186:187], v[132:133] op_sel_hi:[1,0,1]
	v_pk_fma_f32 v[34:35], v[34:35], v[186:187], v[130:131] op_sel_hi:[1,0,1]
	v_max_f32_e32 v32, 0, v32
	v_max_f32_e32 v33, 0, v33
	global_store_dwordx4 v[44:45], v[40:43], off
	v_max_f32_e32 v36, 0, v36
	v_max_f32_e32 v37, 0, v37
	v_pk_mul_f32 v[40:41], v[32:33], v[32:33]
	v_max_f32_e32 v32, 0, v38
	v_max_f32_e32 v34, 0, v34
	v_max_f32_e32 v33, 0, v39
	v_max_f32_e32 v35, 0, v35
	v_pk_mul_f32 v[36:37], v[36:37], v[36:37]
	v_pk_mul_f32 v[38:39], v[32:33], v[32:33]
	v_pk_mul_f32 v[42:43], v[34:35], v[34:35]
	v_pk_fma_f32 v[24:25], v[24:25], v[184:185], v[128:129] op_sel_hi:[1,0,1]
	v_cvt_pk_bf16_f32 v32, v36, v37
	v_cvt_pk_bf16_f32 v33, v38, v39
	v_cvt_pk_bf16_f32 v34, v40, v41
	v_cvt_pk_bf16_f32 v35, v42, v43
	v_lshl_add_u64 v[36:37], v[62:63], 0, v[174:175]
	v_pk_fma_f32 v[30:31], v[30:31], v[184:185], v[134:135] op_sel_hi:[1,0,1]
	v_pk_fma_f32 v[28:29], v[28:29], v[184:185], v[132:133] op_sel_hi:[1,0,1]
	v_pk_fma_f32 v[26:27], v[26:27], v[184:185], v[130:131] op_sel_hi:[1,0,1]
	v_max_f32_e32 v24, 0, v24
	v_max_f32_e32 v25, 0, v25
	global_store_dwordx4 v[36:37], v[32:35], off
	v_max_f32_e32 v28, 0, v28
	v_max_f32_e32 v29, 0, v29
	v_pk_mul_f32 v[32:33], v[24:25], v[24:25]
	v_max_f32_e32 v24, 0, v30
	v_max_f32_e32 v26, 0, v26
	v_max_f32_e32 v25, 0, v31
	v_max_f32_e32 v27, 0, v27
	v_pk_mul_f32 v[28:29], v[28:29], v[28:29]
	v_pk_mul_f32 v[30:31], v[24:25], v[24:25]
	v_pk_mul_f32 v[34:35], v[26:27], v[26:27]
	v_pk_fma_f32 v[16:17], v[16:17], v[182:183], v[128:129] op_sel_hi:[1,0,1]
	v_cvt_pk_bf16_f32 v24, v28, v29
	v_cvt_pk_bf16_f32 v25, v30, v31
	v_cvt_pk_bf16_f32 v26, v32, v33
	v_cvt_pk_bf16_f32 v27, v34, v35
	v_pk_fma_f32 v[22:23], v[22:23], v[182:183], v[134:135] op_sel_hi:[1,0,1]
	v_pk_fma_f32 v[20:21], v[20:21], v[182:183], v[132:133] op_sel_hi:[1,0,1]
	v_pk_fma_f32 v[18:19], v[18:19], v[182:183], v[130:131] op_sel_hi:[1,0,1]
	v_max_f32_e32 v16, 0, v16
	v_max_f32_e32 v17, 0, v17
	global_store_dwordx4 v[88:89], v[24:27], off offset:256
	v_max_f32_e32 v20, 0, v20
	v_max_f32_e32 v21, 0, v21
	v_pk_mul_f32 v[24:25], v[16:17], v[16:17]
	v_max_f32_e32 v16, 0, v22
	v_max_f32_e32 v18, 0, v18
	v_max_f32_e32 v17, 0, v23
	v_max_f32_e32 v19, 0, v19
	v_pk_mul_f32 v[20:21], v[20:21], v[20:21]
	v_pk_mul_f32 v[22:23], v[16:17], v[16:17]
	v_pk_mul_f32 v[26:27], v[18:19], v[18:19]
	v_pk_fma_f32 v[8:9], v[8:9], v[180:181], v[128:129] op_sel_hi:[1,0,1]
	v_cvt_pk_bf16_f32 v16, v20, v21
	v_cvt_pk_bf16_f32 v17, v22, v23
	v_cvt_pk_bf16_f32 v18, v24, v25
	v_cvt_pk_bf16_f32 v19, v26, v27
	v_pk_fma_f32 v[14:15], v[14:15], v[180:181], v[134:135] op_sel_hi:[1,0,1]
	v_pk_fma_f32 v[12:13], v[12:13], v[180:181], v[132:133] op_sel_hi:[1,0,1]
	v_pk_fma_f32 v[10:11], v[10:11], v[180:181], v[130:131] op_sel_hi:[1,0,1]
	v_max_f32_e32 v8, 0, v8
	v_max_f32_e32 v9, 0, v9
	global_store_dwordx4 v[80:81], v[16:19], off offset:256
	v_max_f32_e32 v12, 0, v12
	v_max_f32_e32 v13, 0, v13
	v_pk_mul_f32 v[16:17], v[8:9], v[8:9]
	v_max_f32_e32 v8, 0, v14
	v_max_f32_e32 v10, 0, v10
	v_max_f32_e32 v9, 0, v15
	v_max_f32_e32 v11, 0, v11
	v_pk_mul_f32 v[12:13], v[12:13], v[12:13]
	v_pk_mul_f32 v[14:15], v[8:9], v[8:9]
	v_pk_mul_f32 v[18:19], v[10:11], v[10:11]
	v_pk_fma_f32 v[0:1], v[0:1], v[178:179], v[128:129] op_sel_hi:[1,0,1]
	v_cvt_pk_bf16_f32 v8, v12, v13
	v_cvt_pk_bf16_f32 v9, v14, v15
	v_cvt_pk_bf16_f32 v10, v16, v17
	v_cvt_pk_bf16_f32 v11, v18, v19
	v_pk_fma_f32 v[6:7], v[6:7], v[178:179], v[134:135] op_sel_hi:[1,0,1]
	v_pk_fma_f32 v[4:5], v[4:5], v[178:179], v[132:133] op_sel_hi:[1,0,1]
	v_pk_fma_f32 v[2:3], v[2:3], v[178:179], v[130:131] op_sel_hi:[1,0,1]
	v_max_f32_e32 v0, 0, v0
	v_max_f32_e32 v1, 0, v1
	global_store_dwordx4 v[72:73], v[8:11], off offset:256
	v_max_f32_e32 v4, 0, v4
	v_max_f32_e32 v5, 0, v5
	v_pk_mul_f32 v[8:9], v[0:1], v[0:1]
	v_max_f32_e32 v0, 0, v6
	v_max_f32_e32 v2, 0, v2
	v_max_f32_e32 v1, 0, v7
	v_max_f32_e32 v3, 0, v3
	v_pk_mul_f32 v[4:5], v[4:5], v[4:5]
	v_pk_mul_f32 v[6:7], v[0:1], v[0:1]
	v_pk_mul_f32 v[10:11], v[2:3], v[2:3]
	v_cvt_pk_bf16_f32 v0, v4, v5
	v_cvt_pk_bf16_f32 v1, v6, v7
	v_cvt_pk_bf16_f32 v2, v8, v9
	v_cvt_pk_bf16_f32 v3, v10, v11
	s_mov_b64 s[4:5], -1
	global_store_dwordx4 v[56:57], v[0:3], off offset:256
	s_cbranch_vccnz .LBB0_1702
	s_andn2_b64 vcc, exec, s[10:11]
	s_cbranch_vccnz .LBB0_1701
	s_barrier
	s_branch .LBB0_1701
